# attention: softmax without per-tile running max (exp2 of raw log2-scaled scores, safe path kept as overflow fallback); plus GEMM loop wait/setprio cleanup and select nop removal
# speedup vs baseline: 1.0293x; 1.0213x over previous
; __device__ __forceinline__ void attn_phase(const bf16_t* Z, const bf16_t* Kb, const bf16_t* Vb, unsigned* MASKb, unsigned* itemcnt, bf16_t* Y, LAS unsigned char* lds, int wave, int lane, int bid, int G) {
;     ...
;             unsigned* mrow = MASKb + ((size_t)(b * 128 + qb) * 128) * 32 + ql;
;             const bf16_t* kb = Kb + ((size_t)(b * 4 + h) * 128) * 2048 + ql * 16 + hi * 8;
;             const bf16_t* vb = Vb + ((size_t)(b * 4 + h) * 128) * 2048 + ql * 16 + hi * 8;
;             f32x16 o0, o1;
; #pragma unroll
;             for (int r = 0; r < 16; ++r) { o0[r] = 0.f; o1[r] = 0.f; }
;             float m = NEGF, l = 0.f;
;             bf16x8 kA[4], kB[4]; bf16x8 vA[2][2], vB[2][2]; unsigned mA = 0u, mB = 0u;
.Lat_nospin:
	s_barrier
	s_lshl_b32 s8, s18, 21
	s_or_b32 s8, s8, s24
	v_readlane_b32 s6, v255, 34
	v_readlane_b32 s7, v255, 35
	v_readlane_b32 s10, v255, 32
	v_readlane_b32 s11, v255, 33
	v_readlane_b32 s30, v255, 41
	v_readlane_b32 s31, v255, 42
	s_add_u32 s6, s6, s8
	s_addc_u32 s7, s7, 0
	s_add_u32 s10, s10, s8
	s_addc_u32 s11, s11, 0
	s_lshl_b32 s20, s18, 7
	s_lshl_b32 s21, s35, 1
	s_add_i32 s20, s20, s21
	s_lshl_b32 s20, s20, 14
	s_add_u32 s20, s30, s20
	s_addc_u32 s21, s31, 0
	s_add_i32 s19, s35, 1
	s_lshl_b32 s9, s19, 1
	s_and_b64 s[30:31], s[12:13], exec
	s_cselect_b32 s8, 0, s19
	s_cselect_b32 s19, s19, s9
	s_add_i32 s9, s19, -1
	s_lshl_b32 s35, s35, 1
	s_lshl_b32 s26, s18, 12
	s_lshl_b32 s34, s35, 5
	s_add_i32 s18, s34, s26
	v_or_b32_e32 v0, s18, v138
	v_mad_u64_u32 v[34:35], vcc, v0, s33, v[148:149]
	s_mov_b32 s30, 0x30000
	s_mov_b32 s31, 0
	global_load_dwordx4 v[82:85], v[34:35], off offset:2560
	global_load_dwordx4 v[86:89], v[34:35], off offset:2592
	global_load_dwordx4 v[90:93], v[34:35], off offset:2624
	global_load_dwordx4 v[94:97], v[34:35], off offset:2656
	v_lshl_add_u64 v[36:37], v[34:35], 0, s[30:31]
	global_load_dwordx4 v[114:117], v[36:37], off offset:2560
	global_load_dwordx4 v[118:121], v[36:37], off offset:2592
	global_load_dwordx4 v[122:125], v[36:37], off offset:2624
	global_load_dwordx4 v[126:129], v[36:37], off offset:2656
	v_lshlrev_b32_e32 v175, 2, v139
	v_lshl_add_u32 v175, v138, 5, v175
	v_lshlrev_b32_e32 v176, 2, v138
	v_add_u32_e32 v177, 0x4000, v176
	s_mov_b32 s100, s8
	s_lshl_b32 s27, s8, 12
	s_add_u32 s28, s6, s27
	s_addc_u32 s29, s7, 0
	global_load_dwordx4 v[66:69], v175, s[28:29]
	global_load_dwordx4 v[70:73], v175, s[28:29] offset:1024
	global_load_dwordx4 v[74:77], v175, s[28:29] offset:2048
	global_load_dwordx4 v[78:81], v175, s[28:29] offset:3072
	s_lshl_b32 s34, s8, 7
	s_add_u32 s30, s20, s34
	s_addc_u32 s31, s21, 0
	global_load_dword v173, v176, s[30:31] sc1
	global_load_dword v174, v177, s[30:31] sc1
	s_add_u32 s28, s10, s27
	s_addc_u32 s29, s11, 0
	global_load_dwordx4 v[98:101], v175, s[28:29]
	global_load_dwordx4 v[102:105], v175, s[28:29] offset:1024
	global_load_dwordx4 v[106:109], v175, s[28:29] offset:2048
	global_load_dwordx4 v[110:113], v175, s[28:29] offset:3072
	v_mov_b32_e32 v2, 0
	v_mov_b32_e32 v3, 0
	v_mov_b32_e32 v4, 0
	v_mov_b32_e32 v5, 0
	v_mov_b32_e32 v6, 0
	v_mov_b32_e32 v7, 0
	v_mov_b32_e32 v8, 0
	v_mov_b32_e32 v9, 0
	v_mov_b32_e32 v10, 0
	v_mov_b32_e32 v11, 0
	v_mov_b32_e32 v12, 0
	v_mov_b32_e32 v13, 0
	v_mov_b32_e32 v14, 0
	v_mov_b32_e32 v15, 0
	v_mov_b32_e32 v16, 0
	v_mov_b32_e32 v17, 0
	v_mov_b32_e32 v18, 0
	v_mov_b32_e32 v19, 0
	v_mov_b32_e32 v20, 0
	v_mov_b32_e32 v21, 0
	v_mov_b32_e32 v22, 0
	v_mov_b32_e32 v23, 0
	v_mov_b32_e32 v24, 0
	v_mov_b32_e32 v25, 0
	v_mov_b32_e32 v26, 0
	v_mov_b32_e32 v27, 0
	v_mov_b32_e32 v28, 0
	v_mov_b32_e32 v29, 0
	v_mov_b32_e32 v30, 0
	v_mov_b32_e32 v31, 0
	v_mov_b32_e32 v32, 0
	v_mov_b32_e32 v33, 0
	v_mov_b32_e32 v198, 0
	v_mov_b32_e32 v199, 0
	v_mov_b32_e32 v200, 0
	v_mov_b32_e32 v201, 0
	v_mov_b32_e32 v202, 0
	v_mov_b32_e32 v203, 0
	v_mov_b32_e32 v204, 0
	v_mov_b32_e32 v205, 0
	v_mov_b32_e32 v206, 0
	v_mov_b32_e32 v207, 0
	v_mov_b32_e32 v208, 0
	v_mov_b32_e32 v209, 0
	v_mov_b32_e32 v210, 0
	v_mov_b32_e32 v211, 0
	v_mov_b32_e32 v212, 0
	v_mov_b32_e32 v213, 0
	v_mov_b32_e32 v220, 0
	v_mov_b32_e32 v221, 0
	v_mov_b32_e32 v222, 0
	v_mov_b32_e32 v223, 0
	v_mov_b32_e32 v224, 0
	v_mov_b32_e32 v225, 0
	v_mov_b32_e32 v226, 0
	v_mov_b32_e32 v227, 0
	v_mov_b32_e32 v228, 0
	v_mov_b32_e32 v229, 0
	v_mov_b32_e32 v230, 0
	v_mov_b32_e32 v231, 0
	v_mov_b32_e32 v232, 0
	v_mov_b32_e32 v233, 0
	v_mov_b32_e32 v234, 0
	v_mov_b32_e32 v235, 0
	v_mov_b32_e32 v167, 0
	v_mov_b32_e32 v169, 0
	v_mov_b32_e32 v168, 0
	v_mov_b32_e32 v170, 0
.Lat_loop_f:
	s_waitcnt vmcnt(6)
	v_mfma_f32_32x32x16_bf16 v[34:49], v[66:69], v[82:85], 0
	v_mfma_f32_32x32x16_bf16 v[34:49], v[70:73], v[86:89], v[34:49]
	v_mfma_f32_32x32x16_bf16 v[34:49], v[74:77], v[90:93], v[34:49]
	v_mfma_f32_32x32x16_bf16 v[34:49], v[78:81], v[94:97], v[34:49]
	v_mfma_f32_32x32x16_bf16 v[50:65], v[66:69], v[114:117], 0
	v_mfma_f32_32x32x16_bf16 v[50:65], v[70:73], v[118:121], v[50:65]
	v_mfma_f32_32x32x16_bf16 v[50:65], v[74:77], v[122:125], v[50:65]
	v_mfma_f32_32x32x16_bf16 v[50:65], v[78:81], v[126:129], v[50:65]
	s_add_i32 s26, s8, 1
	s_min_i32 s26, s26, s9
	s_lshl_b32 s27, s26, 12
	s_add_u32 s28, s6, s27
	s_addc_u32 s29, s7, 0
	s_lshl_b32 s34, s26, 7
	s_add_u32 s30, s20, s34
	s_addc_u32 s31, s21, 0
	s_cmp_gt_u32 s8, s35
	s_cselect_b32 s82, 0, -1
	s_waitcnt vmcnt(4)
; __device__ __forceinline__ void attn_phase(const bf16_t* Z, const bf16_t* Kb, const bf16_t* Vb, unsigned* MASKb, unsigned* itemcnt, bf16_t* Y, LAS unsigned char* lds, int wave, int lane, int bid, int G) {
;     ...
;             if (tb < te) ATT_LOAD(kA, vA, mA, tb);
;             for (int kt = tb; kt < te; kt += 2) {
;                 { const int k1 = (kt + 1 < te) ? kt + 1 : kt; ATT_LOAD(kB, vB, mB, k1); }
;                 ATT_COMP(kA, vA, mA);
;                 { const int k2 = (kt + 2 < te) ? kt + 2 : te - 1; ATT_LOAD(kA, vA, mA, k2); }
;                 if (kt + 1 < te) ATT_COMP(kB, vB, mB);
;             }
	v_lshrrev_b32_e32 v171, v139, v173
	v_lshrrev_b32_e32 v172, v139, v174
	v_and_b32_e32 v171, s82, v171
	global_load_dwordx4 v[66:69], v175, s[28:29]
	global_load_dwordx4 v[70:73], v175, s[28:29] offset:1024
	global_load_dwordx4 v[74:77], v175, s[28:29] offset:2048
	global_load_dwordx4 v[78:81], v175, s[28:29] offset:3072
	global_load_dword v173, v176, s[30:31] sc1
	global_load_dword v174, v177, s[30:31] sc1
	v_bfe_i32 v178, v171, 0, 1
	v_bitop3_b32 v34, v34, s96, v178 bitop3:0xe4
	v_bfe_i32 v180, v171, 1, 1
	v_bitop3_b32 v35, v35, s96, v180 bitop3:0xe4
	v_bfe_i32 v178, v171, 2, 1
	v_bitop3_b32 v36, v36, s96, v178 bitop3:0xe4
	v_bfe_i32 v180, v171, 3, 1
	v_bitop3_b32 v37, v37, s96, v180 bitop3:0xe4
	v_bfe_i32 v178, v171, 8, 1
	v_bitop3_b32 v38, v38, s96, v178 bitop3:0xe4
	v_bfe_i32 v180, v171, 9, 1
	v_bitop3_b32 v39, v39, s96, v180 bitop3:0xe4
	v_bfe_i32 v178, v171, 10, 1
	v_bitop3_b32 v40, v40, s96, v178 bitop3:0xe4
	v_bfe_i32 v180, v171, 11, 1
	v_bitop3_b32 v41, v41, s96, v180 bitop3:0xe4
	v_bfe_i32 v178, v171, 16, 1
	v_bitop3_b32 v42, v42, s96, v178 bitop3:0xe4
	v_bfe_i32 v180, v171, 17, 1
	v_bitop3_b32 v43, v43, s96, v180 bitop3:0xe4
	v_bfe_i32 v178, v171, 18, 1
	v_bitop3_b32 v44, v44, s96, v178 bitop3:0xe4
	v_bfe_i32 v180, v171, 19, 1
	v_bitop3_b32 v45, v45, s96, v180 bitop3:0xe4
	v_bfe_i32 v178, v171, 24, 1
	v_bitop3_b32 v46, v46, s96, v178 bitop3:0xe4
	v_bfe_i32 v180, v171, 25, 1
	v_bitop3_b32 v47, v47, s96, v180 bitop3:0xe4
	v_bfe_i32 v178, v171, 26, 1
	v_bitop3_b32 v48, v48, s96, v178 bitop3:0xe4
	v_bfe_i32 v180, v171, 27, 1
	v_bitop3_b32 v49, v49, s96, v180 bitop3:0xe4
	v_exp_f32_e32 v34, v34
	v_exp_f32_e32 v35, v35
	v_exp_f32_e32 v36, v36
	v_add_f32_e32 v196, v34, v35
	v_exp_f32_e32 v37, v37
	v_add_f32_e32 v196, v196, v36
	v_exp_f32_e32 v38, v38
	v_add_f32_e32 v196, v196, v37
	v_exp_f32_e32 v39, v39
	v_add_f32_e32 v196, v196, v38
	v_exp_f32_e32 v40, v40
	v_add_f32_e32 v196, v196, v39
	v_exp_f32_e32 v41, v41
	v_add_f32_e32 v196, v196, v40
	v_exp_f32_e32 v42, v42
	v_add_f32_e32 v196, v196, v41
	v_exp_f32_e32 v43, v43
	v_add_f32_e32 v196, v196, v42
	v_exp_f32_e32 v44, v44
	v_add_f32_e32 v196, v196, v43
	v_exp_f32_e32 v45, v45
	v_add_f32_e32 v196, v196, v44
	v_exp_f32_e32 v46, v46
	v_add_f32_e32 v196, v196, v45
	v_exp_f32_e32 v47, v47
	v_add_f32_e32 v196, v196, v46
	v_exp_f32_e32 v48, v48
	v_add_f32_e32 v196, v196, v47
	v_exp_f32_e32 v49, v49
	v_add_f32_e32 v196, v196, v48
	s_nop 0
	v_add_f32_e32 v196, v196, v49
	v_add_f32_e32 v167, v167, v196
	v_cvt_pk_bf16_f32 v130, v34, v35
	v_cvt_pk_bf16_f32 v131, v36, v37
	v_cvt_pk_bf16_f32 v132, v38, v39
	v_cvt_pk_bf16_f32 v133, v40, v41
	v_cvt_pk_bf16_f32 v134, v42, v43
	v_cvt_pk_bf16_f32 v135, v44, v45
	v_cvt_pk_bf16_f32 v136, v46, v47
	v_cvt_pk_bf16_f32 v137, v48, v49
	v_bfe_i32 v178, v172, 0, 1
	v_bitop3_b32 v50, v50, s96, v178 bitop3:0xe4
	v_bfe_i32 v180, v172, 1, 1
	v_bitop3_b32 v51, v51, s96, v180 bitop3:0xe4
	v_bfe_i32 v178, v172, 2, 1
	v_bitop3_b32 v52, v52, s96, v178 bitop3:0xe4
	v_bfe_i32 v180, v172, 3, 1
	v_bitop3_b32 v53, v53, s96, v180 bitop3:0xe4
	v_bfe_i32 v178, v172, 8, 1
	v_bitop3_b32 v54, v54, s96, v178 bitop3:0xe4
	v_bfe_i32 v180, v172, 9, 1
	v_bitop3_b32 v55, v55, s96, v180 bitop3:0xe4
	v_bfe_i32 v178, v172, 10, 1
	v_bitop3_b32 v56, v56, s96, v178 bitop3:0xe4
	v_bfe_i32 v180, v172, 11, 1
	v_bitop3_b32 v57, v57, s96, v180 bitop3:0xe4
	v_bfe_i32 v178, v172, 16, 1
	v_bitop3_b32 v58, v58, s96, v178 bitop3:0xe4
	v_bfe_i32 v180, v172, 17, 1
	v_bitop3_b32 v59, v59, s96, v180 bitop3:0xe4
	v_bfe_i32 v178, v172, 18, 1
	v_bitop3_b32 v60, v60, s96, v178 bitop3:0xe4
	v_bfe_i32 v180, v172, 19, 1
	v_bitop3_b32 v61, v61, s96, v180 bitop3:0xe4
	v_bfe_i32 v178, v172, 24, 1
	v_bitop3_b32 v62, v62, s96, v178 bitop3:0xe4
	v_bfe_i32 v180, v172, 25, 1
	v_bitop3_b32 v63, v63, s96, v180 bitop3:0xe4
	v_bfe_i32 v178, v172, 26, 1
	v_bitop3_b32 v64, v64, s96, v178 bitop3:0xe4
	v_bfe_i32 v180, v172, 27, 1
	v_bitop3_b32 v65, v65, s96, v180 bitop3:0xe4
	v_exp_f32_e32 v50, v50
	v_exp_f32_e32 v51, v51
	v_exp_f32_e32 v52, v52
	v_add_f32_e32 v196, v50, v51
	v_exp_f32_e32 v53, v53
	v_add_f32_e32 v196, v196, v52
	v_exp_f32_e32 v54, v54
	v_add_f32_e32 v196, v196, v53
	v_exp_f32_e32 v55, v55
	v_add_f32_e32 v196, v196, v54
	v_exp_f32_e32 v56, v56
	v_add_f32_e32 v196, v196, v55
	v_exp_f32_e32 v57, v57
	v_add_f32_e32 v196, v196, v56
	v_exp_f32_e32 v58, v58
	v_add_f32_e32 v196, v196, v57
	v_exp_f32_e32 v59, v59
	v_add_f32_e32 v196, v196, v58
	v_exp_f32_e32 v60, v60
	v_add_f32_e32 v196, v196, v59
	v_exp_f32_e32 v61, v61
	v_add_f32_e32 v196, v196, v60
	v_exp_f32_e32 v62, v62
	v_add_f32_e32 v196, v196, v61
	v_exp_f32_e32 v63, v63
	v_add_f32_e32 v196, v196, v62
	v_exp_f32_e32 v64, v64
	v_add_f32_e32 v196, v196, v63
	v_exp_f32_e32 v65, v65
	v_add_f32_e32 v196, v196, v64
	s_nop 0
	v_add_f32_e32 v196, v196, v65
	v_add_f32_e32 v169, v169, v196
	v_cvt_pk_bf16_f32 v182, v50, v51
	v_cvt_pk_bf16_f32 v183, v52, v53
	v_cvt_pk_bf16_f32 v184, v54, v55
	v_cvt_pk_bf16_f32 v185, v56, v57
	v_cvt_pk_bf16_f32 v186, v58, v59
	v_cvt_pk_bf16_f32 v187, v60, v61
	v_cvt_pk_bf16_f32 v188, v62, v63
	v_cvt_pk_bf16_f32 v189, v64, v65
	s_waitcnt vmcnt(6)
	v_mfma_f32_32x32x16_bf16 v[18:33], v[98:101], v[130:133], v[18:33]
	v_mfma_f32_32x32x16_bf16 v[2:17], v[106:109], v[130:133], v[2:17]
	v_mfma_f32_32x32x16_bf16 v[18:33], v[102:105], v[134:137], v[18:33]
	v_mfma_f32_32x32x16_bf16 v[2:17], v[110:113], v[134:137], v[2:17]
	v_mfma_f32_32x32x16_bf16 v[198:213], v[98:101], v[182:185], v[198:213]
	v_mfma_f32_32x32x16_bf16 v[220:235], v[106:109], v[182:185], v[220:235]
	v_mfma_f32_32x32x16_bf16 v[198:213], v[102:105], v[186:189], v[198:213]
	v_mfma_f32_32x32x16_bf16 v[220:235], v[110:113], v[186:189], v[220:235]
	s_add_u32 s28, s10, s27
	s_addc_u32 s29, s11, 0
	global_load_dwordx4 v[98:101], v175, s[28:29]
	global_load_dwordx4 v[102:105], v175, s[28:29] offset:1024
	global_load_dwordx4 v[106:109], v175, s[28:29] offset:2048
	global_load_dwordx4 v[110:113], v175, s[28:29] offset:3072
	s_add_i32 s8, s8, 1
	s_cmp_lt_i32 s8, s19
	s_cbranch_scc1 .Lat_loop_f
	s_waitcnt vmcnt(0)
	s_movk_i32 s26, 0x207
	v_cmp_class_f32_e64 vcc, v167, s26
	s_cbranch_vccnz .Lat_safe
	v_cmp_class_f32_e64 vcc, v169, s26
	s_cbranch_vccz .Lat_epi0
; __device__ __forceinline__ void attn_phase(const bf16_t* Z, const bf16_t* Kb, const bf16_t* Vb, unsigned* MASKb, unsigned* itemcnt, bf16_t* Y, LAS unsigned char* lds, int wave, int lane, int bid, int G) {
;     ...
;             f32x16 o0, o1;
; #pragma unroll
;             for (int r = 0; r < 16; ++r) { o0[r] = 0.f; o1[r] = 0.f; }
;             float m = NEGF, l = 0.f;
;             bf16x8 kA[4], kB[4]; bf16x8 vA[2][2], vB[2][2]; unsigned mA = 0u, mB = 0u;
;     ...
;             if (tb < te) ATT_LOAD(kA, vA, mA, tb);
.Lat_safe:
	s_mov_b32 s8, s100
	s_lshl_b32 s27, s8, 12
	s_add_u32 s28, s6, s27
	s_addc_u32 s29, s7, 0
	global_load_dwordx4 v[66:69], v175, s[28:29]
	global_load_dwordx4 v[70:73], v175, s[28:29] offset:1024
	global_load_dwordx4 v[74:77], v175, s[28:29] offset:2048
	global_load_dwordx4 v[78:81], v175, s[28:29] offset:3072
	s_lshl_b32 s34, s8, 7
	s_add_u32 s30, s20, s34
	s_addc_u32 s31, s21, 0
	global_load_dword v173, v176, s[30:31] sc1
	global_load_dword v174, v177, s[30:31] sc1
	s_add_u32 s28, s10, s27
	s_addc_u32 s29, s11, 0
	global_load_dwordx4 v[98:101], v175, s[28:29]
	global_load_dwordx4 v[102:105], v175, s[28:29] offset:1024
	global_load_dwordx4 v[106:109], v175, s[28:29] offset:2048
	global_load_dwordx4 v[110:113], v175, s[28:29] offset:3072
	v_mov_b32_e32 v2, 0
	v_mov_b32_e32 v3, 0
	v_mov_b32_e32 v4, 0
	v_mov_b32_e32 v5, 0
	v_mov_b32_e32 v6, 0
	v_mov_b32_e32 v7, 0
	v_mov_b32_e32 v8, 0
	v_mov_b32_e32 v9, 0
	v_mov_b32_e32 v10, 0
	v_mov_b32_e32 v11, 0
	v_mov_b32_e32 v12, 0
	v_mov_b32_e32 v13, 0
	v_mov_b32_e32 v14, 0
	v_mov_b32_e32 v15, 0
	v_mov_b32_e32 v16, 0
	v_mov_b32_e32 v17, 0
	v_mov_b32_e32 v18, 0
	v_mov_b32_e32 v19, 0
	v_mov_b32_e32 v20, 0
	v_mov_b32_e32 v21, 0
	v_mov_b32_e32 v22, 0
	v_mov_b32_e32 v23, 0
	v_mov_b32_e32 v24, 0
	v_mov_b32_e32 v25, 0
	v_mov_b32_e32 v26, 0
	v_mov_b32_e32 v27, 0
	v_mov_b32_e32 v28, 0
	v_mov_b32_e32 v29, 0
	v_mov_b32_e32 v30, 0
	v_mov_b32_e32 v31, 0
	v_mov_b32_e32 v32, 0
	v_mov_b32_e32 v33, 0
	v_mov_b32_e32 v198, 0
	v_mov_b32_e32 v199, 0
	v_mov_b32_e32 v200, 0
	v_mov_b32_e32 v201, 0
	v_mov_b32_e32 v202, 0
	v_mov_b32_e32 v203, 0
	v_mov_b32_e32 v204, 0
	v_mov_b32_e32 v205, 0
	v_mov_b32_e32 v206, 0
	v_mov_b32_e32 v207, 0
	v_mov_b32_e32 v208, 0
	v_mov_b32_e32 v209, 0
	v_mov_b32_e32 v210, 0
	v_mov_b32_e32 v211, 0
	v_mov_b32_e32 v212, 0
	v_mov_b32_e32 v213, 0
	v_mov_b32_e32 v220, 0
	v_mov_b32_e32 v221, 0
	v_mov_b32_e32 v222, 0
	v_mov_b32_e32 v223, 0
	v_mov_b32_e32 v224, 0
	v_mov_b32_e32 v225, 0
	v_mov_b32_e32 v226, 0
	v_mov_b32_e32 v227, 0
	v_mov_b32_e32 v228, 0
	v_mov_b32_e32 v229, 0
	v_mov_b32_e32 v230, 0
	v_mov_b32_e32 v231, 0
	v_mov_b32_e32 v232, 0
	v_mov_b32_e32 v233, 0
	v_mov_b32_e32 v234, 0
	v_mov_b32_e32 v235, 0
	v_mov_b32_e32 v167, 0
	v_mov_b32_e32 v169, 0
	v_mov_b32_e32 v168, 0xf149f2ca
	v_mov_b32_e32 v170, 0xf149f2ca

; __device__ __forceinline__ float swap32(float v, int hi) { auto rr = __builtin_amdgcn_permlane32_swap(__float_as_uint(v), __float_as_uint(v), false, false); return hi ? __uint_as_float(rr[0]) : __uint_as_float(rr[1]); }
; __device__ __forceinline__ void attn_phase(const bf16_t* Z, const bf16_t* Kb, const bf16_t* Vb, unsigned* MASKb, unsigned* itemcnt, bf16_t* Y, LAS unsigned char* lds, int wave, int lane, int bid, int G) {
;     ...
;             const float lt = l + swap32(l, hi);
;             if (half == 1) {
.Lat_epi0:
	s_mov_b32 s35, 0

; __device__ __forceinline__ int count_ge(const unsigned (&u)[64], unsigned cand, int nblk) {
;     int c0 = 0, c1 = 0;
;     const unsigned ts = __builtin_amdgcn_readfirstlane(cand);
; #pragma unroll
;     for (int B = 0; B < 2; ++B) {
;         if (B < nblk) {
; #pragma unroll
;             for (int i = 0; i < 32; i += 4) CNT4(c0, c1, ts, u[B * 32 + i], u[B * 32 + i + 1], u[B * 32 + i + 2], u[B * 32 + i + 3]);
;         }
;     }
;     return wave_isum(c0 + c1);
; }
; __device__ __forceinline__ float keyval(unsigned k) { return __uint_as_float((k & 0x80000000u) ? (k ^ 0x80000000u) : ~k); }
; __device__ __forceinline__ unsigned valkey(float f) { const unsigned b = __float_as_uint(f); return b ^ ((unsigned)((int)b >> 31) | 0x80000000u); }
; __device__ __forceinline__ void select_query(const unsigned (&u)[64], unsigned vmax, int q, int b, int lane, unsigned* MASKb) {
;     const int n = q + 1, nblk = (n + 2047) >> 11;
;     unsigned T = 0u, TG = 0u; int rrem = 0;
;     if (n > 256) {
;         const unsigned kmax = wave_umax(vmax);
;         const unsigned K0 = 0x80000000u;
;         bool exact = false, done = false;
;         unsigned lo = 0u, hi = 0u; float Llo = 1.f, Lhi = 1.f;
;         const float L256 = 8.0028150156f;
;         const int cpos = count_ge(u, K0 + 1u, nblk);
.LBB0_130:
	v_add_u32_e32 v0, 0x800, v106
	s_movk_i32 s4, 0xff
	v_ashrrev_i32_e32 v190, 11, v0
	v_cmp_lt_i32_e32 vcc, s4, v106
	v_mov_b32_e32 v192, 0
	v_mov_b32_e32 v193, 0
	v_mov_b32_e32 v191, 0
	s_and_saveexec_b64 s[8:9], vcc
	s_cbranch_execz .LBB0_173
	v_max_u32_dpp v34, v185, v185 row_shr:1 row_mask:0xf bank_mask:0xf bound_ctrl:1
	v_mov_b32_e32 v0, 0
	v_cmp_lt_i32_e64 s[4:5], 0, v190
	v_max_u32_dpp v34, v34, v34 row_shr:2 row_mask:0xf bank_mask:0xf bound_ctrl:1
	s_nop 1
	v_max_u32_dpp v34, v34, v34 row_shr:4 row_mask:0xf bank_mask:0xf bound_ctrl:1
	s_nop 1
	v_max_u32_dpp v34, v34, v34 row_shr:8 row_mask:0xf bank_mask:0xf bound_ctrl:1
	s_nop 1
	v_max_u32_dpp v34, v34, v34 row_bcast:15 row_mask:0xa bank_mask:0xf
	s_nop 1
	v_max_u32_dpp v34, v34, v34 row_bcast:31 row_mask:0xc bank_mask:0xf
	s_nop 0
	v_readlane_b32 s18, v34, 63
	v_mov_b32_e32 v34, 0
	s_and_saveexec_b64 s[6:7], s[4:5]
	s_cbranch_execz .LBB0_133
	v_readlane_b32 s10, v255, 13
	v_mov_b32_e32 v34, v1
	v_mov_b32_e32 v0, v1
	v_readlane_b32 s11, v255, 14
	s_mov_b32 s19, s11
	v_cmp_le_u32_e64 s[10:11], s19, v138
	v_cmp_le_u32_e64 s[12:13], s19, v140
	v_cmp_le_u32_e64 s[14:15], s19, v139
	v_cmp_le_u32_e64 s[16:17], s19, v141
	v_addc_co_u32_e64 v34, s[22:23], 0, v34, s[10:11]
	v_addc_co_u32_e64 v0, s[24:25], 0, v0, s[12:13]
	v_addc_co_u32_e64 v34, s[22:23], 0, v34, s[14:15]
	v_addc_co_u32_e64 v0, s[24:25], 0, v0, s[16:17]
	v_cmp_le_u32_e64 s[10:11], s19, v142
	v_cmp_le_u32_e64 s[12:13], s19, v146
	v_cmp_le_u32_e64 s[14:15], s19, v143
	v_cmp_le_u32_e64 s[16:17], s19, v147
	v_addc_co_u32_e64 v34, s[22:23], 0, v34, s[10:11]
	v_addc_co_u32_e64 v0, s[24:25], 0, v0, s[12:13]
	v_addc_co_u32_e64 v34, s[22:23], 0, v34, s[14:15]
	v_addc_co_u32_e64 v0, s[24:25], 0, v0, s[16:17]
	v_cmp_le_u32_e64 s[10:11], s19, v144
	v_cmp_le_u32_e64 s[12:13], s19, v148
	v_cmp_le_u32_e64 s[14:15], s19, v145
	v_cmp_le_u32_e64 s[16:17], s19, v149
	v_addc_co_u32_e64 v34, s[22:23], 0, v34, s[10:11]
	v_addc_co_u32_e64 v0, s[24:25], 0, v0, s[12:13]
	v_addc_co_u32_e64 v34, s[22:23], 0, v34, s[14:15]
	v_addc_co_u32_e64 v0, s[24:25], 0, v0, s[16:17]
	v_cmp_le_u32_e64 s[10:11], s19, v150
	v_cmp_le_u32_e64 s[12:13], s19, v152
	v_cmp_le_u32_e64 s[14:15], s19, v151
	v_cmp_le_u32_e64 s[16:17], s19, v154
	v_addc_co_u32_e64 v34, s[22:23], 0, v34, s[10:11]
	v_addc_co_u32_e64 v0, s[24:25], 0, v0, s[12:13]
	v_addc_co_u32_e64 v34, s[22:23], 0, v34, s[14:15]
	v_addc_co_u32_e64 v0, s[24:25], 0, v0, s[16:17]
	v_cmp_le_u32_e64 s[10:11], s19, v153
	v_cmp_le_u32_e64 s[12:13], s19, v156
	v_cmp_le_u32_e64 s[14:15], s19, v155
	v_cmp_le_u32_e64 s[16:17], s19, v157
	v_addc_co_u32_e64 v34, s[22:23], 0, v34, s[10:11]
	v_addc_co_u32_e64 v0, s[24:25], 0, v0, s[12:13]
	v_addc_co_u32_e64 v34, s[22:23], 0, v34, s[14:15]
	v_addc_co_u32_e64 v0, s[24:25], 0, v0, s[16:17]
	v_cmp_le_u32_e64 s[10:11], s19, v158
	v_cmp_le_u32_e64 s[12:13], s19, v160
	v_cmp_le_u32_e64 s[14:15], s19, v159
	v_cmp_le_u32_e64 s[16:17], s19, v161
	v_addc_co_u32_e64 v34, s[22:23], 0, v34, s[10:11]
	v_addc_co_u32_e64 v0, s[24:25], 0, v0, s[12:13]
	v_addc_co_u32_e64 v34, s[22:23], 0, v34, s[14:15]
	v_addc_co_u32_e64 v0, s[24:25], 0, v0, s[16:17]
	v_cmp_le_u32_e64 s[10:11], s19, v167
	v_cmp_le_u32_e64 s[12:13], s19, v169
	v_cmp_le_u32_e64 s[14:15], s19, v168
	v_cmp_le_u32_e64 s[16:17], s19, v170
	v_addc_co_u32_e64 v34, s[22:23], 0, v34, s[10:11]
	v_addc_co_u32_e64 v0, s[24:25], 0, v0, s[12:13]
	v_addc_co_u32_e64 v34, s[22:23], 0, v34, s[14:15]
	v_addc_co_u32_e64 v0, s[24:25], 0, v0, s[16:17]
	v_cmp_le_u32_e64 s[10:11], s19, v173
	v_cmp_le_u32_e64 s[12:13], s19, v174
	v_cmp_le_u32_e64 s[14:15], s19, v175
	v_cmp_le_u32_e64 s[16:17], s19, v176
	v_addc_co_u32_e64 v34, s[22:23], 0, v34, s[10:11]
	v_addc_co_u32_e64 v0, s[24:25], 0, v0, s[12:13]
	v_addc_co_u32_e64 v34, s[22:23], 0, v34, s[14:15]
	v_addc_co_u32_e64 v0, s[24:25], 0, v0, s[16:17]
.LBB0_133:
	s_or_b64 exec, exec, s[6:7]
	v_cmp_lt_i32_e64 s[6:7], 1, v190
	s_and_saveexec_b64 s[10:11], s[6:7]
	s_cbranch_execz .LBB0_135
	v_readlane_b32 s12, v255, 13
	v_readlane_b32 s13, v255, 14
	s_mov_b32 s19, s13
	v_cmp_le_u32_e64 s[12:13], s19, v76
	v_cmp_le_u32_e64 s[14:15], s19, v78
	v_cmp_le_u32_e64 s[16:17], s19, v77
	v_cmp_le_u32_e64 s[22:23], s19, v79
	v_addc_co_u32_e64 v34, s[24:25], 0, v34, s[12:13]
	v_addc_co_u32_e64 v0, s[26:27], 0, v0, s[14:15]
	v_addc_co_u32_e64 v34, s[24:25], 0, v34, s[16:17]
	v_addc_co_u32_e64 v0, s[26:27], 0, v0, s[22:23]
	v_cmp_le_u32_e64 s[12:13], s19, v80
	v_cmp_le_u32_e64 s[14:15], s19, v84
	v_cmp_le_u32_e64 s[16:17], s19, v81
	v_cmp_le_u32_e64 s[22:23], s19, v85
	v_addc_co_u32_e64 v34, s[24:25], 0, v34, s[12:13]
	v_addc_co_u32_e64 v0, s[26:27], 0, v0, s[14:15]
	v_addc_co_u32_e64 v34, s[24:25], 0, v34, s[16:17]
	v_addc_co_u32_e64 v0, s[26:27], 0, v0, s[22:23]
	v_cmp_le_u32_e64 s[12:13], s19, v82
	v_cmp_le_u32_e64 s[14:15], s19, v86
	v_cmp_le_u32_e64 s[16:17], s19, v83
	v_cmp_le_u32_e64 s[22:23], s19, v87
	v_addc_co_u32_e64 v34, s[24:25], 0, v34, s[12:13]
	v_addc_co_u32_e64 v0, s[26:27], 0, v0, s[14:15]
	v_addc_co_u32_e64 v34, s[24:25], 0, v34, s[16:17]
	v_addc_co_u32_e64 v0, s[26:27], 0, v0, s[22:23]
	v_cmp_le_u32_e64 s[12:13], s19, v89
	v_cmp_le_u32_e64 s[14:15], s19, v91
	v_cmp_le_u32_e64 s[16:17], s19, v90
	v_cmp_le_u32_e64 s[22:23], s19, v93
	v_addc_co_u32_e64 v34, s[24:25], 0, v34, s[12:13]
	v_addc_co_u32_e64 v0, s[26:27], 0, v0, s[14:15]
	v_addc_co_u32_e64 v34, s[24:25], 0, v34, s[16:17]
	v_addc_co_u32_e64 v0, s[26:27], 0, v0, s[22:23]
	v_cmp_le_u32_e64 s[12:13], s19, v92
	v_cmp_le_u32_e64 s[14:15], s19, v95
	v_cmp_le_u32_e64 s[16:17], s19, v94
	v_cmp_le_u32_e64 s[22:23], s19, v96
	v_addc_co_u32_e64 v34, s[24:25], 0, v34, s[12:13]
	v_addc_co_u32_e64 v0, s[26:27], 0, v0, s[14:15]
	v_addc_co_u32_e64 v34, s[24:25], 0, v34, s[16:17]
	v_addc_co_u32_e64 v0, s[26:27], 0, v0, s[22:23]
	v_cmp_le_u32_e64 s[12:13], s19, v97
	v_cmp_le_u32_e64 s[14:15], s19, v172
	v_cmp_le_u32_e64 s[16:17], s19, v171
	v_cmp_le_u32_e64 s[22:23], s19, v178
	v_addc_co_u32_e64 v34, s[24:25], 0, v34, s[12:13]
	v_addc_co_u32_e64 v0, s[26:27], 0, v0, s[14:15]
	v_addc_co_u32_e64 v34, s[24:25], 0, v34, s[16:17]
	v_addc_co_u32_e64 v0, s[26:27], 0, v0, s[22:23]
	v_cmp_le_u32_e64 s[12:13], s19, v180
	v_cmp_le_u32_e64 s[14:15], s19, v183
	v_cmp_le_u32_e64 s[16:17], s19, v182
	v_cmp_le_u32_e64 s[22:23], s19, v184
	v_addc_co_u32_e64 v34, s[24:25], 0, v34, s[12:13]
	v_addc_co_u32_e64 v0, s[26:27], 0, v0, s[14:15]
	v_addc_co_u32_e64 v34, s[24:25], 0, v34, s[16:17]
	v_addc_co_u32_e64 v0, s[26:27], 0, v0, s[22:23]
	v_cmp_le_u32_e64 s[12:13], s19, v186
	v_cmp_le_u32_e64 s[14:15], s19, v187
	v_cmp_le_u32_e64 s[16:17], s19, v188
	v_cmp_le_u32_e64 s[22:23], s19, v189
	v_addc_co_u32_e64 v34, s[24:25], 0, v34, s[12:13]
	v_addc_co_u32_e64 v0, s[26:27], 0, v0, s[14:15]
	v_addc_co_u32_e64 v34, s[24:25], 0, v34, s[16:17]
	v_addc_co_u32_e64 v0, s[26:27], 0, v0, s[22:23]
; __device__ __forceinline__ int count_ge(const unsigned (&u)[64], unsigned cand, int nblk) {
;     ...
;     return wave_isum(c0 + c1);
; }
; __device__ __forceinline__ float keyval(unsigned k) { return __uint_as_float((k & 0x80000000u) ? (k ^ 0x80000000u) : ~k); }
; __device__ __forceinline__ unsigned valkey(float f) { const unsigned b = __float_as_uint(f); return b ^ ((unsigned)((int)b >> 31) | 0x80000000u); }
; __device__ __forceinline__ void select_query(const unsigned (&u)[64], unsigned vmax, int q, int b, int lane, unsigned* MASKb) {
;     const int n = q + 1, nblk = (n + 2047) >> 11;
;     unsigned T = 0u, TG = 0u; int rrem = 0;
;     if (n > 256) {
;         const unsigned kmax = wave_umax(vmax);
;         const unsigned K0 = 0x80000000u;
;         bool exact = false, done = false;
;         unsigned lo = 0u, hi = 0u; float Llo = 1.f, Lhi = 1.f;
;         const float L256 = 8.0028150156f;
;         const int cpos = count_ge(u, K0 + 1u, nblk);
;         if (cpos == 256) { T = K0 + 1u; exact = true; done = true; }
;         else if (cpos > 256) { lo = K0 + 1u; Llo = __log2f((float)cpos) - L256; hi = kmax + 1u; Lhi = L256 + 1.f; }
;         else {
;             const int c0 = count_ge(u, K0, nblk);
;             if (c0 >= 256) { T = K0; exact = (c0 == 256); done = true; }
.LBB0_135:
	s_or_b64 exec, exec, s[10:11]
	v_add_u32_e32 v0, v34, v0
	s_nop 1
	v_add_u32_dpp v0, v0, v0 row_shr:1 row_mask:0xf bank_mask:0xf bound_ctrl:1
	s_nop 1
	v_add_u32_dpp v0, v0, v0 row_shr:2 row_mask:0xf bank_mask:0xf bound_ctrl:1
	s_nop 1
	v_add_u32_dpp v0, v0, v0 row_shr:4 row_mask:0xf bank_mask:0xf bound_ctrl:1
	s_nop 1
	v_add_u32_dpp v0, v0, v0 row_shr:8 row_mask:0xf bank_mask:0xf bound_ctrl:1
	s_nop 1
	v_add_u32_dpp v0, v0, v0 row_bcast:15 row_mask:0xa bank_mask:0xf
	s_nop 1
	v_add_u32_dpp v0, v0, v0 row_bcast:31 row_mask:0xc bank_mask:0xf
	s_nop 0
	v_readlane_b32 s19, v0, 63
	s_cmpk_eq_i32 s19, 0x100
	s_cbranch_scc1 .LBB0_146
	s_cmpk_lt_i32 s19, 0x101
	s_mov_b64 s[14:15], -1
	s_cbranch_scc0 .LBB0_147
	v_mov_b32_e32 v0, 0
	v_mov_b32_e32 v34, 0
	s_and_saveexec_b64 s[10:11], s[4:5]
	s_cbranch_execz .LBB0_139
	v_mov_b32_e32 v34, v1
	v_mov_b32_e32 v0, v1
	v_cmp_le_u32_e64 s[12:13], s38, v138
	v_cmp_le_u32_e64 s[14:15], s38, v140
	v_cmp_le_u32_e64 s[16:17], s38, v139
	v_cmp_le_u32_e64 s[22:23], s38, v141
	v_addc_co_u32_e64 v34, s[24:25], 0, v34, s[12:13]
	v_addc_co_u32_e64 v0, s[26:27], 0, v0, s[14:15]
	v_addc_co_u32_e64 v34, s[24:25], 0, v34, s[16:17]
	v_addc_co_u32_e64 v0, s[26:27], 0, v0, s[22:23]
	v_cmp_le_u32_e64 s[12:13], s38, v142
	v_cmp_le_u32_e64 s[14:15], s38, v146
	v_cmp_le_u32_e64 s[16:17], s38, v143
	v_cmp_le_u32_e64 s[22:23], s38, v147
	v_addc_co_u32_e64 v34, s[24:25], 0, v34, s[12:13]
	v_addc_co_u32_e64 v0, s[26:27], 0, v0, s[14:15]
	v_addc_co_u32_e64 v34, s[24:25], 0, v34, s[16:17]
	v_addc_co_u32_e64 v0, s[26:27], 0, v0, s[22:23]
	v_cmp_le_u32_e64 s[12:13], s38, v144
	v_cmp_le_u32_e64 s[14:15], s38, v148
	v_cmp_le_u32_e64 s[16:17], s38, v145
	v_cmp_le_u32_e64 s[22:23], s38, v149
	v_addc_co_u32_e64 v34, s[24:25], 0, v34, s[12:13]
	v_addc_co_u32_e64 v0, s[26:27], 0, v0, s[14:15]
	v_addc_co_u32_e64 v34, s[24:25], 0, v34, s[16:17]
	v_addc_co_u32_e64 v0, s[26:27], 0, v0, s[22:23]
	v_cmp_le_u32_e64 s[12:13], s38, v150
	v_cmp_le_u32_e64 s[14:15], s38, v152
	v_cmp_le_u32_e64 s[16:17], s38, v151
	v_cmp_le_u32_e64 s[22:23], s38, v154
	v_addc_co_u32_e64 v34, s[24:25], 0, v34, s[12:13]
	v_addc_co_u32_e64 v0, s[26:27], 0, v0, s[14:15]
	v_addc_co_u32_e64 v34, s[24:25], 0, v34, s[16:17]
	v_addc_co_u32_e64 v0, s[26:27], 0, v0, s[22:23]
	v_cmp_le_u32_e64 s[12:13], s38, v153
	v_cmp_le_u32_e64 s[14:15], s38, v156
	v_cmp_le_u32_e64 s[16:17], s38, v155
	v_cmp_le_u32_e64 s[22:23], s38, v157
	v_addc_co_u32_e64 v34, s[24:25], 0, v34, s[12:13]
	v_addc_co_u32_e64 v0, s[26:27], 0, v0, s[14:15]
	v_addc_co_u32_e64 v34, s[24:25], 0, v34, s[16:17]
	v_addc_co_u32_e64 v0, s[26:27], 0, v0, s[22:23]
	v_cmp_le_u32_e64 s[12:13], s38, v158
	v_cmp_le_u32_e64 s[14:15], s38, v160
	v_cmp_le_u32_e64 s[16:17], s38, v159
	v_cmp_le_u32_e64 s[22:23], s38, v161
	v_addc_co_u32_e64 v34, s[24:25], 0, v34, s[12:13]
	v_addc_co_u32_e64 v0, s[26:27], 0, v0, s[14:15]
	v_addc_co_u32_e64 v34, s[24:25], 0, v34, s[16:17]
	v_addc_co_u32_e64 v0, s[26:27], 0, v0, s[22:23]
	v_cmp_le_u32_e64 s[12:13], s38, v167
	v_cmp_le_u32_e64 s[14:15], s38, v169
	v_cmp_le_u32_e64 s[16:17], s38, v168
	v_cmp_le_u32_e64 s[22:23], s38, v170
	v_addc_co_u32_e64 v34, s[24:25], 0, v34, s[12:13]
	v_addc_co_u32_e64 v0, s[26:27], 0, v0, s[14:15]
	v_addc_co_u32_e64 v34, s[24:25], 0, v34, s[16:17]
	v_addc_co_u32_e64 v0, s[26:27], 0, v0, s[22:23]
	v_cmp_le_u32_e64 s[12:13], s38, v173
	v_cmp_le_u32_e64 s[14:15], s38, v174
	v_cmp_le_u32_e64 s[16:17], s38, v175
	v_cmp_le_u32_e64 s[22:23], s38, v176
	v_addc_co_u32_e64 v34, s[24:25], 0, v34, s[12:13]
	v_addc_co_u32_e64 v0, s[26:27], 0, v0, s[14:15]
	v_addc_co_u32_e64 v34, s[24:25], 0, v34, s[16:17]
	v_addc_co_u32_e64 v0, s[26:27], 0, v0, s[22:23]
.LBB0_139:
	s_or_b64 exec, exec, s[10:11]
	s_and_saveexec_b64 s[10:11], s[6:7]
	s_cbranch_execz .LBB0_141
	v_cmp_le_u32_e64 s[12:13], s38, v76
	v_cmp_le_u32_e64 s[14:15], s38, v78
	v_cmp_le_u32_e64 s[16:17], s38, v77
	v_cmp_le_u32_e64 s[22:23], s38, v79
	v_addc_co_u32_e64 v34, s[24:25], 0, v34, s[12:13]
	v_addc_co_u32_e64 v0, s[26:27], 0, v0, s[14:15]
	v_addc_co_u32_e64 v34, s[24:25], 0, v34, s[16:17]
	v_addc_co_u32_e64 v0, s[26:27], 0, v0, s[22:23]
	v_cmp_le_u32_e64 s[12:13], s38, v80
	v_cmp_le_u32_e64 s[14:15], s38, v84
	v_cmp_le_u32_e64 s[16:17], s38, v81
	v_cmp_le_u32_e64 s[22:23], s38, v85
	v_addc_co_u32_e64 v34, s[24:25], 0, v34, s[12:13]
	v_addc_co_u32_e64 v0, s[26:27], 0, v0, s[14:15]
	v_addc_co_u32_e64 v34, s[24:25], 0, v34, s[16:17]
	v_addc_co_u32_e64 v0, s[26:27], 0, v0, s[22:23]
	v_cmp_le_u32_e64 s[12:13], s38, v82
	v_cmp_le_u32_e64 s[14:15], s38, v86
	v_cmp_le_u32_e64 s[16:17], s38, v83
	v_cmp_le_u32_e64 s[22:23], s38, v87
	v_addc_co_u32_e64 v34, s[24:25], 0, v34, s[12:13]
	v_addc_co_u32_e64 v0, s[26:27], 0, v0, s[14:15]
	v_addc_co_u32_e64 v34, s[24:25], 0, v34, s[16:17]
	v_addc_co_u32_e64 v0, s[26:27], 0, v0, s[22:23]
	v_cmp_le_u32_e64 s[12:13], s38, v89
	v_cmp_le_u32_e64 s[14:15], s38, v91
	v_cmp_le_u32_e64 s[16:17], s38, v90
	v_cmp_le_u32_e64 s[22:23], s38, v93
	v_addc_co_u32_e64 v34, s[24:25], 0, v34, s[12:13]
	v_addc_co_u32_e64 v0, s[26:27], 0, v0, s[14:15]
	v_addc_co_u32_e64 v34, s[24:25], 0, v34, s[16:17]
	v_addc_co_u32_e64 v0, s[26:27], 0, v0, s[22:23]
	v_cmp_le_u32_e64 s[12:13], s38, v92
	v_cmp_le_u32_e64 s[14:15], s38, v95
	v_cmp_le_u32_e64 s[16:17], s38, v94
	v_cmp_le_u32_e64 s[22:23], s38, v96
	v_addc_co_u32_e64 v34, s[24:25], 0, v34, s[12:13]
	v_addc_co_u32_e64 v0, s[26:27], 0, v0, s[14:15]
	v_addc_co_u32_e64 v34, s[24:25], 0, v34, s[16:17]
	v_addc_co_u32_e64 v0, s[26:27], 0, v0, s[22:23]
	v_cmp_le_u32_e64 s[12:13], s38, v97
	v_cmp_le_u32_e64 s[14:15], s38, v172
	v_cmp_le_u32_e64 s[16:17], s38, v171
	v_cmp_le_u32_e64 s[22:23], s38, v178
	v_addc_co_u32_e64 v34, s[24:25], 0, v34, s[12:13]
	v_addc_co_u32_e64 v0, s[26:27], 0, v0, s[14:15]
	v_addc_co_u32_e64 v34, s[24:25], 0, v34, s[16:17]
	v_addc_co_u32_e64 v0, s[26:27], 0, v0, s[22:23]
	v_cmp_le_u32_e64 s[12:13], s38, v180
	v_cmp_le_u32_e64 s[14:15], s38, v183
	v_cmp_le_u32_e64 s[16:17], s38, v182
	v_cmp_le_u32_e64 s[22:23], s38, v184
	v_addc_co_u32_e64 v34, s[24:25], 0, v34, s[12:13]
	v_addc_co_u32_e64 v0, s[26:27], 0, v0, s[14:15]
	v_addc_co_u32_e64 v34, s[24:25], 0, v34, s[16:17]
	v_addc_co_u32_e64 v0, s[26:27], 0, v0, s[22:23]
	v_cmp_le_u32_e64 s[12:13], s38, v186
	v_cmp_le_u32_e64 s[14:15], s38, v187
	v_cmp_le_u32_e64 s[16:17], s38, v188
	v_cmp_le_u32_e64 s[22:23], s38, v189
	v_addc_co_u32_e64 v34, s[24:25], 0, v34, s[12:13]
	v_addc_co_u32_e64 v0, s[26:27], 0, v0, s[14:15]
	v_addc_co_u32_e64 v34, s[24:25], 0, v34, s[16:17]
	v_addc_co_u32_e64 v0, s[26:27], 0, v0, s[22:23]

; __device__ __forceinline__ float keyval(unsigned k) { return __uint_as_float((k & 0x80000000u) ? (k ^ 0x80000000u) : ~k); }
; __device__ __forceinline__ unsigned valkey(float f) { const unsigned b = __float_as_uint(f); return b ^ ((unsigned)((int)b >> 31) | 0x80000000u); }
; __device__ __forceinline__ void select_query(const unsigned (&u)[64], unsigned vmax, int q, int b, int lane, unsigned* MASKb) {
;     ...
;         while (!done) {
;             if (hi - lo <= 1u) { T = lo; exact = false; break; }
;             const float vlo = keyval(lo), vhi = keyval(hi);
;             const float frac = (it >= 9 && (it & 1)) ? 0.5f : Llo * __builtin_amdgcn_rcpf(Llo + Lhi);
;             unsigned mid = valkey(vlo + frac * (vhi - vlo));
;             if (mid <= lo) mid = lo + 1u;
;             if (mid >= hi) mid = hi - 1u;
;             mid = __builtin_amdgcn_readfirstlane(mid);
;             const int c = count_ge(u, mid, nblk);
.LBB0_152:
	s_sub_i32 s14, s12, s13
	s_cmp_lt_u32 s14, 2
	s_cbranch_scc1 .LBB0_150
	s_cmp_gt_i32 s13, -1
	s_cselect_b32 s15, -1, 0x80000000
	s_cmp_gt_i32 s12, -1
	s_cselect_b32 s14, -1, 0x80000000
	v_add_f32_e32 v35, v34, v0
	s_xor_b64 s[14:15], s[14:15], s[12:13]
	v_rcp_f32_e32 v35, v35
	s_cmp_lt_i32 s22, 9
	s_cselect_b64 s[16:17], -1, 0
	s_bitcmp0_b32 s22, 0
	s_cselect_b64 s[18:19], -1, 0
	v_mul_f32_e32 v35, v0, v35
	s_or_b64 vcc, s[16:17], s[18:19]
	v_mov_b32_e32 v36, s15
	v_cndmask_b32_e32 v35, 0.5, v35, vcc
	v_sub_f32_e32 v36, s14, v36
	v_fma_f32 v35, v35, v36, s15
	v_ashrrev_i32_e32 v36, 31, v35
	v_bitop3_b32 v35, v36, v35, s38 bitop3:0x36
	s_add_i32 s14, s13, 1
	v_mov_b32_e32 v36, s14
	v_cmp_lt_u32_e32 vcc, s13, v35
	s_add_i32 s14, s12, -1
	s_nop 0
	v_cndmask_b32_e32 v35, v36, v35, vcc
	v_mov_b32_e32 v36, s14
	v_cmp_gt_u32_e32 vcc, s12, v35
	s_nop 1
	v_cndmask_b32_e32 v35, v36, v35, vcc
	v_mov_b32_e32 v36, 0
	v_readfirstlane_b32 s14, v35
	v_mov_b32_e32 v35, 0
	s_and_saveexec_b64 s[16:17], s[4:5]
	s_cbranch_execz .LBB0_155
	v_mov_b32_e32 v36, 0
	v_mov_b32_e32 v35, 0
	v_cmp_le_u32_e64 s[18:19], s14, v138
	v_cmp_le_u32_e64 s[24:25], s14, v140
	v_cmp_le_u32_e64 s[26:27], s14, v139
	v_cmp_le_u32_e64 s[28:29], s14, v141
	v_addc_co_u32_e64 v36, s[30:31], 0, v36, s[18:19]
	v_addc_co_u32_e64 v35, s[34:35], 0, v35, s[24:25]
	v_addc_co_u32_e64 v36, s[30:31], 0, v36, s[26:27]
	v_addc_co_u32_e64 v35, s[34:35], 0, v35, s[28:29]
	v_cmp_le_u32_e64 s[18:19], s14, v142
	v_cmp_le_u32_e64 s[24:25], s14, v146
	v_cmp_le_u32_e64 s[26:27], s14, v143
	v_cmp_le_u32_e64 s[28:29], s14, v147
	v_addc_co_u32_e64 v36, s[30:31], 0, v36, s[18:19]
	v_addc_co_u32_e64 v35, s[34:35], 0, v35, s[24:25]
	v_addc_co_u32_e64 v36, s[30:31], 0, v36, s[26:27]
	v_addc_co_u32_e64 v35, s[34:35], 0, v35, s[28:29]
	v_cmp_le_u32_e64 s[18:19], s14, v144
	v_cmp_le_u32_e64 s[24:25], s14, v148
	v_cmp_le_u32_e64 s[26:27], s14, v145
	v_cmp_le_u32_e64 s[28:29], s14, v149
	v_addc_co_u32_e64 v36, s[30:31], 0, v36, s[18:19]
	v_addc_co_u32_e64 v35, s[34:35], 0, v35, s[24:25]
	v_addc_co_u32_e64 v36, s[30:31], 0, v36, s[26:27]
	v_addc_co_u32_e64 v35, s[34:35], 0, v35, s[28:29]
	v_cmp_le_u32_e64 s[18:19], s14, v150
	v_cmp_le_u32_e64 s[24:25], s14, v152
	v_cmp_le_u32_e64 s[26:27], s14, v151
	v_cmp_le_u32_e64 s[28:29], s14, v154
	v_addc_co_u32_e64 v36, s[30:31], 0, v36, s[18:19]
	v_addc_co_u32_e64 v35, s[34:35], 0, v35, s[24:25]
	v_addc_co_u32_e64 v36, s[30:31], 0, v36, s[26:27]
	v_addc_co_u32_e64 v35, s[34:35], 0, v35, s[28:29]
	v_cmp_le_u32_e64 s[18:19], s14, v153
	v_cmp_le_u32_e64 s[24:25], s14, v156
	v_cmp_le_u32_e64 s[26:27], s14, v155
	v_cmp_le_u32_e64 s[28:29], s14, v157
	v_addc_co_u32_e64 v36, s[30:31], 0, v36, s[18:19]
	v_addc_co_u32_e64 v35, s[34:35], 0, v35, s[24:25]
	v_addc_co_u32_e64 v36, s[30:31], 0, v36, s[26:27]
	v_addc_co_u32_e64 v35, s[34:35], 0, v35, s[28:29]
	v_cmp_le_u32_e64 s[18:19], s14, v158
	v_cmp_le_u32_e64 s[24:25], s14, v160
	v_cmp_le_u32_e64 s[26:27], s14, v159
	v_cmp_le_u32_e64 s[28:29], s14, v161
	v_addc_co_u32_e64 v36, s[30:31], 0, v36, s[18:19]
	v_addc_co_u32_e64 v35, s[34:35], 0, v35, s[24:25]
	v_addc_co_u32_e64 v36, s[30:31], 0, v36, s[26:27]
	v_addc_co_u32_e64 v35, s[34:35], 0, v35, s[28:29]
	v_cmp_le_u32_e64 s[18:19], s14, v167
	v_cmp_le_u32_e64 s[24:25], s14, v169
	v_cmp_le_u32_e64 s[26:27], s14, v168
	v_cmp_le_u32_e64 s[28:29], s14, v170
	v_addc_co_u32_e64 v36, s[30:31], 0, v36, s[18:19]
	v_addc_co_u32_e64 v35, s[34:35], 0, v35, s[24:25]
	v_addc_co_u32_e64 v36, s[30:31], 0, v36, s[26:27]
	v_addc_co_u32_e64 v35, s[34:35], 0, v35, s[28:29]
	v_cmp_le_u32_e64 s[18:19], s14, v173
	v_cmp_le_u32_e64 s[24:25], s14, v174
	v_cmp_le_u32_e64 s[26:27], s14, v175
	v_cmp_le_u32_e64 s[28:29], s14, v176
	v_addc_co_u32_e64 v36, s[30:31], 0, v36, s[18:19]
	v_addc_co_u32_e64 v35, s[34:35], 0, v35, s[24:25]
	v_addc_co_u32_e64 v36, s[30:31], 0, v36, s[26:27]
	v_addc_co_u32_e64 v35, s[34:35], 0, v35, s[28:29]
.LBB0_155:
	s_or_b64 exec, exec, s[16:17]
	s_and_saveexec_b64 s[16:17], s[6:7]
	s_cbranch_execz .LBB0_157
	v_cmp_le_u32_e64 s[18:19], s14, v76
	v_cmp_le_u32_e64 s[24:25], s14, v78
	v_cmp_le_u32_e64 s[26:27], s14, v77
	v_cmp_le_u32_e64 s[28:29], s14, v79
	v_addc_co_u32_e64 v36, s[30:31], 0, v36, s[18:19]
	v_addc_co_u32_e64 v35, s[34:35], 0, v35, s[24:25]
	v_addc_co_u32_e64 v36, s[30:31], 0, v36, s[26:27]
	v_addc_co_u32_e64 v35, s[34:35], 0, v35, s[28:29]
	v_cmp_le_u32_e64 s[18:19], s14, v80
	v_cmp_le_u32_e64 s[24:25], s14, v84
	v_cmp_le_u32_e64 s[26:27], s14, v81
	v_cmp_le_u32_e64 s[28:29], s14, v85
	v_addc_co_u32_e64 v36, s[30:31], 0, v36, s[18:19]
	v_addc_co_u32_e64 v35, s[34:35], 0, v35, s[24:25]
	v_addc_co_u32_e64 v36, s[30:31], 0, v36, s[26:27]
	v_addc_co_u32_e64 v35, s[34:35], 0, v35, s[28:29]
	v_cmp_le_u32_e64 s[18:19], s14, v82
	v_cmp_le_u32_e64 s[24:25], s14, v86
	v_cmp_le_u32_e64 s[26:27], s14, v83
	v_cmp_le_u32_e64 s[28:29], s14, v87
	v_addc_co_u32_e64 v36, s[30:31], 0, v36, s[18:19]
	v_addc_co_u32_e64 v35, s[34:35], 0, v35, s[24:25]
	v_addc_co_u32_e64 v36, s[30:31], 0, v36, s[26:27]
	v_addc_co_u32_e64 v35, s[34:35], 0, v35, s[28:29]
	v_cmp_le_u32_e64 s[18:19], s14, v89
	v_cmp_le_u32_e64 s[24:25], s14, v91
	v_cmp_le_u32_e64 s[26:27], s14, v90
	v_cmp_le_u32_e64 s[28:29], s14, v93
	v_addc_co_u32_e64 v36, s[30:31], 0, v36, s[18:19]
	v_addc_co_u32_e64 v35, s[34:35], 0, v35, s[24:25]
	v_addc_co_u32_e64 v36, s[30:31], 0, v36, s[26:27]
	v_addc_co_u32_e64 v35, s[34:35], 0, v35, s[28:29]
	v_cmp_le_u32_e64 s[18:19], s14, v92
	v_cmp_le_u32_e64 s[24:25], s14, v95
	v_cmp_le_u32_e64 s[26:27], s14, v94
	v_cmp_le_u32_e64 s[28:29], s14, v96
	v_addc_co_u32_e64 v36, s[30:31], 0, v36, s[18:19]
	v_addc_co_u32_e64 v35, s[34:35], 0, v35, s[24:25]
	v_addc_co_u32_e64 v36, s[30:31], 0, v36, s[26:27]
	v_addc_co_u32_e64 v35, s[34:35], 0, v35, s[28:29]
	v_cmp_le_u32_e64 s[18:19], s14, v97
	v_cmp_le_u32_e64 s[24:25], s14, v172
	v_cmp_le_u32_e64 s[26:27], s14, v171
	v_cmp_le_u32_e64 s[28:29], s14, v178
	v_addc_co_u32_e64 v36, s[30:31], 0, v36, s[18:19]
	v_addc_co_u32_e64 v35, s[34:35], 0, v35, s[24:25]
	v_addc_co_u32_e64 v36, s[30:31], 0, v36, s[26:27]
	v_addc_co_u32_e64 v35, s[34:35], 0, v35, s[28:29]
	v_cmp_le_u32_e64 s[18:19], s14, v180
	v_cmp_le_u32_e64 s[24:25], s14, v183
	v_cmp_le_u32_e64 s[26:27], s14, v182
	v_cmp_le_u32_e64 s[28:29], s14, v184
	v_addc_co_u32_e64 v36, s[30:31], 0, v36, s[18:19]
	v_addc_co_u32_e64 v35, s[34:35], 0, v35, s[24:25]
	v_addc_co_u32_e64 v36, s[30:31], 0, v36, s[26:27]
	v_addc_co_u32_e64 v35, s[34:35], 0, v35, s[28:29]
	v_cmp_le_u32_e64 s[18:19], s14, v186
	v_cmp_le_u32_e64 s[24:25], s14, v187
	v_cmp_le_u32_e64 s[26:27], s14, v188
	v_cmp_le_u32_e64 s[28:29], s14, v189
	v_addc_co_u32_e64 v36, s[30:31], 0, v36, s[18:19]
	v_addc_co_u32_e64 v35, s[34:35], 0, v35, s[24:25]
	v_addc_co_u32_e64 v36, s[30:31], 0, v36, s[26:27]
	v_addc_co_u32_e64 v35, s[34:35], 0, v35, s[28:29]

; __device__ __forceinline__ int count_ge(const unsigned (&u)[64], unsigned cand, int nblk) {
;     int c0 = 0, c1 = 0;
;     const unsigned ts = __builtin_amdgcn_readfirstlane(cand);
; #pragma unroll
;     for (int B = 0; B < 2; ++B) {
;         if (B < nblk) {
; #pragma unroll
;             for (int i = 0; i < 32; i += 4) CNT4(c0, c1, ts, u[B * 32 + i], u[B * 32 + i + 1], u[B * 32 + i + 2], u[B * 32 + i + 3]);
;         }
;     }
;     return wave_isum(c0 + c1);
; }
; __device__ __forceinline__ void select_query(const unsigned (&u)[64], unsigned vmax, int q, int b, int lane, unsigned* MASKb) {
;     ...
;         if (exact) TG = T - 1u; else { TG = T; rrem = 256 - count_ge(u, T + 1u, nblk); }
.LBB0_164:
	s_andn2_b64 vcc, exec, s[10:11]
	s_mov_b64 s[10:11], -1
	s_cbranch_vccz .LBB0_170
	s_add_i32 s12, s21, 1
	v_mov_b32_e32 v0, 0
	v_mov_b32_e32 v34, 0
	s_and_saveexec_b64 s[10:11], s[4:5]
	s_cbranch_execz .LBB0_167
	v_mov_b32_e32 v34, v1
	v_mov_b32_e32 v0, v1
	v_cmp_le_u32_e64 s[4:5], s12, v138
	v_cmp_le_u32_e64 s[14:15], s12, v140
	v_cmp_le_u32_e64 s[16:17], s12, v139
	v_cmp_le_u32_e64 s[18:19], s12, v141
	v_addc_co_u32_e64 v34, s[22:23], 0, v34, s[4:5]
	v_addc_co_u32_e64 v0, s[24:25], 0, v0, s[14:15]
	v_addc_co_u32_e64 v34, s[22:23], 0, v34, s[16:17]
	v_addc_co_u32_e64 v0, s[24:25], 0, v0, s[18:19]
	v_cmp_le_u32_e64 s[4:5], s12, v142
	v_cmp_le_u32_e64 s[14:15], s12, v146
	v_cmp_le_u32_e64 s[16:17], s12, v143
	v_cmp_le_u32_e64 s[18:19], s12, v147
	v_addc_co_u32_e64 v34, s[22:23], 0, v34, s[4:5]
	v_addc_co_u32_e64 v0, s[24:25], 0, v0, s[14:15]
	v_addc_co_u32_e64 v34, s[22:23], 0, v34, s[16:17]
	v_addc_co_u32_e64 v0, s[24:25], 0, v0, s[18:19]
	v_cmp_le_u32_e64 s[4:5], s12, v144
	v_cmp_le_u32_e64 s[14:15], s12, v148
	v_cmp_le_u32_e64 s[16:17], s12, v145
	v_cmp_le_u32_e64 s[18:19], s12, v149
	v_addc_co_u32_e64 v34, s[22:23], 0, v34, s[4:5]
	v_addc_co_u32_e64 v0, s[24:25], 0, v0, s[14:15]
	v_addc_co_u32_e64 v34, s[22:23], 0, v34, s[16:17]
	v_addc_co_u32_e64 v0, s[24:25], 0, v0, s[18:19]
	v_cmp_le_u32_e64 s[4:5], s12, v150
	v_cmp_le_u32_e64 s[14:15], s12, v152
	v_cmp_le_u32_e64 s[16:17], s12, v151
	v_cmp_le_u32_e64 s[18:19], s12, v154
	v_addc_co_u32_e64 v34, s[22:23], 0, v34, s[4:5]
	v_addc_co_u32_e64 v0, s[24:25], 0, v0, s[14:15]
	v_addc_co_u32_e64 v34, s[22:23], 0, v34, s[16:17]
	v_addc_co_u32_e64 v0, s[24:25], 0, v0, s[18:19]
	v_cmp_le_u32_e64 s[4:5], s12, v153
	v_cmp_le_u32_e64 s[14:15], s12, v156
	v_cmp_le_u32_e64 s[16:17], s12, v155
	v_cmp_le_u32_e64 s[18:19], s12, v157
	v_addc_co_u32_e64 v34, s[22:23], 0, v34, s[4:5]
	v_addc_co_u32_e64 v0, s[24:25], 0, v0, s[14:15]
	v_addc_co_u32_e64 v34, s[22:23], 0, v34, s[16:17]
	v_addc_co_u32_e64 v0, s[24:25], 0, v0, s[18:19]
	v_cmp_le_u32_e64 s[4:5], s12, v158
	v_cmp_le_u32_e64 s[14:15], s12, v160
	v_cmp_le_u32_e64 s[16:17], s12, v159
	v_cmp_le_u32_e64 s[18:19], s12, v161
	v_addc_co_u32_e64 v34, s[22:23], 0, v34, s[4:5]
	v_addc_co_u32_e64 v0, s[24:25], 0, v0, s[14:15]
	v_addc_co_u32_e64 v34, s[22:23], 0, v34, s[16:17]
	v_addc_co_u32_e64 v0, s[24:25], 0, v0, s[18:19]
	v_cmp_le_u32_e64 s[4:5], s12, v167
	v_cmp_le_u32_e64 s[14:15], s12, v169
	v_cmp_le_u32_e64 s[16:17], s12, v168
	v_cmp_le_u32_e64 s[18:19], s12, v170
	v_addc_co_u32_e64 v34, s[22:23], 0, v34, s[4:5]
	v_addc_co_u32_e64 v0, s[24:25], 0, v0, s[14:15]
	v_addc_co_u32_e64 v34, s[22:23], 0, v34, s[16:17]
	v_addc_co_u32_e64 v0, s[24:25], 0, v0, s[18:19]
	v_cmp_le_u32_e64 s[4:5], s12, v173
	v_cmp_le_u32_e64 s[14:15], s12, v174
	v_cmp_le_u32_e64 s[16:17], s12, v175
	v_cmp_le_u32_e64 s[18:19], s12, v176
	v_addc_co_u32_e64 v34, s[22:23], 0, v34, s[4:5]
	v_addc_co_u32_e64 v0, s[24:25], 0, v0, s[14:15]
	v_addc_co_u32_e64 v34, s[22:23], 0, v34, s[16:17]
	v_addc_co_u32_e64 v0, s[24:25], 0, v0, s[18:19]
.LBB0_167:
	s_or_b64 exec, exec, s[10:11]
	s_and_saveexec_b64 s[4:5], s[6:7]
	s_cbranch_execz .LBB0_169
	v_cmp_le_u32_e64 s[6:7], s12, v76
	v_cmp_le_u32_e64 s[10:11], s12, v78
	v_cmp_le_u32_e64 s[14:15], s12, v77
	v_cmp_le_u32_e64 s[16:17], s12, v79
	v_addc_co_u32_e64 v34, s[18:19], 0, v34, s[6:7]
	v_addc_co_u32_e64 v0, s[22:23], 0, v0, s[10:11]
	v_addc_co_u32_e64 v34, s[18:19], 0, v34, s[14:15]
	v_addc_co_u32_e64 v0, s[22:23], 0, v0, s[16:17]
	v_cmp_le_u32_e64 s[6:7], s12, v80
	v_cmp_le_u32_e64 s[10:11], s12, v84
	v_cmp_le_u32_e64 s[14:15], s12, v81
	v_cmp_le_u32_e64 s[16:17], s12, v85
	v_addc_co_u32_e64 v34, s[18:19], 0, v34, s[6:7]
	v_addc_co_u32_e64 v0, s[22:23], 0, v0, s[10:11]
	v_addc_co_u32_e64 v34, s[18:19], 0, v34, s[14:15]
	v_addc_co_u32_e64 v0, s[22:23], 0, v0, s[16:17]
	v_cmp_le_u32_e64 s[6:7], s12, v82
	v_cmp_le_u32_e64 s[10:11], s12, v86
	v_cmp_le_u32_e64 s[14:15], s12, v83
	v_cmp_le_u32_e64 s[16:17], s12, v87
	v_addc_co_u32_e64 v34, s[18:19], 0, v34, s[6:7]
	v_addc_co_u32_e64 v0, s[22:23], 0, v0, s[10:11]
	v_addc_co_u32_e64 v34, s[18:19], 0, v34, s[14:15]
	v_addc_co_u32_e64 v0, s[22:23], 0, v0, s[16:17]
	v_cmp_le_u32_e64 s[6:7], s12, v89
	v_cmp_le_u32_e64 s[10:11], s12, v91
	v_cmp_le_u32_e64 s[14:15], s12, v90
	v_cmp_le_u32_e64 s[16:17], s12, v93
	v_addc_co_u32_e64 v34, s[18:19], 0, v34, s[6:7]
	v_addc_co_u32_e64 v0, s[22:23], 0, v0, s[10:11]
	v_addc_co_u32_e64 v34, s[18:19], 0, v34, s[14:15]
	v_addc_co_u32_e64 v0, s[22:23], 0, v0, s[16:17]
	v_cmp_le_u32_e64 s[6:7], s12, v92
	v_cmp_le_u32_e64 s[10:11], s12, v95
	v_cmp_le_u32_e64 s[14:15], s12, v94
	v_cmp_le_u32_e64 s[16:17], s12, v96
	v_addc_co_u32_e64 v34, s[18:19], 0, v34, s[6:7]
	v_addc_co_u32_e64 v0, s[22:23], 0, v0, s[10:11]
	v_addc_co_u32_e64 v34, s[18:19], 0, v34, s[14:15]
	v_addc_co_u32_e64 v0, s[22:23], 0, v0, s[16:17]
	v_cmp_le_u32_e64 s[6:7], s12, v97
	v_cmp_le_u32_e64 s[10:11], s12, v172
	v_cmp_le_u32_e64 s[14:15], s12, v171
	v_cmp_le_u32_e64 s[16:17], s12, v178
	v_addc_co_u32_e64 v34, s[18:19], 0, v34, s[6:7]
	v_addc_co_u32_e64 v0, s[22:23], 0, v0, s[10:11]
	v_addc_co_u32_e64 v34, s[18:19], 0, v34, s[14:15]
	v_addc_co_u32_e64 v0, s[22:23], 0, v0, s[16:17]
	v_cmp_le_u32_e64 s[6:7], s12, v180
	v_cmp_le_u32_e64 s[10:11], s12, v183
	v_cmp_le_u32_e64 s[14:15], s12, v182
	v_cmp_le_u32_e64 s[16:17], s12, v184
	v_addc_co_u32_e64 v34, s[18:19], 0, v34, s[6:7]
	v_addc_co_u32_e64 v0, s[22:23], 0, v0, s[10:11]
	v_addc_co_u32_e64 v34, s[18:19], 0, v34, s[14:15]
	v_addc_co_u32_e64 v0, s[22:23], 0, v0, s[16:17]
	v_cmp_le_u32_e64 s[6:7], s12, v186
	v_cmp_le_u32_e64 s[10:11], s12, v187
	v_cmp_le_u32_e64 s[14:15], s12, v188
	v_cmp_le_u32_e64 s[16:17], s12, v189
	v_addc_co_u32_e64 v34, s[18:19], 0, v34, s[6:7]
	v_addc_co_u32_e64 v0, s[22:23], 0, v0, s[10:11]
	v_addc_co_u32_e64 v34, s[18:19], 0, v34, s[14:15]
	v_addc_co_u32_e64 v0, s[22:23], 0, v0, s[16:17]

; __device__ __forceinline__ void select_query(const unsigned (&u)[64], unsigned vmax, int q, int b, int lane, unsigned* MASKb) {
;     ...
;     int tbase = 0;
; #pragma unroll
;     for (int B = 0; B < 2; ++B) {
;         if (B < nblk) {
;             unsigned w = 0u; const unsigned tgs = __builtin_amdgcn_readfirstlane(TG);
; #pragma unroll
;             for (int e = 31; e >= 3; e -= 4) BIT4(w, tgs, u[B * 32 + e], u[B * 32 + e - 1], u[B * 32 + e - 2], u[B * 32 + e - 3]);
;             if (rrem > 0) {
;                 int ec = 0;
; #pragma unroll
;                 for (int e = 0; e < 32; ++e) ec += (u[B * 32 + e] == T) ? 1 : 0;
;                 int incl = ec;
; #pragma unroll
;                 for (int o = 1; o < 64; o <<= 1) { const int t = __shfl_up(incl, o); if (lane >= o) incl += t; }
;                 const int total = __builtin_amdgcn_readlane(incl, 63);
;                 const int quota = rrem - tbase - (incl - ec);
.LBB0_173:
	s_or_b64 exec, exec, s[8:9]
	v_ashrrev_i32_e64 v88, 5, s75
	v_lshl_add_u32 v34, s20, 7, v88
	v_ashrrev_i32_e32 v35, 31, v34
	v_and_b32_e64 v0, s75, 30
	v_readlane_b32 s4, v255, 41
	v_lshlrev_b64 v[34:35], 7, v[34:35]
	v_ashrrev_i32_e32 v69, 31, v68
	v_lshlrev_b32_e32 v0, 2, v0
	v_readlane_b32 s5, v255, 42
	v_mov_b32_e32 v185, 0
	v_cmp_lt_i32_e32 vcc, 0, v191
	v_lshl_add_u64 v[34:35], v[34:35], 0, v[68:69]
	v_lshl_add_u64 v[36:37], s[4:5], 0, v[0:1]
	v_cmp_lt_i32_e64 s[4:5], 0, v190
	s_and_saveexec_b64 s[72:73], s[4:5]
	s_cbranch_execz .LBB0_179
	v_mov_b32_e32 v0, 0
	v_readfirstlane_b32 s14, v193
	v_cmp_gt_u32_e64 s[4:5], v176, s14
	v_cmp_gt_u32_e64 s[6:7], v175, s14
	v_cmp_gt_u32_e64 s[8:9], v174, s14
	v_cmp_gt_u32_e64 s[10:11], v173, s14
	v_addc_co_u32_e64 v0, s[12:13], v0, v0, s[4:5]
	v_addc_co_u32_e64 v0, s[12:13], v0, v0, s[6:7]
	v_addc_co_u32_e64 v0, s[12:13], v0, v0, s[8:9]
	v_addc_co_u32_e64 v0, s[12:13], v0, v0, s[10:11]
	v_mov_b32_e32 v185, 0
	v_cmp_gt_u32_e64 s[4:5], v170, s14
	v_cmp_gt_u32_e64 s[6:7], v168, s14
	v_cmp_gt_u32_e64 s[8:9], v169, s14
	v_cmp_gt_u32_e64 s[10:11], v167, s14
	v_addc_co_u32_e64 v0, s[12:13], v0, v0, s[4:5]
	v_addc_co_u32_e64 v0, s[12:13], v0, v0, s[6:7]
	v_addc_co_u32_e64 v0, s[12:13], v0, v0, s[8:9]
	v_addc_co_u32_e64 v0, s[12:13], v0, v0, s[10:11]
	v_cmp_gt_u32_e64 s[4:5], v161, s14
	v_cmp_gt_u32_e64 s[6:7], v159, s14
	v_cmp_gt_u32_e64 s[8:9], v160, s14
	v_cmp_gt_u32_e64 s[10:11], v158, s14
	v_addc_co_u32_e64 v0, s[12:13], v0, v0, s[4:5]
	v_addc_co_u32_e64 v0, s[12:13], v0, v0, s[6:7]
	v_addc_co_u32_e64 v0, s[12:13], v0, v0, s[8:9]
	v_addc_co_u32_e64 v0, s[12:13], v0, v0, s[10:11]
	v_cmp_gt_u32_e64 s[4:5], v157, s14
	v_cmp_gt_u32_e64 s[6:7], v155, s14
	v_cmp_gt_u32_e64 s[8:9], v156, s14
	v_cmp_gt_u32_e64 s[10:11], v153, s14
	v_addc_co_u32_e64 v0, s[12:13], v0, v0, s[4:5]
	v_addc_co_u32_e64 v0, s[12:13], v0, v0, s[6:7]
	v_addc_co_u32_e64 v0, s[12:13], v0, v0, s[8:9]
	v_addc_co_u32_e64 v0, s[12:13], v0, v0, s[10:11]
	v_cmp_gt_u32_e64 s[4:5], v154, s14
	v_cmp_gt_u32_e64 s[6:7], v151, s14
	v_cmp_gt_u32_e64 s[8:9], v152, s14
	v_cmp_gt_u32_e64 s[10:11], v150, s14
	v_addc_co_u32_e64 v0, s[12:13], v0, v0, s[4:5]
	v_addc_co_u32_e64 v0, s[12:13], v0, v0, s[6:7]
	v_addc_co_u32_e64 v0, s[12:13], v0, v0, s[8:9]
	v_addc_co_u32_e64 v0, s[12:13], v0, v0, s[10:11]
	v_cmp_gt_u32_e64 s[4:5], v149, s14
	v_cmp_gt_u32_e64 s[6:7], v145, s14
	v_cmp_gt_u32_e64 s[8:9], v148, s14
	v_cmp_gt_u32_e64 s[10:11], v144, s14
	v_addc_co_u32_e64 v0, s[12:13], v0, v0, s[4:5]
	v_addc_co_u32_e64 v0, s[12:13], v0, v0, s[6:7]
	v_addc_co_u32_e64 v0, s[12:13], v0, v0, s[8:9]
	v_addc_co_u32_e64 v0, s[12:13], v0, v0, s[10:11]
	v_cmp_gt_u32_e64 s[4:5], v147, s14
	v_cmp_gt_u32_e64 s[6:7], v143, s14
	v_cmp_gt_u32_e64 s[8:9], v146, s14
	v_cmp_gt_u32_e64 s[10:11], v142, s14
	v_addc_co_u32_e64 v0, s[12:13], v0, v0, s[4:5]
	v_addc_co_u32_e64 v0, s[12:13], v0, v0, s[6:7]
	v_addc_co_u32_e64 v0, s[12:13], v0, v0, s[8:9]
	v_addc_co_u32_e64 v0, s[12:13], v0, v0, s[10:11]
	v_cmp_gt_u32_e64 s[4:5], v141, s14
	v_cmp_gt_u32_e64 s[6:7], v139, s14
	v_cmp_gt_u32_e64 s[8:9], v140, s14
	v_cmp_gt_u32_e64 s[10:11], v138, s14
	v_addc_co_u32_e64 v0, s[12:13], v0, v0, s[4:5]
	v_addc_co_u32_e64 v0, s[12:13], v0, v0, s[6:7]
	v_addc_co_u32_e64 v0, s[12:13], v0, v0, s[8:9]
	v_addc_co_u32_e64 v0, s[12:13], v0, v0, s[10:11]
	s_and_saveexec_b64 s[90:91], vcc
	s_cbranch_execz .LBB0_176
	v_cmp_eq_u32_e64 s[4:5], v176, v192
	v_cmp_eq_u32_e64 s[6:7], v174, v192
	v_cmp_eq_u32_e64 s[8:9], v175, v192
	v_cndmask_b32_e64 v174, 0, 1, s[4:5]
	v_cmp_eq_u32_e64 s[10:11], v170, v192
	v_addc_co_u32_e64 v174, s[12:13], 0, v174, s[8:9]
	v_cndmask_b32_e64 v170, 0, 1, s[6:7]
	v_cmp_eq_u32_e64 s[12:13], v173, v192
	v_cmp_eq_u32_e64 s[14:15], v169, v192
	v_cndmask_b32_e64 v169, 0, 1, s[10:11]
	v_addc_co_u32_e64 v170, s[18:19], v174, v170, s[12:13]
	v_cmp_eq_u32_e64 s[18:19], v168, v192
	v_cmp_eq_u32_e64 s[16:17], v161, v192
	v_cndmask_b32_e64 v161, 0, 1, s[14:15]
	v_addc_co_u32_e64 v168, s[24:25], v170, v169, s[18:19]
	v_cmp_eq_u32_e64 s[24:25], v167, v192
	v_cmp_eq_u32_e64 s[20:21], v160, v192
	v_cndmask_b32_e64 v160, 0, 1, s[16:17]
	v_addc_co_u32_e64 v161, s[28:29], v168, v161, s[24:25]
	v_cmp_eq_u32_e64 s[28:29], v159, v192
	v_cmp_eq_u32_e64 s[22:23], v157, v192
	v_cndmask_b32_e64 v157, 0, 1, s[20:21]
	v_addc_co_u32_e64 v159, s[36:37], v161, v160, s[28:29]
	v_cmp_eq_u32_e64 s[36:37], v158, v192
	v_cmp_eq_u32_e64 s[26:27], v156, v192
	v_cndmask_b32_e64 v156, 0, 1, s[22:23]
	v_addc_co_u32_e64 v157, s[42:43], v159, v157, s[36:37]
	v_cmp_eq_u32_e64 s[42:43], v155, v192
	v_cmp_eq_u32_e64 s[30:31], v154, v192
	v_cndmask_b32_e64 v154, 0, 1, s[26:27]
	v_addc_co_u32_e64 v155, s[48:49], v157, v156, s[42:43]
	v_cmp_eq_u32_e64 s[48:49], v153, v192
	v_cmp_eq_u32_e64 s[34:35], v152, v192
	v_cndmask_b32_e64 v152, 0, 1, s[30:31]
	v_addc_co_u32_e64 v153, s[52:53], v155, v154, s[48:49]
	v_cmp_eq_u32_e64 s[52:53], v151, v192
	s_mov_b32 s82, s38
	v_cmp_eq_u32_e64 s[38:39], v149, v192
	v_addc_co_u32_e64 v151, s[56:57], v153, v152, s[52:53]
	v_cndmask_b32_e64 v149, 0, 1, s[34:35]
	v_cmp_eq_u32_e64 s[56:57], v150, v192
	v_cmp_eq_u32_e64 s[40:41], v148, v192
	v_cndmask_b32_e64 v148, 0, 1, s[38:39]
	v_addc_co_u32_e64 v149, s[58:59], v151, v149, s[56:57]
	v_cmp_eq_u32_e64 s[58:59], v145, v192
	v_cmp_eq_u32_e64 s[44:45], v147, v192
	v_cndmask_b32_e64 v147, 0, 1, s[40:41]
	v_addc_co_u32_e64 v145, s[60:61], v149, v148, s[58:59]
	v_cmp_eq_u32_e64 s[60:61], v144, v192
	v_cmp_eq_u32_e64 s[46:47], v146, v192
	v_cndmask_b32_e64 v146, 0, 1, s[44:45]
	v_addc_co_u32_e64 v144, s[62:63], v145, v147, s[60:61]
	v_cmp_eq_u32_e64 s[62:63], v143, v192
	v_cmp_eq_u32_e64 s[50:51], v141, v192
	v_cndmask_b32_e64 v141, 0, 1, s[46:47]
	v_addc_co_u32_e64 v143, s[64:65], v144, v146, s[62:63]
	v_cmp_eq_u32_e64 s[64:65], v142, v192
	v_cmp_eq_u32_e64 s[54:55], v140, v192
	v_cndmask_b32_e64 v140, 0, 1, s[50:51]
	v_addc_co_u32_e64 v141, s[66:67], v143, v141, s[64:65]
	v_cmp_eq_u32_e64 s[66:67], v139, v192
	v_cndmask_b32_e64 v69, 0, 1, s[54:55]
	s_nop 0
	v_addc_co_u32_e64 v139, s[68:69], v141, v140, s[66:67]
	v_cmp_eq_u32_e64 s[68:69], v138, v192
	s_nop 1
	v_addc_co_u32_e64 v69, s[70:71], v139, v69, s[68:69]
	ds_bpermute_b32 v138, v100, v69
	v_cmp_lt_i32_e64 s[70:71], 0, v68
	s_waitcnt lgkmcnt(0)
; __device__ __forceinline__ void select_query(const unsigned (&u)[64], unsigned vmax, int q, int b, int lane, unsigned* MASKb) {
;     ...
;                 for (int o = 1; o < 64; o <<= 1) { const int t = __shfl_up(incl, o); if (lane >= o) incl += t; }
;                 const int total = __builtin_amdgcn_readlane(incl, 63);
;                 const int quota = rrem - tbase - (incl - ec);
;                 int taken = 0;
; #pragma unroll
;                 for (int e = 0; e < 32; ++e) { const bool is = (u[B * 32 + e] == T) && (taken < quota); w |= is ? (1u << e) : 0u; taken += is ? 1 : 0; }
	s_nop 0
	v_cndmask_b32_e64 v138, 0, v138, s[70:71]
	v_add_u32_e32 v138, v138, v69
	ds_bpermute_b32 v139, v101, v138
	v_cmp_lt_i32_e64 s[70:71], 1, v68
	v_add_u32_e32 v69, v69, v191
	s_waitcnt lgkmcnt(0)
	v_cndmask_b32_e64 v139, 0, v139, s[70:71]
	v_add_u32_e32 v138, v139, v138
	ds_bpermute_b32 v139, v102, v138
	v_cmp_lt_i32_e64 s[70:71], 3, v68
	s_waitcnt lgkmcnt(0)
	s_nop 0
	v_cndmask_b32_e64 v139, 0, v139, s[70:71]
	v_add_u32_e32 v138, v139, v138
	ds_bpermute_b32 v139, v103, v138
	v_cmp_lt_i32_e64 s[70:71], 7, v68
	s_waitcnt lgkmcnt(0)
	s_nop 0
	v_cndmask_b32_e64 v139, 0, v139, s[70:71]
	v_add_u32_e32 v138, v139, v138
	ds_bpermute_b32 v139, v104, v138
	v_cmp_lt_i32_e64 s[70:71], 15, v68
	s_waitcnt lgkmcnt(0)
	s_nop 0
	v_cndmask_b32_e64 v139, 0, v139, s[70:71]
	v_add_u32_e32 v138, v139, v138
	ds_bpermute_b32 v139, v105, v138
	v_cmp_lt_i32_e64 s[70:71], 31, v68
	s_waitcnt lgkmcnt(0)
	s_nop 0
	v_cndmask_b32_e64 v139, 0, v139, s[70:71]
	v_add_u32_e32 v138, v139, v138
	v_sub_u32_e32 v69, v69, v138
	v_cmp_lt_i32_e64 s[70:71], 0, v69
	s_and_b64 s[68:69], s[68:69], s[70:71]
	v_cndmask_b32_e64 v139, 0, 1, s[68:69]
	v_cmp_gt_i32_e64 s[68:69], v69, v139
	s_and_b64 s[54:55], s[54:55], s[68:69]
	v_cndmask_b32_e64 v140, 0, 2, s[54:55]
	v_cndmask_b32_e64 v141, 0, 1, s[54:55]
	v_addc_co_u32_e64 v142, s[54:55], 0, v139, s[54:55]
	v_cmp_lt_i32_e64 s[54:55], v142, v69
	s_and_b64 s[54:55], s[66:67], s[54:55]
	s_nop 0
	v_cndmask_b32_e64 v142, 0, 4, s[54:55]
	v_addc_co_u32_e64 v141, s[54:55], v141, v139, s[54:55]
	v_cmp_lt_i32_e64 s[54:55], v141, v69
	s_and_b64 s[50:51], s[50:51], s[54:55]
	v_cndmask_b32_e64 v143, 0, 8, s[50:51]
	v_cndmask_b32_e64 v144, 0, 1, s[50:51]
	v_addc_co_u32_e64 v145, s[50:51], 0, v141, s[50:51]
	v_cmp_lt_i32_e64 s[50:51], v145, v69
	s_and_b64 s[50:51], s[64:65], s[50:51]
	v_or3_b32 v140, v140, v142, v143
	v_cndmask_b32_e64 v146, 0, 16, s[50:51]
	v_cndmask_b32_e64 v147, 0, 1, s[50:51]
	v_addc_co_u32_e64 v141, s[50:51], v141, v144, s[50:51]
	v_cmp_lt_i32_e64 s[50:51], v141, v69
	s_and_b64 s[46:47], s[46:47], s[50:51]
	v_cndmask_b32_e64 v144, 0, 32, s[46:47]
	v_cndmask_b32_e64 v148, 0, 1, s[46:47]
	v_addc_co_u32_e64 v145, s[46:47], v145, v147, s[46:47]
	v_cmp_lt_i32_e64 s[46:47], v145, v69
	s_and_b64 s[46:47], s[62:63], s[46:47]
	v_or3_b32 v140, v140, v146, v144
	v_cndmask_b32_e64 v147, 0, 64, s[46:47]
	v_cndmask_b32_e64 v149, 0, 1, s[46:47]
	v_addc_co_u32_e64 v141, s[46:47], v141, v148, s[46:47]
	v_cmp_lt_i32_e64 s[46:47], v141, v69
	s_and_b64 s[44:45], s[44:45], s[46:47]
	v_mov_b32_e32 v148, 0x80
	v_cndmask_b32_e64 v148, 0, v148, s[44:45]
	v_cndmask_b32_e64 v150, 0, 1, s[44:45]
	v_addc_co_u32_e64 v145, s[44:45], v145, v149, s[44:45]
	v_cmp_lt_i32_e64 s[44:45], v145, v69
	s_and_b64 s[44:45], s[60:61], s[44:45]
	v_mov_b32_e32 v149, 0x100
	v_cndmask_b32_e64 v149, 0, v149, s[44:45]
	v_cndmask_b32_e64 v151, 0, 1, s[44:45]
	v_addc_co_u32_e64 v141, s[44:45], v141, v150, s[44:45]
	v_cmp_lt_i32_e64 s[44:45], v141, v69
	s_and_b64 s[40:41], s[40:41], s[44:45]
	v_mov_b32_e32 v150, 0x200
	v_cndmask_b32_e64 v150, 0, v150, s[40:41]
	v_cndmask_b32_e64 v152, 0, 1, s[40:41]
	v_addc_co_u32_e64 v145, s[40:41], v145, v151, s[40:41]
	v_cmp_lt_i32_e64 s[40:41], v145, v69
	s_and_b64 s[40:41], s[58:59], s[40:41]
	v_mov_b32_e32 v151, 0x400
	v_cndmask_b32_e64 v151, 0, v151, s[40:41]
	v_cndmask_b32_e64 v153, 0, 1, s[40:41]
	v_addc_co_u32_e64 v141, s[40:41], v141, v152, s[40:41]
	v_cmp_lt_i32_e64 s[40:41], v141, v69
	s_and_b64 s[38:39], s[38:39], s[40:41]
	v_mov_b32_e32 v152, 0x800
	v_cndmask_b32_e64 v152, 0, v152, s[38:39]
	v_cndmask_b32_e64 v154, 0, 1, s[38:39]
	v_addc_co_u32_e64 v145, s[38:39], v145, v153, s[38:39]
	v_cmp_lt_i32_e64 s[38:39], v145, v69
	s_and_b64 s[38:39], s[56:57], s[38:39]
	v_mov_b32_e32 v153, 0x1000
	v_cndmask_b32_e64 v153, 0, v153, s[38:39]
	v_cndmask_b32_e64 v155, 0, 1, s[38:39]
	v_addc_co_u32_e64 v141, s[38:39], v141, v154, s[38:39]
	v_cmp_lt_i32_e64 s[38:39], v141, v69
	s_and_b64 s[34:35], s[34:35], s[38:39]
	v_cndmask_b32_e64 v154, 0, v240, s[34:35]
	v_cndmask_b32_e64 v156, 0, 1, s[34:35]
	v_addc_co_u32_e64 v145, s[34:35], v145, v155, s[34:35]
	v_cmp_lt_i32_e64 s[34:35], v145, v69
	s_and_b64 s[34:35], s[52:53], s[34:35]
	v_mov_b32_e32 v155, 0x4000
	v_cndmask_b32_e64 v155, 0, v155, s[34:35]
	v_cndmask_b32_e64 v157, 0, 1, s[34:35]
	v_addc_co_u32_e64 v141, s[34:35], v141, v156, s[34:35]
	v_cmp_lt_i32_e64 s[34:35], v141, v69
	s_and_b64 s[30:31], s[30:31], s[34:35]
; __device__ __forceinline__ void select_query(const unsigned (&u)[64], unsigned vmax, int q, int b, int lane, unsigned* MASKb) {
;     ...
; #pragma unroll
;                 for (int e = 0; e < 32; ++e) { const bool is = (u[B * 32 + e] == T) && (taken < quota); w |= is ? (1u << e) : 0u; taken += is ? 1 : 0; }
;                 tbase += total;
;             }
;             if (64 * B + lane <= (q >> 5)) __hip_atomic_store(MASKb + ((size_t)(b * 128 + (q >> 5)) * 128 + 64 * B + lane) * 32 + (q & 31), w, __ATOMIC_RELAXED, __HIP_MEMORY_SCOPE_AGENT);
	v_mov_b32_e32 v156, 0x8000
	v_cndmask_b32_e64 v156, 0, v156, s[30:31]
	v_cndmask_b32_e64 v158, 0, 1, s[30:31]
	v_addc_co_u32_e64 v145, s[30:31], v145, v157, s[30:31]
	v_cmp_lt_i32_e64 s[30:31], v145, v69
	s_and_b64 s[30:31], s[48:49], s[30:31]
	v_mov_b32_e32 v157, 0x10000
	v_cndmask_b32_e64 v157, 0, v157, s[30:31]
	v_cndmask_b32_e64 v159, 0, 1, s[30:31]
	v_addc_co_u32_e64 v141, s[30:31], v141, v158, s[30:31]
	v_cmp_lt_i32_e64 s[30:31], v141, v69
	s_and_b64 s[26:27], s[26:27], s[30:31]
	v_mov_b32_e32 v158, 0x20000
	v_cndmask_b32_e64 v158, 0, v158, s[26:27]
	v_cndmask_b32_e64 v160, 0, 1, s[26:27]
	v_addc_co_u32_e64 v145, s[26:27], v145, v159, s[26:27]
	v_cmp_lt_i32_e64 s[26:27], v145, v69
	s_and_b64 s[26:27], s[42:43], s[26:27]
	v_mov_b32_e32 v159, 0x40000
	v_cndmask_b32_e64 v159, 0, v159, s[26:27]
	v_cndmask_b32_e64 v161, 0, 1, s[26:27]
	v_addc_co_u32_e64 v141, s[26:27], v141, v160, s[26:27]
	v_cmp_lt_i32_e64 s[26:27], v141, v69
	s_and_b64 s[22:23], s[22:23], s[26:27]
	v_mov_b32_e32 v160, 0x80000
	v_cndmask_b32_e64 v160, 0, v160, s[22:23]
	v_cndmask_b32_e64 v167, 0, 1, s[22:23]
	v_addc_co_u32_e64 v145, s[22:23], v145, v161, s[22:23]
	v_cmp_lt_i32_e64 s[22:23], v145, v69
	s_and_b64 s[22:23], s[36:37], s[22:23]
	v_mov_b32_e32 v161, 0x100000
	v_cndmask_b32_e64 v161, 0, v161, s[22:23]
	v_cndmask_b32_e64 v168, 0, 1, s[22:23]
	v_addc_co_u32_e64 v141, s[22:23], v141, v167, s[22:23]
	v_cmp_lt_i32_e64 s[22:23], v141, v69
	s_and_b64 s[20:21], s[20:21], s[22:23]
	v_mov_b32_e32 v167, 0x200000
	v_cndmask_b32_e64 v167, 0, v167, s[20:21]
	v_cndmask_b32_e64 v169, 0, 1, s[20:21]
	v_addc_co_u32_e64 v145, s[20:21], v145, v168, s[20:21]
	v_cmp_lt_i32_e64 s[20:21], v145, v69
	s_and_b64 s[20:21], s[28:29], s[20:21]
	v_mov_b32_e32 v168, 0x400000
	v_cndmask_b32_e64 v168, 0, v168, s[20:21]
	v_cndmask_b32_e64 v170, 0, 1, s[20:21]
	v_addc_co_u32_e64 v141, s[20:21], v141, v169, s[20:21]
	v_cmp_lt_i32_e64 s[20:21], v141, v69
	s_and_b64 s[16:17], s[16:17], s[20:21]
	v_mov_b32_e32 v169, 0x800000
	v_cndmask_b32_e64 v169, 0, v169, s[16:17]
	v_cndmask_b32_e64 v173, 0, 1, s[16:17]
	v_addc_co_u32_e64 v145, s[16:17], v145, v170, s[16:17]
	v_cmp_lt_i32_e64 s[16:17], v145, v69
	s_and_b64 s[16:17], s[24:25], s[16:17]
	v_mov_b32_e32 v170, 0x1000000
	v_cndmask_b32_e64 v170, 0, v170, s[16:17]
	v_cndmask_b32_e64 v174, 0, 1, s[16:17]
	v_addc_co_u32_e64 v141, s[16:17], v141, v173, s[16:17]
	v_cmp_lt_i32_e64 s[16:17], v141, v69
	s_and_b64 s[14:15], s[14:15], s[16:17]
	v_bfrev_b32_e32 v173, 64
	v_cndmask_b32_e64 v173, 0, v173, s[14:15]
	v_cndmask_b32_e64 v175, 0, 1, s[14:15]
	v_addc_co_u32_e64 v145, s[14:15], v145, v174, s[14:15]
	v_cmp_lt_i32_e64 s[14:15], v145, v69
	s_and_b64 s[14:15], s[18:19], s[14:15]
	v_bfrev_b32_e32 v174, 32
	v_cndmask_b32_e64 v174, 0, v174, s[14:15]
	v_cndmask_b32_e64 v176, 0, 1, s[14:15]
	v_addc_co_u32_e64 v141, s[14:15], v141, v175, s[14:15]
	v_cmp_lt_i32_e64 s[14:15], v141, v69
	s_and_b64 s[10:11], s[10:11], s[14:15]
	v_bfrev_b32_e32 v175, 16
	v_cndmask_b32_e64 v175, 0, v175, s[10:11]
	v_cndmask_b32_e64 v185, 0, 1, s[10:11]
	v_addc_co_u32_e64 v145, s[10:11], v145, v176, s[10:11]
	v_cmp_lt_i32_e64 s[10:11], v145, v69
	v_or3_b32 v140, v140, v147, v148
	s_and_b64 s[10:11], s[12:13], s[10:11]
	v_bfrev_b32_e32 v176, 8
	v_or3_b32 v140, v140, v149, v150
	v_cndmask_b32_e64 v176, 0, v176, s[10:11]
	v_cndmask_b32_e64 v194, 0, 1, s[10:11]
	v_addc_co_u32_e64 v141, s[10:11], v141, v185, s[10:11]
	v_or3_b32 v140, v140, v151, v152
	v_cmp_lt_i32_e64 s[10:11], v141, v69
	v_or3_b32 v140, v140, v153, v154
	s_and_b64 s[6:7], s[6:7], s[10:11]
	v_bfrev_b32_e32 v185, 4
	v_or3_b32 v140, v140, v155, v156
	v_cndmask_b32_e64 v185, 0, v185, s[6:7]
	v_cndmask_b32_e64 v195, 0, 1, s[6:7]
	v_addc_co_u32_e64 v145, s[6:7], v145, v194, s[6:7]
	v_or3_b32 v140, v140, v157, v158
	v_cmp_lt_i32_e64 s[6:7], v145, v69
	v_or3_b32 v140, v140, v159, v160
	s_and_b64 s[6:7], s[8:9], s[6:7]
	v_or3_b32 v140, v140, v161, v167
	v_cndmask_b32_e64 v145, 0, 2.0, s[6:7]
	v_addc_co_u32_e64 v141, s[6:7], v141, v195, s[6:7]
	v_or3_b32 v140, v140, v168, v169
	v_cmp_lt_i32_e64 s[6:7], v141, v69
	v_or3_b32 v140, v140, v170, v173
	s_and_b64 s[4:5], s[4:5], s[6:7]
	v_bfrev_b32_e32 v69, 1
	v_or3_b32 v140, v140, v174, v175
	v_cndmask_b32_e64 v69, 0, v69, s[4:5]
	v_or3_b32 v140, v140, v176, v185
	v_or3_b32 v69, v140, v145, v69
	v_readlane_b32 s4, v138, 63
	s_mov_b32 s38, s82
	v_or3_b32 v0, v69, v139, v0
	v_mov_b32_e32 v185, s4

; __device__ __forceinline__ void select_query(const unsigned (&u)[64], unsigned vmax, int q, int b, int lane, unsigned* MASKb) {
;     ...
;     int tbase = 0;
; #pragma unroll
;     for (int B = 0; B < 2; ++B) {
;         if (B < nblk) {
;             unsigned w = 0u; const unsigned tgs = __builtin_amdgcn_readfirstlane(TG);
; #pragma unroll
;             for (int e = 31; e >= 3; e -= 4) BIT4(w, tgs, u[B * 32 + e], u[B * 32 + e - 1], u[B * 32 + e - 2], u[B * 32 + e - 3]);
;             if (rrem > 0) {
;                 int ec = 0;
; #pragma unroll
;                 for (int e = 0; e < 32; ++e) ec += (u[B * 32 + e] == T) ? 1 : 0;
;                 int incl = ec;
; #pragma unroll
;                 for (int o = 1; o < 64; o <<= 1) { const int t = __shfl_up(incl, o); if (lane >= o) incl += t; }
;                 const int total = __builtin_amdgcn_readlane(incl, 63);
;                 const int quota = rrem - tbase - (incl - ec);
.LBB0_179:
	s_or_b64 exec, exec, s[72:73]
	v_cmp_lt_i32_e64 s[4:5], 1, v190
	s_and_saveexec_b64 s[70:71], s[4:5]
	s_cbranch_execz .LBB0_184
	v_mov_b32_e32 v0, v1
	v_readfirstlane_b32 s14, v193
	v_cmp_gt_u32_e64 s[4:5], v189, s14
	v_cmp_gt_u32_e64 s[6:7], v188, s14
	v_cmp_gt_u32_e64 s[8:9], v187, s14
	v_cmp_gt_u32_e64 s[10:11], v186, s14
	v_addc_co_u32_e64 v0, s[12:13], v0, v0, s[4:5]
	v_addc_co_u32_e64 v0, s[12:13], v0, v0, s[6:7]
	v_addc_co_u32_e64 v0, s[12:13], v0, v0, s[8:9]
	v_addc_co_u32_e64 v0, s[12:13], v0, v0, s[10:11]
	v_cmp_gt_u32_e64 s[4:5], v184, s14
	v_cmp_gt_u32_e64 s[6:7], v182, s14
	v_cmp_gt_u32_e64 s[8:9], v183, s14
	v_cmp_gt_u32_e64 s[10:11], v180, s14
	v_addc_co_u32_e64 v0, s[12:13], v0, v0, s[4:5]
	v_addc_co_u32_e64 v0, s[12:13], v0, v0, s[6:7]
	v_addc_co_u32_e64 v0, s[12:13], v0, v0, s[8:9]
	v_addc_co_u32_e64 v0, s[12:13], v0, v0, s[10:11]
	v_cmp_gt_u32_e64 s[4:5], v178, s14
	v_cmp_gt_u32_e64 s[6:7], v171, s14
	v_cmp_gt_u32_e64 s[8:9], v172, s14
	v_cmp_gt_u32_e64 s[10:11], v97, s14
	v_addc_co_u32_e64 v0, s[12:13], v0, v0, s[4:5]
	v_addc_co_u32_e64 v0, s[12:13], v0, v0, s[6:7]
	v_addc_co_u32_e64 v0, s[12:13], v0, v0, s[8:9]
	v_addc_co_u32_e64 v0, s[12:13], v0, v0, s[10:11]
	v_cmp_gt_u32_e64 s[4:5], v96, s14
	v_cmp_gt_u32_e64 s[6:7], v94, s14
	v_cmp_gt_u32_e64 s[8:9], v95, s14
	v_cmp_gt_u32_e64 s[10:11], v92, s14
	v_addc_co_u32_e64 v0, s[12:13], v0, v0, s[4:5]
	v_addc_co_u32_e64 v0, s[12:13], v0, v0, s[6:7]
	v_addc_co_u32_e64 v0, s[12:13], v0, v0, s[8:9]
	v_addc_co_u32_e64 v0, s[12:13], v0, v0, s[10:11]
	v_cmp_gt_u32_e64 s[4:5], v93, s14
	v_cmp_gt_u32_e64 s[6:7], v90, s14
	v_cmp_gt_u32_e64 s[8:9], v91, s14
	v_cmp_gt_u32_e64 s[10:11], v89, s14
	v_addc_co_u32_e64 v0, s[12:13], v0, v0, s[4:5]
	v_addc_co_u32_e64 v0, s[12:13], v0, v0, s[6:7]
	v_addc_co_u32_e64 v0, s[12:13], v0, v0, s[8:9]
	v_addc_co_u32_e64 v0, s[12:13], v0, v0, s[10:11]
	v_cmp_gt_u32_e64 s[4:5], v87, s14
	v_cmp_gt_u32_e64 s[6:7], v83, s14
	v_cmp_gt_u32_e64 s[8:9], v86, s14
	v_cmp_gt_u32_e64 s[10:11], v82, s14
	v_addc_co_u32_e64 v0, s[12:13], v0, v0, s[4:5]
	v_addc_co_u32_e64 v0, s[12:13], v0, v0, s[6:7]
	v_addc_co_u32_e64 v0, s[12:13], v0, v0, s[8:9]
	v_addc_co_u32_e64 v0, s[12:13], v0, v0, s[10:11]
	v_cmp_gt_u32_e64 s[4:5], v85, s14
	v_cmp_gt_u32_e64 s[6:7], v81, s14
	v_cmp_gt_u32_e64 s[8:9], v84, s14
	v_cmp_gt_u32_e64 s[10:11], v80, s14
	v_addc_co_u32_e64 v0, s[12:13], v0, v0, s[4:5]
	v_addc_co_u32_e64 v0, s[12:13], v0, v0, s[6:7]
	v_addc_co_u32_e64 v0, s[12:13], v0, v0, s[8:9]
	v_addc_co_u32_e64 v0, s[12:13], v0, v0, s[10:11]
	v_cmp_gt_u32_e64 s[4:5], v79, s14
	v_cmp_gt_u32_e64 s[6:7], v77, s14
	v_cmp_gt_u32_e64 s[8:9], v78, s14
	v_cmp_gt_u32_e64 s[10:11], v76, s14
	v_addc_co_u32_e64 v0, s[12:13], v0, v0, s[4:5]
	v_addc_co_u32_e64 v0, s[12:13], v0, v0, s[6:7]
	v_addc_co_u32_e64 v0, s[12:13], v0, v0, s[8:9]
	v_addc_co_u32_e64 v0, s[12:13], v0, v0, s[10:11]
	s_and_saveexec_b64 s[72:73], vcc
	s_cbranch_execz .LBB0_182
	v_cmp_eq_u32_e32 vcc, v189, v192
	v_cmp_eq_u32_e64 s[6:7], v188, v192
	v_cmp_eq_u32_e64 s[4:5], v187, v192
	v_cndmask_b32_e64 v142, 0, 1, vcc
	v_addc_co_u32_e64 v142, s[10:11], 0, v142, s[6:7]
	v_cndmask_b32_e64 v141, 0, 1, s[4:5]
	v_cmp_eq_u32_e64 s[10:11], v186, v192
	v_cmp_eq_u32_e64 s[8:9], v184, v192
	v_cmp_eq_u32_e64 s[12:13], v183, v192
	v_addc_co_u32_e64 v141, s[16:17], v142, v141, s[10:11]
	v_cndmask_b32_e64 v140, 0, 1, s[8:9]
	v_cmp_eq_u32_e64 s[16:17], v182, v192
	v_cndmask_b32_e64 v139, 0, 1, s[12:13]
	v_cmp_eq_u32_e64 s[14:15], v178, v192
	v_addc_co_u32_e64 v140, s[22:23], v141, v140, s[16:17]
	v_cmp_eq_u32_e64 s[22:23], v180, v192
	v_cndmask_b32_e64 v138, 0, 1, s[14:15]
	v_cmp_eq_u32_e64 s[18:19], v172, v192
	v_addc_co_u32_e64 v139, s[26:27], v140, v139, s[22:23]
	v_cmp_eq_u32_e64 s[26:27], v171, v192
	v_cmp_eq_u32_e64 s[20:21], v96, v192
	v_cndmask_b32_e64 v96, 0, 1, s[18:19]
	v_addc_co_u32_e64 v138, s[34:35], v139, v138, s[26:27]
	v_cmp_eq_u32_e64 s[34:35], v97, v192
	v_cmp_eq_u32_e64 s[24:25], v95, v192
	v_cndmask_b32_e64 v95, 0, 1, s[20:21]
	v_addc_co_u32_e64 v96, s[40:41], v138, v96, s[34:35]
	v_cmp_eq_u32_e64 s[40:41], v94, v192
	v_cmp_eq_u32_e64 s[28:29], v93, v192
	v_cndmask_b32_e64 v93, 0, 1, s[24:25]
	v_addc_co_u32_e64 v94, s[46:47], v96, v95, s[40:41]
	v_cmp_eq_u32_e64 s[46:47], v92, v192
	v_cmp_eq_u32_e64 s[30:31], v91, v192
	v_cndmask_b32_e64 v91, 0, 1, s[28:29]
	v_addc_co_u32_e64 v92, s[50:51], v94, v93, s[46:47]
	v_cmp_eq_u32_e64 s[50:51], v90, v192
	v_cmp_eq_u32_e64 s[36:37], v87, v192
	v_cndmask_b32_e64 v87, 0, 1, s[30:31]
	v_addc_co_u32_e64 v90, s[54:55], v92, v91, s[50:51]
	v_cmp_eq_u32_e64 s[54:55], v89, v192
	s_mov_b32 s82, s38
	v_cmp_eq_u32_e64 s[38:39], v86, v192
	v_addc_co_u32_e64 v87, s[56:57], v90, v87, s[54:55]
	v_cndmask_b32_e64 v86, 0, 1, s[36:37]
	v_cmp_eq_u32_e64 s[56:57], v83, v192
	v_cmp_eq_u32_e64 s[42:43], v85, v192
	v_cndmask_b32_e64 v85, 0, 1, s[38:39]
	v_addc_co_u32_e64 v83, s[58:59], v87, v86, s[56:57]
	v_cmp_eq_u32_e64 s[58:59], v82, v192
	v_cmp_eq_u32_e64 s[44:45], v84, v192
	v_cndmask_b32_e64 v84, 0, 1, s[42:43]
	v_addc_co_u32_e64 v82, s[60:61], v83, v85, s[58:59]
	v_cmp_eq_u32_e64 s[60:61], v81, v192
	v_cmp_eq_u32_e64 s[48:49], v79, v192
	v_cndmask_b32_e64 v79, 0, 1, s[44:45]
	v_addc_co_u32_e64 v81, s[62:63], v82, v84, s[60:61]
	v_cmp_eq_u32_e64 s[62:63], v80, v192
	v_cmp_eq_u32_e64 s[52:53], v78, v192
	v_cndmask_b32_e64 v78, 0, 1, s[48:49]
	v_addc_co_u32_e64 v79, s[64:65], v81, v79, s[62:63]
	v_cmp_eq_u32_e64 s[64:65], v77, v192
	v_cndmask_b32_e64 v69, 0, 1, s[52:53]
	s_nop 0
	v_addc_co_u32_e64 v77, s[66:67], v79, v78, s[64:65]
	v_cmp_eq_u32_e64 s[66:67], v76, v192
	s_nop 1
	v_addc_co_u32_e64 v69, s[68:69], v77, v69, s[66:67]
	ds_bpermute_b32 v76, v100, v69
	v_cmp_lt_i32_e64 s[68:69], 0, v68
	s_waitcnt lgkmcnt(0)
; __device__ __forceinline__ void select_query(const unsigned (&u)[64], unsigned vmax, int q, int b, int lane, unsigned* MASKb) {
;     ...
;                 for (int o = 1; o < 64; o <<= 1) { const int t = __shfl_up(incl, o); if (lane >= o) incl += t; }
;                 const int total = __builtin_amdgcn_readlane(incl, 63);
;                 const int quota = rrem - tbase - (incl - ec);
;                 int taken = 0;
; #pragma unroll
;                 for (int e = 0; e < 32; ++e) { const bool is = (u[B * 32 + e] == T) && (taken < quota); w |= is ? (1u << e) : 0u; taken += is ? 1 : 0; }
	s_nop 0
	v_cndmask_b32_e64 v76, 0, v76, s[68:69]
	v_add_u32_e32 v76, v76, v69
	ds_bpermute_b32 v77, v101, v76
	v_cmp_lt_i32_e64 s[68:69], 1, v68
	v_add_u32_e32 v69, v69, v191
	s_waitcnt lgkmcnt(0)
	v_cndmask_b32_e64 v77, 0, v77, s[68:69]
	v_add_u32_e32 v76, v77, v76
	ds_bpermute_b32 v77, v102, v76
	v_cmp_lt_i32_e64 s[68:69], 3, v68
	s_waitcnt lgkmcnt(0)
	s_nop 0
	v_cndmask_b32_e64 v77, 0, v77, s[68:69]
	v_add_u32_e32 v76, v77, v76
	ds_bpermute_b32 v77, v103, v76
	v_cmp_lt_i32_e64 s[68:69], 7, v68
	s_waitcnt lgkmcnt(0)
	s_nop 0
	v_cndmask_b32_e64 v77, 0, v77, s[68:69]
	v_add_u32_e32 v76, v77, v76
	ds_bpermute_b32 v77, v104, v76
	v_cmp_lt_i32_e64 s[68:69], 15, v68
	s_waitcnt lgkmcnt(0)
	s_nop 0
	v_cndmask_b32_e64 v77, 0, v77, s[68:69]
	v_add_u32_e32 v76, v77, v76
	ds_bpermute_b32 v77, v105, v76
	v_cmp_lt_i32_e64 s[68:69], 31, v68
	s_waitcnt lgkmcnt(0)
	s_nop 0
	v_cndmask_b32_e64 v77, 0, v77, s[68:69]
	v_add3_u32 v76, v185, v76, v77
	v_sub_u32_e32 v69, v69, v76
	v_cmp_lt_i32_e64 s[68:69], 0, v69
	s_and_b64 s[66:67], s[66:67], s[68:69]
	v_cndmask_b32_e64 v76, 0, 1, s[66:67]
	v_cmp_gt_i32_e64 s[66:67], v69, v76
	s_and_b64 s[52:53], s[52:53], s[66:67]
	v_cndmask_b32_e64 v77, 0, 2, s[52:53]
	v_cndmask_b32_e64 v78, 0, 1, s[52:53]
	v_addc_co_u32_e64 v79, s[52:53], 0, v76, s[52:53]
	v_cmp_lt_i32_e64 s[52:53], v79, v69
	s_and_b64 s[52:53], s[64:65], s[52:53]
	s_nop 0
	v_cndmask_b32_e64 v79, 0, 4, s[52:53]
	v_addc_co_u32_e64 v78, s[52:53], v78, v76, s[52:53]
	v_cmp_lt_i32_e64 s[52:53], v78, v69
	s_and_b64 s[48:49], s[48:49], s[52:53]
	v_cndmask_b32_e64 v80, 0, 8, s[48:49]
	v_cndmask_b32_e64 v81, 0, 1, s[48:49]
	v_addc_co_u32_e64 v82, s[48:49], 0, v78, s[48:49]
	v_cmp_lt_i32_e64 s[48:49], v82, v69
	s_and_b64 s[48:49], s[62:63], s[48:49]
	v_or3_b32 v77, v77, v79, v80
	v_cndmask_b32_e64 v83, 0, 16, s[48:49]
	v_cndmask_b32_e64 v84, 0, 1, s[48:49]
	v_addc_co_u32_e64 v78, s[48:49], v78, v81, s[48:49]
	v_cmp_lt_i32_e64 s[48:49], v78, v69
	s_and_b64 s[44:45], s[44:45], s[48:49]
	v_cndmask_b32_e64 v81, 0, 32, s[44:45]
	v_cndmask_b32_e64 v85, 0, 1, s[44:45]
	v_addc_co_u32_e64 v82, s[44:45], v82, v84, s[44:45]
	v_cmp_lt_i32_e64 s[44:45], v82, v69
	s_and_b64 s[44:45], s[60:61], s[44:45]
	v_or3_b32 v77, v77, v83, v81
	v_cndmask_b32_e64 v84, 0, 64, s[44:45]
	v_cndmask_b32_e64 v86, 0, 1, s[44:45]
	v_addc_co_u32_e64 v78, s[44:45], v78, v85, s[44:45]
	v_cmp_lt_i32_e64 s[44:45], v78, v69
	s_and_b64 s[42:43], s[42:43], s[44:45]
	v_mov_b32_e32 v85, 0x80
	v_cndmask_b32_e64 v85, 0, v85, s[42:43]
	v_cndmask_b32_e64 v87, 0, 1, s[42:43]
	v_addc_co_u32_e64 v82, s[42:43], v82, v86, s[42:43]
	v_cmp_lt_i32_e64 s[42:43], v82, v69
	s_and_b64 s[42:43], s[58:59], s[42:43]
	v_mov_b32_e32 v86, 0x100
	v_cndmask_b32_e64 v86, 0, v86, s[42:43]
	v_cndmask_b32_e64 v89, 0, 1, s[42:43]
	v_addc_co_u32_e64 v78, s[42:43], v78, v87, s[42:43]
	v_cmp_lt_i32_e64 s[42:43], v78, v69
	s_and_b64 s[38:39], s[38:39], s[42:43]
	v_mov_b32_e32 v87, 0x200
	v_cndmask_b32_e64 v87, 0, v87, s[38:39]
	v_cndmask_b32_e64 v90, 0, 1, s[38:39]
	v_addc_co_u32_e64 v82, s[38:39], v82, v89, s[38:39]
	v_cmp_lt_i32_e64 s[38:39], v82, v69
	s_and_b64 s[38:39], s[56:57], s[38:39]
	v_mov_b32_e32 v89, 0x400
	v_cndmask_b32_e64 v89, 0, v89, s[38:39]
	v_cndmask_b32_e64 v91, 0, 1, s[38:39]
	v_addc_co_u32_e64 v78, s[38:39], v78, v90, s[38:39]
	v_cmp_lt_i32_e64 s[38:39], v78, v69
	s_and_b64 s[36:37], s[36:37], s[38:39]
	v_mov_b32_e32 v90, 0x800
	v_cndmask_b32_e64 v90, 0, v90, s[36:37]
	v_cndmask_b32_e64 v92, 0, 1, s[36:37]
	v_addc_co_u32_e64 v82, s[36:37], v82, v91, s[36:37]
	v_cmp_lt_i32_e64 s[36:37], v82, v69
	s_and_b64 s[36:37], s[54:55], s[36:37]
	v_mov_b32_e32 v91, 0x1000
	v_cndmask_b32_e64 v91, 0, v91, s[36:37]
	v_cndmask_b32_e64 v93, 0, 1, s[36:37]
	v_addc_co_u32_e64 v78, s[36:37], v78, v92, s[36:37]
	v_cmp_lt_i32_e64 s[36:37], v78, v69
	s_and_b64 s[30:31], s[30:31], s[36:37]
	v_cndmask_b32_e64 v92, 0, v240, s[30:31]
	v_cndmask_b32_e64 v94, 0, 1, s[30:31]
	v_addc_co_u32_e64 v82, s[30:31], v82, v93, s[30:31]
	v_cmp_lt_i32_e64 s[30:31], v82, v69
	s_and_b64 s[30:31], s[50:51], s[30:31]
	v_mov_b32_e32 v93, 0x4000
	v_cndmask_b32_e64 v93, 0, v93, s[30:31]
	v_cndmask_b32_e64 v95, 0, 1, s[30:31]
	v_addc_co_u32_e64 v78, s[30:31], v78, v94, s[30:31]
	v_cmp_lt_i32_e64 s[30:31], v78, v69
; __device__ __forceinline__ void select_query(const unsigned (&u)[64], unsigned vmax, int q, int b, int lane, unsigned* MASKb) {
;     ...
; #pragma unroll
;                 for (int e = 0; e < 32; ++e) { const bool is = (u[B * 32 + e] == T) && (taken < quota); w |= is ? (1u << e) : 0u; taken += is ? 1 : 0; }
;                 tbase += total;
;             }
;             if (64 * B + lane <= (q >> 5)) __hip_atomic_store(MASKb + ((size_t)(b * 128 + (q >> 5)) * 128 + 64 * B + lane) * 32 + (q & 31), w, __ATOMIC_RELAXED, __HIP_MEMORY_SCOPE_AGENT);
	s_and_b64 s[28:29], s[28:29], s[30:31]
	v_mov_b32_e32 v94, 0x8000
	v_cndmask_b32_e64 v94, 0, v94, s[28:29]
	v_cndmask_b32_e64 v96, 0, 1, s[28:29]
	v_addc_co_u32_e64 v82, s[28:29], v82, v95, s[28:29]
	v_cmp_lt_i32_e64 s[28:29], v82, v69
	s_and_b64 s[28:29], s[46:47], s[28:29]
	v_mov_b32_e32 v95, 0x10000
	v_cndmask_b32_e64 v95, 0, v95, s[28:29]
	v_cndmask_b32_e64 v97, 0, 1, s[28:29]
	v_addc_co_u32_e64 v78, s[28:29], v78, v96, s[28:29]
	v_cmp_lt_i32_e64 s[28:29], v78, v69
	s_and_b64 s[24:25], s[24:25], s[28:29]
	v_mov_b32_e32 v96, 0x20000
	v_cndmask_b32_e64 v96, 0, v96, s[24:25]
	v_cndmask_b32_e64 v138, 0, 1, s[24:25]
	v_addc_co_u32_e64 v82, s[24:25], v82, v97, s[24:25]
	v_cmp_lt_i32_e64 s[24:25], v82, v69
	s_and_b64 s[24:25], s[40:41], s[24:25]
	v_mov_b32_e32 v97, 0x40000
	v_cndmask_b32_e64 v97, 0, v97, s[24:25]
	v_cndmask_b32_e64 v139, 0, 1, s[24:25]
	v_addc_co_u32_e64 v78, s[24:25], v78, v138, s[24:25]
	v_cmp_lt_i32_e64 s[24:25], v78, v69
	s_and_b64 s[20:21], s[20:21], s[24:25]
	v_mov_b32_e32 v138, 0x80000
	v_cndmask_b32_e64 v138, 0, v138, s[20:21]
	v_cndmask_b32_e64 v140, 0, 1, s[20:21]
	v_addc_co_u32_e64 v82, s[20:21], v82, v139, s[20:21]
	v_cmp_lt_i32_e64 s[20:21], v82, v69
	s_and_b64 s[20:21], s[34:35], s[20:21]
	v_mov_b32_e32 v139, 0x100000
	v_cndmask_b32_e64 v139, 0, v139, s[20:21]
	v_cndmask_b32_e64 v141, 0, 1, s[20:21]
	v_addc_co_u32_e64 v78, s[20:21], v78, v140, s[20:21]
	v_cmp_lt_i32_e64 s[20:21], v78, v69
	s_and_b64 s[18:19], s[18:19], s[20:21]
	v_mov_b32_e32 v140, 0x200000
	v_cndmask_b32_e64 v140, 0, v140, s[18:19]
	v_cndmask_b32_e64 v142, 0, 1, s[18:19]
	v_addc_co_u32_e64 v82, s[18:19], v82, v141, s[18:19]
	v_cmp_lt_i32_e64 s[18:19], v82, v69
	s_and_b64 s[18:19], s[26:27], s[18:19]
	v_mov_b32_e32 v141, 0x400000
	v_cndmask_b32_e64 v141, 0, v141, s[18:19]
	v_cndmask_b32_e64 v143, 0, 1, s[18:19]
	v_addc_co_u32_e64 v78, s[18:19], v78, v142, s[18:19]
	v_cmp_lt_i32_e64 s[18:19], v78, v69
	s_and_b64 s[14:15], s[14:15], s[18:19]
	v_mov_b32_e32 v142, 0x800000
	v_cndmask_b32_e64 v142, 0, v142, s[14:15]
	v_cndmask_b32_e64 v144, 0, 1, s[14:15]
	v_addc_co_u32_e64 v82, s[14:15], v82, v143, s[14:15]
	v_cmp_lt_i32_e64 s[14:15], v82, v69
	s_and_b64 s[14:15], s[22:23], s[14:15]
	v_mov_b32_e32 v143, 0x1000000
	v_cndmask_b32_e64 v143, 0, v143, s[14:15]
	v_cndmask_b32_e64 v145, 0, 1, s[14:15]
	v_addc_co_u32_e64 v78, s[14:15], v78, v144, s[14:15]
	v_cmp_lt_i32_e64 s[14:15], v78, v69
	s_and_b64 s[12:13], s[12:13], s[14:15]
	v_bfrev_b32_e32 v144, 64
	v_cndmask_b32_e64 v144, 0, v144, s[12:13]
	v_cndmask_b32_e64 v146, 0, 1, s[12:13]
	v_addc_co_u32_e64 v82, s[12:13], v82, v145, s[12:13]
	v_cmp_lt_i32_e64 s[12:13], v82, v69
	s_and_b64 s[12:13], s[16:17], s[12:13]
	v_bfrev_b32_e32 v145, 32
	v_cndmask_b32_e64 v145, 0, v145, s[12:13]
	v_cndmask_b32_e64 v147, 0, 1, s[12:13]
	v_addc_co_u32_e64 v78, s[12:13], v78, v146, s[12:13]
	v_cmp_lt_i32_e64 s[12:13], v78, v69
	s_and_b64 s[8:9], s[8:9], s[12:13]
	v_bfrev_b32_e32 v146, 16
	v_cndmask_b32_e64 v146, 0, v146, s[8:9]
	v_cndmask_b32_e64 v148, 0, 1, s[8:9]
	v_addc_co_u32_e64 v82, s[8:9], v82, v147, s[8:9]
	v_cmp_lt_i32_e64 s[8:9], v82, v69
	v_or3_b32 v77, v77, v84, v85
	s_and_b64 s[8:9], s[10:11], s[8:9]
	v_bfrev_b32_e32 v147, 8
	v_or3_b32 v77, v77, v86, v87
	v_cndmask_b32_e64 v147, 0, v147, s[8:9]
	v_cndmask_b32_e64 v149, 0, 1, s[8:9]
	v_addc_co_u32_e64 v78, s[8:9], v78, v148, s[8:9]
	v_or3_b32 v77, v77, v89, v90
	v_cmp_lt_i32_e64 s[8:9], v78, v69
	v_or3_b32 v77, v77, v91, v92
	s_and_b64 s[4:5], s[4:5], s[8:9]
	v_bfrev_b32_e32 v148, 4
	v_or3_b32 v77, v77, v93, v94
	v_cndmask_b32_e64 v148, 0, v148, s[4:5]
	v_cndmask_b32_e64 v150, 0, 1, s[4:5]
	v_addc_co_u32_e64 v82, s[4:5], v82, v149, s[4:5]
	v_or3_b32 v77, v77, v95, v96
	v_cmp_lt_i32_e64 s[4:5], v82, v69
	v_or3_b32 v77, v77, v97, v138
	s_and_b64 s[4:5], s[6:7], s[4:5]
	v_or3_b32 v77, v77, v139, v140
	v_cndmask_b32_e64 v82, 0, 2.0, s[4:5]
	v_addc_co_u32_e64 v78, s[4:5], v78, v150, s[4:5]
	v_or3_b32 v77, v77, v141, v142
	v_cmp_lt_i32_e64 s[4:5], v78, v69
	v_or3_b32 v77, v77, v143, v144
	s_and_b64 vcc, vcc, s[4:5]
	v_bfrev_b32_e32 v69, 1
	v_or3_b32 v77, v77, v145, v146
	v_cndmask_b32_e32 v69, 0, v69, vcc
	v_or3_b32 v77, v77, v147, v148
	v_or3_b32 v69, v77, v82, v69
	s_mov_b32 s38, s82
	v_or3_b32 v0, v69, v76, v0

; __device__ __forceinline__ int count_ge(const unsigned (&u)[64], unsigned cand, int nblk) {
;     int c0 = 0, c1 = 0;
;     const unsigned ts = __builtin_amdgcn_readfirstlane(cand);
; #pragma unroll
;     for (int B = 0; B < 2; ++B) {
;         if (B < nblk) {
; #pragma unroll
;             for (int i = 0; i < 32; i += 4) CNT4(c0, c1, ts, u[B * 32 + i], u[B * 32 + i + 1], u[B * 32 + i + 2], u[B * 32 + i + 3]);
;         }
;     }
;     return wave_isum(c0 + c1);
; }
; __device__ __forceinline__ float keyval(unsigned k) { return __uint_as_float((k & 0x80000000u) ? (k ^ 0x80000000u) : ~k); }
; __device__ __forceinline__ unsigned valkey(float f) { const unsigned b = __float_as_uint(f); return b ^ ((unsigned)((int)b >> 31) | 0x80000000u); }
; __device__ __forceinline__ void select_query(const unsigned (&u)[64], unsigned vmax, int q, int b, int lane, unsigned* MASKb) {
;     const int n = q + 1, nblk = (n + 2047) >> 11;
;     unsigned T = 0u, TG = 0u; int rrem = 0;
;     if (n > 256) {
;         const unsigned kmax = wave_umax(vmax);
;         const unsigned K0 = 0x80000000u;
;         bool exact = false, done = false;
;         unsigned lo = 0u, hi = 0u; float Llo = 1.f, Lhi = 1.f;
;         const float L256 = 8.0028150156f;
;         const int cpos = count_ge(u, K0 + 1u, nblk);
.LBB0_184:
	s_or_b64 exec, exec, s[70:71]
	v_add_u32_e32 v0, 0x801, v106
	s_movk_i32 s4, 0xfe
	v_ashrrev_i32_e32 v0, 11, v0
	v_cmp_lt_i32_e32 vcc, s4, v106
	v_mov_b32_e32 v76, 0
	v_mov_b32_e32 v77, 0
	v_mov_b32_e32 v69, 0
	s_and_saveexec_b64 s[8:9], vcc
	s_cbranch_execz .LBB0_227
	v_max_u32_dpp v76, v177, v177 row_shr:1 row_mask:0xf bank_mask:0xf bound_ctrl:1
	v_mov_b32_e32 v69, 0
	v_cmp_lt_i32_e64 s[4:5], 0, v0
	v_max_u32_dpp v76, v76, v76 row_shr:2 row_mask:0xf bank_mask:0xf bound_ctrl:1
	s_nop 1
	v_max_u32_dpp v76, v76, v76 row_shr:4 row_mask:0xf bank_mask:0xf bound_ctrl:1
	s_nop 1
	v_max_u32_dpp v76, v76, v76 row_shr:8 row_mask:0xf bank_mask:0xf bound_ctrl:1
	s_nop 1
	v_max_u32_dpp v76, v76, v76 row_bcast:15 row_mask:0xa bank_mask:0xf
	s_nop 1
	v_max_u32_dpp v76, v76, v76 row_bcast:31 row_mask:0xc bank_mask:0xf
	s_nop 0
	v_readlane_b32 s18, v76, 63
	v_mov_b32_e32 v76, 0
	s_and_saveexec_b64 s[6:7], s[4:5]
	s_cbranch_execz .LBB0_187
	v_readlane_b32 s10, v255, 13
	v_mov_b32_e32 v76, v1
	v_mov_b32_e32 v69, v1
	v_readlane_b32 s11, v255, 14
	s_mov_b32 s19, s11
	v_cmp_le_u32_e64 s[10:11], s19, v98
	v_cmp_le_u32_e64 s[12:13], s19, v107
	v_cmp_le_u32_e64 s[14:15], s19, v99
	v_cmp_le_u32_e64 s[16:17], s19, v108
	v_addc_co_u32_e64 v76, s[20:21], 0, v76, s[10:11]
	v_addc_co_u32_e64 v69, s[22:23], 0, v69, s[12:13]
	v_addc_co_u32_e64 v76, s[20:21], 0, v76, s[14:15]
	v_addc_co_u32_e64 v69, s[22:23], 0, v69, s[16:17]
	v_cmp_le_u32_e64 s[10:11], s19, v109
	v_cmp_le_u32_e64 s[12:13], s19, v113
	v_cmp_le_u32_e64 s[14:15], s19, v110
	v_cmp_le_u32_e64 s[16:17], s19, v114
	v_addc_co_u32_e64 v76, s[20:21], 0, v76, s[10:11]
	v_addc_co_u32_e64 v69, s[22:23], 0, v69, s[12:13]
	v_addc_co_u32_e64 v76, s[20:21], 0, v76, s[14:15]
	v_addc_co_u32_e64 v69, s[22:23], 0, v69, s[16:17]
	v_cmp_le_u32_e64 s[10:11], s19, v111
	v_cmp_le_u32_e64 s[12:13], s19, v115
	v_cmp_le_u32_e64 s[14:15], s19, v112
	v_cmp_le_u32_e64 s[16:17], s19, v116
	v_addc_co_u32_e64 v76, s[20:21], 0, v76, s[10:11]
	v_addc_co_u32_e64 v69, s[22:23], 0, v69, s[12:13]
	v_addc_co_u32_e64 v76, s[20:21], 0, v76, s[14:15]
	v_addc_co_u32_e64 v69, s[22:23], 0, v69, s[16:17]
	v_cmp_le_u32_e64 s[10:11], s19, v117
	v_cmp_le_u32_e64 s[12:13], s19, v119
	v_cmp_le_u32_e64 s[14:15], s19, v118
	v_cmp_le_u32_e64 s[16:17], s19, v121
	v_addc_co_u32_e64 v76, s[20:21], 0, v76, s[10:11]
	v_addc_co_u32_e64 v69, s[22:23], 0, v69, s[12:13]
	v_addc_co_u32_e64 v76, s[20:21], 0, v76, s[14:15]
	v_addc_co_u32_e64 v69, s[22:23], 0, v69, s[16:17]
	v_cmp_le_u32_e64 s[10:11], s19, v120
	v_cmp_le_u32_e64 s[12:13], s19, v123
	v_cmp_le_u32_e64 s[14:15], s19, v122
	v_cmp_le_u32_e64 s[16:17], s19, v124
	v_addc_co_u32_e64 v76, s[20:21], 0, v76, s[10:11]
	v_addc_co_u32_e64 v69, s[22:23], 0, v69, s[12:13]
	v_addc_co_u32_e64 v76, s[20:21], 0, v76, s[14:15]
	v_addc_co_u32_e64 v69, s[22:23], 0, v69, s[16:17]
	v_cmp_le_u32_e64 s[10:11], s19, v125
	v_cmp_le_u32_e64 s[12:13], s19, v127
	v_cmp_le_u32_e64 s[14:15], s19, v126
	v_cmp_le_u32_e64 s[16:17], s19, v128
	v_addc_co_u32_e64 v76, s[20:21], 0, v76, s[10:11]
	v_addc_co_u32_e64 v69, s[22:23], 0, v69, s[12:13]
	v_addc_co_u32_e64 v76, s[20:21], 0, v76, s[14:15]
	v_addc_co_u32_e64 v69, s[22:23], 0, v69, s[16:17]
	v_cmp_le_u32_e64 s[10:11], s19, v129
	v_cmp_le_u32_e64 s[12:13], s19, v131
	v_cmp_le_u32_e64 s[14:15], s19, v130
	v_cmp_le_u32_e64 s[16:17], s19, v132
	v_addc_co_u32_e64 v76, s[20:21], 0, v76, s[10:11]
	v_addc_co_u32_e64 v69, s[22:23], 0, v69, s[12:13]
	v_addc_co_u32_e64 v76, s[20:21], 0, v76, s[14:15]
	v_addc_co_u32_e64 v69, s[22:23], 0, v69, s[16:17]
	v_cmp_le_u32_e64 s[10:11], s19, v133
	v_cmp_le_u32_e64 s[12:13], s19, v134
	v_cmp_le_u32_e64 s[14:15], s19, v136
	v_cmp_le_u32_e64 s[16:17], s19, v137
	v_addc_co_u32_e64 v76, s[20:21], 0, v76, s[10:11]
	v_addc_co_u32_e64 v69, s[22:23], 0, v69, s[12:13]
	v_addc_co_u32_e64 v76, s[20:21], 0, v76, s[14:15]
	v_addc_co_u32_e64 v69, s[22:23], 0, v69, s[16:17]
.LBB0_187:
	s_or_b64 exec, exec, s[6:7]
	v_cmp_lt_i32_e64 s[6:7], 1, v0
	s_and_saveexec_b64 s[10:11], s[6:7]
	s_cbranch_execz .LBB0_189
	v_readlane_b32 s12, v255, 13
	v_readlane_b32 s13, v255, 14
	s_mov_b32 s19, s13
	v_cmp_le_u32_e64 s[12:13], s19, v46
	v_cmp_le_u32_e64 s[14:15], s19, v48
	v_cmp_le_u32_e64 s[16:17], s19, v47
	v_cmp_le_u32_e64 s[20:21], s19, v49
	v_addc_co_u32_e64 v76, s[22:23], 0, v76, s[12:13]
	v_addc_co_u32_e64 v69, s[24:25], 0, v69, s[14:15]
	v_addc_co_u32_e64 v76, s[22:23], 0, v76, s[16:17]
	v_addc_co_u32_e64 v69, s[24:25], 0, v69, s[20:21]
	v_cmp_le_u32_e64 s[12:13], s19, v42
	v_cmp_le_u32_e64 s[14:15], s19, v50
	v_cmp_le_u32_e64 s[16:17], s19, v43
	v_cmp_le_u32_e64 s[20:21], s19, v44
	v_addc_co_u32_e64 v76, s[22:23], 0, v76, s[12:13]
	v_addc_co_u32_e64 v69, s[24:25], 0, v69, s[14:15]
	v_addc_co_u32_e64 v76, s[22:23], 0, v76, s[16:17]
	v_addc_co_u32_e64 v69, s[24:25], 0, v69, s[20:21]
	v_cmp_le_u32_e64 s[12:13], s19, v38
	v_cmp_le_u32_e64 s[14:15], s19, v45
	v_cmp_le_u32_e64 s[16:17], s19, v39
	v_cmp_le_u32_e64 s[20:21], s19, v40
	v_addc_co_u32_e64 v76, s[22:23], 0, v76, s[12:13]
	v_addc_co_u32_e64 v69, s[24:25], 0, v69, s[14:15]
	v_addc_co_u32_e64 v76, s[22:23], 0, v76, s[16:17]
	v_addc_co_u32_e64 v69, s[24:25], 0, v69, s[20:21]
	v_cmp_le_u32_e64 s[12:13], s19, v41
	v_cmp_le_u32_e64 s[14:15], s19, v52
	v_cmp_le_u32_e64 s[16:17], s19, v51
	v_cmp_le_u32_e64 s[20:21], s19, v54
	v_addc_co_u32_e64 v76, s[22:23], 0, v76, s[12:13]
	v_addc_co_u32_e64 v69, s[24:25], 0, v69, s[14:15]
	v_addc_co_u32_e64 v76, s[22:23], 0, v76, s[16:17]
	v_addc_co_u32_e64 v69, s[24:25], 0, v69, s[20:21]
	v_cmp_le_u32_e64 s[12:13], s19, v53
	v_cmp_le_u32_e64 s[14:15], s19, v56
	v_cmp_le_u32_e64 s[16:17], s19, v55
	v_cmp_le_u32_e64 s[20:21], s19, v57
	v_addc_co_u32_e64 v76, s[22:23], 0, v76, s[12:13]
	v_addc_co_u32_e64 v69, s[24:25], 0, v69, s[14:15]
	v_addc_co_u32_e64 v76, s[22:23], 0, v76, s[16:17]
	v_addc_co_u32_e64 v69, s[24:25], 0, v69, s[20:21]
	v_cmp_le_u32_e64 s[12:13], s19, v58
	v_cmp_le_u32_e64 s[14:15], s19, v60
	v_cmp_le_u32_e64 s[16:17], s19, v59
	v_cmp_le_u32_e64 s[20:21], s19, v61
	v_addc_co_u32_e64 v76, s[22:23], 0, v76, s[12:13]
	v_addc_co_u32_e64 v69, s[24:25], 0, v69, s[14:15]
	v_addc_co_u32_e64 v76, s[22:23], 0, v76, s[16:17]
	v_addc_co_u32_e64 v69, s[24:25], 0, v69, s[20:21]
	v_cmp_le_u32_e64 s[12:13], s19, v62
	v_cmp_le_u32_e64 s[14:15], s19, v64
	v_cmp_le_u32_e64 s[16:17], s19, v63
	v_cmp_le_u32_e64 s[20:21], s19, v65
	v_addc_co_u32_e64 v76, s[22:23], 0, v76, s[12:13]
	v_addc_co_u32_e64 v69, s[24:25], 0, v69, s[14:15]
	v_addc_co_u32_e64 v76, s[22:23], 0, v76, s[16:17]
	v_addc_co_u32_e64 v69, s[24:25], 0, v69, s[20:21]
	v_cmp_le_u32_e64 s[12:13], s19, v72
	v_cmp_le_u32_e64 s[14:15], s19, v73
	v_cmp_le_u32_e64 s[16:17], s19, v74
	v_cmp_le_u32_e64 s[20:21], s19, v75
	v_addc_co_u32_e64 v76, s[22:23], 0, v76, s[12:13]
	v_addc_co_u32_e64 v69, s[24:25], 0, v69, s[14:15]
	v_addc_co_u32_e64 v76, s[22:23], 0, v76, s[16:17]
	v_addc_co_u32_e64 v69, s[24:25], 0, v69, s[20:21]
; __device__ __forceinline__ int count_ge(const unsigned (&u)[64], unsigned cand, int nblk) {
;     ...
;     return wave_isum(c0 + c1);
; }
; __device__ __forceinline__ float keyval(unsigned k) { return __uint_as_float((k & 0x80000000u) ? (k ^ 0x80000000u) : ~k); }
; __device__ __forceinline__ unsigned valkey(float f) { const unsigned b = __float_as_uint(f); return b ^ ((unsigned)((int)b >> 31) | 0x80000000u); }
; __device__ __forceinline__ void select_query(const unsigned (&u)[64], unsigned vmax, int q, int b, int lane, unsigned* MASKb) {
;     const int n = q + 1, nblk = (n + 2047) >> 11;
;     unsigned T = 0u, TG = 0u; int rrem = 0;
;     if (n > 256) {
;         const unsigned kmax = wave_umax(vmax);
;         const unsigned K0 = 0x80000000u;
;         bool exact = false, done = false;
;         unsigned lo = 0u, hi = 0u; float Llo = 1.f, Lhi = 1.f;
;         const float L256 = 8.0028150156f;
;         const int cpos = count_ge(u, K0 + 1u, nblk);
;         if (cpos == 256) { T = K0 + 1u; exact = true; done = true; }
;         else if (cpos > 256) { lo = K0 + 1u; Llo = __log2f((float)cpos) - L256; hi = kmax + 1u; Lhi = L256 + 1.f; }
;         else {
;             const int c0 = count_ge(u, K0, nblk);
;             if (c0 >= 256) { T = K0; exact = (c0 == 256); done = true; }
.LBB0_189:
	s_or_b64 exec, exec, s[10:11]
	v_add_u32_e32 v69, v76, v69
	s_nop 1
	v_add_u32_dpp v69, v69, v69 row_shr:1 row_mask:0xf bank_mask:0xf bound_ctrl:1
	s_nop 1
	v_add_u32_dpp v69, v69, v69 row_shr:2 row_mask:0xf bank_mask:0xf bound_ctrl:1
	s_nop 1
	v_add_u32_dpp v69, v69, v69 row_shr:4 row_mask:0xf bank_mask:0xf bound_ctrl:1
	s_nop 1
	v_add_u32_dpp v69, v69, v69 row_shr:8 row_mask:0xf bank_mask:0xf bound_ctrl:1
	s_nop 1
	v_add_u32_dpp v69, v69, v69 row_bcast:15 row_mask:0xa bank_mask:0xf
	s_nop 1
	v_add_u32_dpp v69, v69, v69 row_bcast:31 row_mask:0xc bank_mask:0xf
	s_nop 0
	v_readlane_b32 s19, v69, 63
	s_cmpk_eq_i32 s19, 0x100
	s_cbranch_scc1 .LBB0_200
	s_cmpk_lt_i32 s19, 0x101
	s_mov_b64 s[14:15], -1
	s_cbranch_scc0 .LBB0_201
	v_mov_b32_e32 v69, 0
	v_mov_b32_e32 v76, 0
	s_and_saveexec_b64 s[10:11], s[4:5]
	s_cbranch_execz .LBB0_193
	v_mov_b32_e32 v76, v1
	v_mov_b32_e32 v69, v1
	v_cmp_le_u32_e64 s[12:13], s38, v98
	v_cmp_le_u32_e64 s[14:15], s38, v107
	v_cmp_le_u32_e64 s[16:17], s38, v99
	v_cmp_le_u32_e64 s[20:21], s38, v108
	v_addc_co_u32_e64 v76, s[22:23], 0, v76, s[12:13]
	v_addc_co_u32_e64 v69, s[24:25], 0, v69, s[14:15]
	v_addc_co_u32_e64 v76, s[22:23], 0, v76, s[16:17]
	v_addc_co_u32_e64 v69, s[24:25], 0, v69, s[20:21]
	v_cmp_le_u32_e64 s[12:13], s38, v109
	v_cmp_le_u32_e64 s[14:15], s38, v113
	v_cmp_le_u32_e64 s[16:17], s38, v110
	v_cmp_le_u32_e64 s[20:21], s38, v114
	v_addc_co_u32_e64 v76, s[22:23], 0, v76, s[12:13]
	v_addc_co_u32_e64 v69, s[24:25], 0, v69, s[14:15]
	v_addc_co_u32_e64 v76, s[22:23], 0, v76, s[16:17]
	v_addc_co_u32_e64 v69, s[24:25], 0, v69, s[20:21]
	v_cmp_le_u32_e64 s[12:13], s38, v111
	v_cmp_le_u32_e64 s[14:15], s38, v115
	v_cmp_le_u32_e64 s[16:17], s38, v112
	v_cmp_le_u32_e64 s[20:21], s38, v116
	v_addc_co_u32_e64 v76, s[22:23], 0, v76, s[12:13]
	v_addc_co_u32_e64 v69, s[24:25], 0, v69, s[14:15]
	v_addc_co_u32_e64 v76, s[22:23], 0, v76, s[16:17]
	v_addc_co_u32_e64 v69, s[24:25], 0, v69, s[20:21]
	v_cmp_le_u32_e64 s[12:13], s38, v117
	v_cmp_le_u32_e64 s[14:15], s38, v119
	v_cmp_le_u32_e64 s[16:17], s38, v118
	v_cmp_le_u32_e64 s[20:21], s38, v121
	v_addc_co_u32_e64 v76, s[22:23], 0, v76, s[12:13]
	v_addc_co_u32_e64 v69, s[24:25], 0, v69, s[14:15]
	v_addc_co_u32_e64 v76, s[22:23], 0, v76, s[16:17]
	v_addc_co_u32_e64 v69, s[24:25], 0, v69, s[20:21]
	v_cmp_le_u32_e64 s[12:13], s38, v120
	v_cmp_le_u32_e64 s[14:15], s38, v123
	v_cmp_le_u32_e64 s[16:17], s38, v122
	v_cmp_le_u32_e64 s[20:21], s38, v124
	v_addc_co_u32_e64 v76, s[22:23], 0, v76, s[12:13]
	v_addc_co_u32_e64 v69, s[24:25], 0, v69, s[14:15]
	v_addc_co_u32_e64 v76, s[22:23], 0, v76, s[16:17]
	v_addc_co_u32_e64 v69, s[24:25], 0, v69, s[20:21]
	v_cmp_le_u32_e64 s[12:13], s38, v125
	v_cmp_le_u32_e64 s[14:15], s38, v127
	v_cmp_le_u32_e64 s[16:17], s38, v126
	v_cmp_le_u32_e64 s[20:21], s38, v128
	v_addc_co_u32_e64 v76, s[22:23], 0, v76, s[12:13]
	v_addc_co_u32_e64 v69, s[24:25], 0, v69, s[14:15]
	v_addc_co_u32_e64 v76, s[22:23], 0, v76, s[16:17]
	v_addc_co_u32_e64 v69, s[24:25], 0, v69, s[20:21]
	v_cmp_le_u32_e64 s[12:13], s38, v129
	v_cmp_le_u32_e64 s[14:15], s38, v131
	v_cmp_le_u32_e64 s[16:17], s38, v130
	v_cmp_le_u32_e64 s[20:21], s38, v132
	v_addc_co_u32_e64 v76, s[22:23], 0, v76, s[12:13]
	v_addc_co_u32_e64 v69, s[24:25], 0, v69, s[14:15]
	v_addc_co_u32_e64 v76, s[22:23], 0, v76, s[16:17]
	v_addc_co_u32_e64 v69, s[24:25], 0, v69, s[20:21]
	v_cmp_le_u32_e64 s[12:13], s38, v133
	v_cmp_le_u32_e64 s[14:15], s38, v134
	v_cmp_le_u32_e64 s[16:17], s38, v136
	v_cmp_le_u32_e64 s[20:21], s38, v137
	v_addc_co_u32_e64 v76, s[22:23], 0, v76, s[12:13]
	v_addc_co_u32_e64 v69, s[24:25], 0, v69, s[14:15]
	v_addc_co_u32_e64 v76, s[22:23], 0, v76, s[16:17]
	v_addc_co_u32_e64 v69, s[24:25], 0, v69, s[20:21]
.LBB0_193:
	s_or_b64 exec, exec, s[10:11]
	s_and_saveexec_b64 s[10:11], s[6:7]
	s_cbranch_execz .LBB0_195
	v_cmp_le_u32_e64 s[12:13], s38, v46
	v_cmp_le_u32_e64 s[14:15], s38, v48
	v_cmp_le_u32_e64 s[16:17], s38, v47
	v_cmp_le_u32_e64 s[20:21], s38, v49
	v_addc_co_u32_e64 v76, s[22:23], 0, v76, s[12:13]
	v_addc_co_u32_e64 v69, s[24:25], 0, v69, s[14:15]
	v_addc_co_u32_e64 v76, s[22:23], 0, v76, s[16:17]
	v_addc_co_u32_e64 v69, s[24:25], 0, v69, s[20:21]
	v_cmp_le_u32_e64 s[12:13], s38, v42
	v_cmp_le_u32_e64 s[14:15], s38, v50
	v_cmp_le_u32_e64 s[16:17], s38, v43
	v_cmp_le_u32_e64 s[20:21], s38, v44
	v_addc_co_u32_e64 v76, s[22:23], 0, v76, s[12:13]
	v_addc_co_u32_e64 v69, s[24:25], 0, v69, s[14:15]
	v_addc_co_u32_e64 v76, s[22:23], 0, v76, s[16:17]
	v_addc_co_u32_e64 v69, s[24:25], 0, v69, s[20:21]
	v_cmp_le_u32_e64 s[12:13], s38, v38
	v_cmp_le_u32_e64 s[14:15], s38, v45
	v_cmp_le_u32_e64 s[16:17], s38, v39
	v_cmp_le_u32_e64 s[20:21], s38, v40
	v_addc_co_u32_e64 v76, s[22:23], 0, v76, s[12:13]
	v_addc_co_u32_e64 v69, s[24:25], 0, v69, s[14:15]
	v_addc_co_u32_e64 v76, s[22:23], 0, v76, s[16:17]
	v_addc_co_u32_e64 v69, s[24:25], 0, v69, s[20:21]
	v_cmp_le_u32_e64 s[12:13], s38, v41
	v_cmp_le_u32_e64 s[14:15], s38, v52
	v_cmp_le_u32_e64 s[16:17], s38, v51
	v_cmp_le_u32_e64 s[20:21], s38, v54
	v_addc_co_u32_e64 v76, s[22:23], 0, v76, s[12:13]
	v_addc_co_u32_e64 v69, s[24:25], 0, v69, s[14:15]
	v_addc_co_u32_e64 v76, s[22:23], 0, v76, s[16:17]
	v_addc_co_u32_e64 v69, s[24:25], 0, v69, s[20:21]
	v_cmp_le_u32_e64 s[12:13], s38, v53
	v_cmp_le_u32_e64 s[14:15], s38, v56
	v_cmp_le_u32_e64 s[16:17], s38, v55
	v_cmp_le_u32_e64 s[20:21], s38, v57
	v_addc_co_u32_e64 v76, s[22:23], 0, v76, s[12:13]
	v_addc_co_u32_e64 v69, s[24:25], 0, v69, s[14:15]
	v_addc_co_u32_e64 v76, s[22:23], 0, v76, s[16:17]
	v_addc_co_u32_e64 v69, s[24:25], 0, v69, s[20:21]
	v_cmp_le_u32_e64 s[12:13], s38, v58
	v_cmp_le_u32_e64 s[14:15], s38, v60
	v_cmp_le_u32_e64 s[16:17], s38, v59
	v_cmp_le_u32_e64 s[20:21], s38, v61
	v_addc_co_u32_e64 v76, s[22:23], 0, v76, s[12:13]
	v_addc_co_u32_e64 v69, s[24:25], 0, v69, s[14:15]
	v_addc_co_u32_e64 v76, s[22:23], 0, v76, s[16:17]
	v_addc_co_u32_e64 v69, s[24:25], 0, v69, s[20:21]
	v_cmp_le_u32_e64 s[12:13], s38, v62
	v_cmp_le_u32_e64 s[14:15], s38, v64
	v_cmp_le_u32_e64 s[16:17], s38, v63
	v_cmp_le_u32_e64 s[20:21], s38, v65
	v_addc_co_u32_e64 v76, s[22:23], 0, v76, s[12:13]
	v_addc_co_u32_e64 v69, s[24:25], 0, v69, s[14:15]
	v_addc_co_u32_e64 v76, s[22:23], 0, v76, s[16:17]
	v_addc_co_u32_e64 v69, s[24:25], 0, v69, s[20:21]
	v_cmp_le_u32_e64 s[12:13], s38, v72
	v_cmp_le_u32_e64 s[14:15], s38, v73
	v_cmp_le_u32_e64 s[16:17], s38, v74
	v_cmp_le_u32_e64 s[20:21], s38, v75
	v_addc_co_u32_e64 v76, s[22:23], 0, v76, s[12:13]
	v_addc_co_u32_e64 v69, s[24:25], 0, v69, s[14:15]
	v_addc_co_u32_e64 v76, s[22:23], 0, v76, s[16:17]
	v_addc_co_u32_e64 v69, s[24:25], 0, v69, s[20:21]

; __device__ __forceinline__ float keyval(unsigned k) { return __uint_as_float((k & 0x80000000u) ? (k ^ 0x80000000u) : ~k); }
; __device__ __forceinline__ unsigned valkey(float f) { const unsigned b = __float_as_uint(f); return b ^ ((unsigned)((int)b >> 31) | 0x80000000u); }
; __device__ __forceinline__ void select_query(const unsigned (&u)[64], unsigned vmax, int q, int b, int lane, unsigned* MASKb) {
;     ...
;         while (!done) {
;             if (hi - lo <= 1u) { T = lo; exact = false; break; }
;             const float vlo = keyval(lo), vhi = keyval(hi);
;             const float frac = (it >= 9 && (it & 1)) ? 0.5f : Llo * __builtin_amdgcn_rcpf(Llo + Lhi);
;             unsigned mid = valkey(vlo + frac * (vhi - vlo));
;             if (mid <= lo) mid = lo + 1u;
;             if (mid >= hi) mid = hi - 1u;
;             mid = __builtin_amdgcn_readfirstlane(mid);
;             const int c = count_ge(u, mid, nblk);
.LBB0_206:
	s_sub_i32 s14, s12, s13
	s_cmp_lt_u32 s14, 2
	s_cbranch_scc1 .LBB0_204
	s_cmp_gt_i32 s13, -1
	s_cselect_b32 s15, -1, 0x80000000
	s_cmp_gt_i32 s12, -1
	s_cselect_b32 s14, -1, 0x80000000
	v_add_f32_e32 v77, v76, v69
	s_xor_b64 s[14:15], s[14:15], s[12:13]
	v_rcp_f32_e32 v77, v77
	s_cmp_lt_i32 s21, 9
	s_cselect_b64 s[16:17], -1, 0
	s_bitcmp0_b32 s21, 0
	s_cselect_b64 s[18:19], -1, 0
	v_mul_f32_e32 v77, v69, v77
	s_or_b64 vcc, s[16:17], s[18:19]
	v_mov_b32_e32 v78, s15
	v_cndmask_b32_e32 v77, 0.5, v77, vcc
	v_sub_f32_e32 v78, s14, v78
	v_fma_f32 v77, v77, v78, s15
	v_ashrrev_i32_e32 v78, 31, v77
	v_bitop3_b32 v77, v78, v77, s38 bitop3:0x36
	s_add_i32 s14, s13, 1
	v_mov_b32_e32 v78, s14
	v_cmp_lt_u32_e32 vcc, s13, v77
	s_add_i32 s14, s12, -1
	s_nop 0
	v_cndmask_b32_e32 v77, v78, v77, vcc
	v_mov_b32_e32 v78, s14
	v_cmp_gt_u32_e32 vcc, s12, v77
	s_nop 1
	v_cndmask_b32_e32 v77, v78, v77, vcc
	v_mov_b32_e32 v78, 0
	v_readfirstlane_b32 s14, v77
	v_mov_b32_e32 v77, 0
	s_and_saveexec_b64 s[16:17], s[4:5]
	s_cbranch_execz .LBB0_209
	v_mov_b32_e32 v78, 0
	v_mov_b32_e32 v77, 0
	v_cmp_le_u32_e64 s[18:19], s14, v98
	v_cmp_le_u32_e64 s[24:25], s14, v107
	v_cmp_le_u32_e64 s[26:27], s14, v99
	v_cmp_le_u32_e64 s[28:29], s14, v108
	v_addc_co_u32_e64 v78, s[30:31], 0, v78, s[18:19]
	v_addc_co_u32_e64 v77, s[34:35], 0, v77, s[24:25]
	v_addc_co_u32_e64 v78, s[30:31], 0, v78, s[26:27]
	v_addc_co_u32_e64 v77, s[34:35], 0, v77, s[28:29]
	v_cmp_le_u32_e64 s[18:19], s14, v109
	v_cmp_le_u32_e64 s[24:25], s14, v113
	v_cmp_le_u32_e64 s[26:27], s14, v110
	v_cmp_le_u32_e64 s[28:29], s14, v114
	v_addc_co_u32_e64 v78, s[30:31], 0, v78, s[18:19]
	v_addc_co_u32_e64 v77, s[34:35], 0, v77, s[24:25]
	v_addc_co_u32_e64 v78, s[30:31], 0, v78, s[26:27]
	v_addc_co_u32_e64 v77, s[34:35], 0, v77, s[28:29]
	v_cmp_le_u32_e64 s[18:19], s14, v111
	v_cmp_le_u32_e64 s[24:25], s14, v115
	v_cmp_le_u32_e64 s[26:27], s14, v112
	v_cmp_le_u32_e64 s[28:29], s14, v116
	v_addc_co_u32_e64 v78, s[30:31], 0, v78, s[18:19]
	v_addc_co_u32_e64 v77, s[34:35], 0, v77, s[24:25]
	v_addc_co_u32_e64 v78, s[30:31], 0, v78, s[26:27]
	v_addc_co_u32_e64 v77, s[34:35], 0, v77, s[28:29]
	v_cmp_le_u32_e64 s[18:19], s14, v117
	v_cmp_le_u32_e64 s[24:25], s14, v119
	v_cmp_le_u32_e64 s[26:27], s14, v118
	v_cmp_le_u32_e64 s[28:29], s14, v121
	v_addc_co_u32_e64 v78, s[30:31], 0, v78, s[18:19]
	v_addc_co_u32_e64 v77, s[34:35], 0, v77, s[24:25]
	v_addc_co_u32_e64 v78, s[30:31], 0, v78, s[26:27]
	v_addc_co_u32_e64 v77, s[34:35], 0, v77, s[28:29]
	v_cmp_le_u32_e64 s[18:19], s14, v120
	v_cmp_le_u32_e64 s[24:25], s14, v123
	v_cmp_le_u32_e64 s[26:27], s14, v122
	v_cmp_le_u32_e64 s[28:29], s14, v124
	v_addc_co_u32_e64 v78, s[30:31], 0, v78, s[18:19]
	v_addc_co_u32_e64 v77, s[34:35], 0, v77, s[24:25]
	v_addc_co_u32_e64 v78, s[30:31], 0, v78, s[26:27]
	v_addc_co_u32_e64 v77, s[34:35], 0, v77, s[28:29]
	v_cmp_le_u32_e64 s[18:19], s14, v125
	v_cmp_le_u32_e64 s[24:25], s14, v127
	v_cmp_le_u32_e64 s[26:27], s14, v126
	v_cmp_le_u32_e64 s[28:29], s14, v128
	v_addc_co_u32_e64 v78, s[30:31], 0, v78, s[18:19]
	v_addc_co_u32_e64 v77, s[34:35], 0, v77, s[24:25]
	v_addc_co_u32_e64 v78, s[30:31], 0, v78, s[26:27]
	v_addc_co_u32_e64 v77, s[34:35], 0, v77, s[28:29]
	v_cmp_le_u32_e64 s[18:19], s14, v129
	v_cmp_le_u32_e64 s[24:25], s14, v131
	v_cmp_le_u32_e64 s[26:27], s14, v130
	v_cmp_le_u32_e64 s[28:29], s14, v132
	v_addc_co_u32_e64 v78, s[30:31], 0, v78, s[18:19]
	v_addc_co_u32_e64 v77, s[34:35], 0, v77, s[24:25]
	v_addc_co_u32_e64 v78, s[30:31], 0, v78, s[26:27]
	v_addc_co_u32_e64 v77, s[34:35], 0, v77, s[28:29]
	v_cmp_le_u32_e64 s[18:19], s14, v133
	v_cmp_le_u32_e64 s[24:25], s14, v134
	v_cmp_le_u32_e64 s[26:27], s14, v136
	v_cmp_le_u32_e64 s[28:29], s14, v137
	v_addc_co_u32_e64 v78, s[30:31], 0, v78, s[18:19]
	v_addc_co_u32_e64 v77, s[34:35], 0, v77, s[24:25]
	v_addc_co_u32_e64 v78, s[30:31], 0, v78, s[26:27]
	v_addc_co_u32_e64 v77, s[34:35], 0, v77, s[28:29]
.LBB0_209:
	s_or_b64 exec, exec, s[16:17]
	s_and_saveexec_b64 s[16:17], s[6:7]
	s_cbranch_execz .LBB0_211
	v_cmp_le_u32_e64 s[18:19], s14, v46
	v_cmp_le_u32_e64 s[24:25], s14, v48
	v_cmp_le_u32_e64 s[26:27], s14, v47
	v_cmp_le_u32_e64 s[28:29], s14, v49
	v_addc_co_u32_e64 v78, s[30:31], 0, v78, s[18:19]
	v_addc_co_u32_e64 v77, s[34:35], 0, v77, s[24:25]
	v_addc_co_u32_e64 v78, s[30:31], 0, v78, s[26:27]
	v_addc_co_u32_e64 v77, s[34:35], 0, v77, s[28:29]
	v_cmp_le_u32_e64 s[18:19], s14, v42
	v_cmp_le_u32_e64 s[24:25], s14, v50
	v_cmp_le_u32_e64 s[26:27], s14, v43
	v_cmp_le_u32_e64 s[28:29], s14, v44
	v_addc_co_u32_e64 v78, s[30:31], 0, v78, s[18:19]
	v_addc_co_u32_e64 v77, s[34:35], 0, v77, s[24:25]
	v_addc_co_u32_e64 v78, s[30:31], 0, v78, s[26:27]
	v_addc_co_u32_e64 v77, s[34:35], 0, v77, s[28:29]
	v_cmp_le_u32_e64 s[18:19], s14, v38
	v_cmp_le_u32_e64 s[24:25], s14, v45
	v_cmp_le_u32_e64 s[26:27], s14, v39
	v_cmp_le_u32_e64 s[28:29], s14, v40
	v_addc_co_u32_e64 v78, s[30:31], 0, v78, s[18:19]
	v_addc_co_u32_e64 v77, s[34:35], 0, v77, s[24:25]
	v_addc_co_u32_e64 v78, s[30:31], 0, v78, s[26:27]
	v_addc_co_u32_e64 v77, s[34:35], 0, v77, s[28:29]
	v_cmp_le_u32_e64 s[18:19], s14, v41
	v_cmp_le_u32_e64 s[24:25], s14, v52
	v_cmp_le_u32_e64 s[26:27], s14, v51
	v_cmp_le_u32_e64 s[28:29], s14, v54
	v_addc_co_u32_e64 v78, s[30:31], 0, v78, s[18:19]
	v_addc_co_u32_e64 v77, s[34:35], 0, v77, s[24:25]
	v_addc_co_u32_e64 v78, s[30:31], 0, v78, s[26:27]
	v_addc_co_u32_e64 v77, s[34:35], 0, v77, s[28:29]
	v_cmp_le_u32_e64 s[18:19], s14, v53
	v_cmp_le_u32_e64 s[24:25], s14, v56
	v_cmp_le_u32_e64 s[26:27], s14, v55
	v_cmp_le_u32_e64 s[28:29], s14, v57
	v_addc_co_u32_e64 v78, s[30:31], 0, v78, s[18:19]
	v_addc_co_u32_e64 v77, s[34:35], 0, v77, s[24:25]
	v_addc_co_u32_e64 v78, s[30:31], 0, v78, s[26:27]
	v_addc_co_u32_e64 v77, s[34:35], 0, v77, s[28:29]
	v_cmp_le_u32_e64 s[18:19], s14, v58
	v_cmp_le_u32_e64 s[24:25], s14, v60
	v_cmp_le_u32_e64 s[26:27], s14, v59
	v_cmp_le_u32_e64 s[28:29], s14, v61
	v_addc_co_u32_e64 v78, s[30:31], 0, v78, s[18:19]
	v_addc_co_u32_e64 v77, s[34:35], 0, v77, s[24:25]
	v_addc_co_u32_e64 v78, s[30:31], 0, v78, s[26:27]
	v_addc_co_u32_e64 v77, s[34:35], 0, v77, s[28:29]
	v_cmp_le_u32_e64 s[18:19], s14, v62
	v_cmp_le_u32_e64 s[24:25], s14, v64
	v_cmp_le_u32_e64 s[26:27], s14, v63
	v_cmp_le_u32_e64 s[28:29], s14, v65
	v_addc_co_u32_e64 v78, s[30:31], 0, v78, s[18:19]
	v_addc_co_u32_e64 v77, s[34:35], 0, v77, s[24:25]
	v_addc_co_u32_e64 v78, s[30:31], 0, v78, s[26:27]
	v_addc_co_u32_e64 v77, s[34:35], 0, v77, s[28:29]
	v_cmp_le_u32_e64 s[18:19], s14, v72
	v_cmp_le_u32_e64 s[24:25], s14, v73
	v_cmp_le_u32_e64 s[26:27], s14, v74
	v_cmp_le_u32_e64 s[28:29], s14, v75
	v_addc_co_u32_e64 v78, s[30:31], 0, v78, s[18:19]
	v_addc_co_u32_e64 v77, s[34:35], 0, v77, s[24:25]
	v_addc_co_u32_e64 v78, s[30:31], 0, v78, s[26:27]
	v_addc_co_u32_e64 v77, s[34:35], 0, v77, s[28:29]

; __device__ __forceinline__ int count_ge(const unsigned (&u)[64], unsigned cand, int nblk) {
;     int c0 = 0, c1 = 0;
;     const unsigned ts = __builtin_amdgcn_readfirstlane(cand);
; #pragma unroll
;     for (int B = 0; B < 2; ++B) {
;         if (B < nblk) {
; #pragma unroll
;             for (int i = 0; i < 32; i += 4) CNT4(c0, c1, ts, u[B * 32 + i], u[B * 32 + i + 1], u[B * 32 + i + 2], u[B * 32 + i + 3]);
;         }
;     }
;     return wave_isum(c0 + c1);
; }
; __device__ __forceinline__ void select_query(const unsigned (&u)[64], unsigned vmax, int q, int b, int lane, unsigned* MASKb) {
;     ...
;         if (exact) TG = T - 1u; else { TG = T; rrem = 256 - count_ge(u, T + 1u, nblk); }
.LBB0_218:
	s_andn2_b64 vcc, exec, s[10:11]
	s_mov_b64 s[10:11], -1
	s_cbranch_vccz .LBB0_224
	s_add_i32 s12, s20, 1
	v_mov_b32_e32 v69, 0
	v_mov_b32_e32 v76, 0
	s_and_saveexec_b64 s[10:11], s[4:5]
	s_cbranch_execz .LBB0_221
	v_mov_b32_e32 v76, v1
	v_mov_b32_e32 v69, v1
	v_cmp_le_u32_e64 s[4:5], s12, v98
	v_cmp_le_u32_e64 s[14:15], s12, v107
	v_cmp_le_u32_e64 s[16:17], s12, v99
	v_cmp_le_u32_e64 s[18:19], s12, v108
	v_addc_co_u32_e64 v76, s[22:23], 0, v76, s[4:5]
	v_addc_co_u32_e64 v69, s[24:25], 0, v69, s[14:15]
	v_addc_co_u32_e64 v76, s[22:23], 0, v76, s[16:17]
	v_addc_co_u32_e64 v69, s[24:25], 0, v69, s[18:19]
	v_cmp_le_u32_e64 s[4:5], s12, v109
	v_cmp_le_u32_e64 s[14:15], s12, v113
	v_cmp_le_u32_e64 s[16:17], s12, v110
	v_cmp_le_u32_e64 s[18:19], s12, v114
	v_addc_co_u32_e64 v76, s[22:23], 0, v76, s[4:5]
	v_addc_co_u32_e64 v69, s[24:25], 0, v69, s[14:15]
	v_addc_co_u32_e64 v76, s[22:23], 0, v76, s[16:17]
	v_addc_co_u32_e64 v69, s[24:25], 0, v69, s[18:19]
	v_cmp_le_u32_e64 s[4:5], s12, v111
	v_cmp_le_u32_e64 s[14:15], s12, v115
	v_cmp_le_u32_e64 s[16:17], s12, v112
	v_cmp_le_u32_e64 s[18:19], s12, v116
	v_addc_co_u32_e64 v76, s[22:23], 0, v76, s[4:5]
	v_addc_co_u32_e64 v69, s[24:25], 0, v69, s[14:15]
	v_addc_co_u32_e64 v76, s[22:23], 0, v76, s[16:17]
	v_addc_co_u32_e64 v69, s[24:25], 0, v69, s[18:19]
	v_cmp_le_u32_e64 s[4:5], s12, v117
	v_cmp_le_u32_e64 s[14:15], s12, v119
	v_cmp_le_u32_e64 s[16:17], s12, v118
	v_cmp_le_u32_e64 s[18:19], s12, v121
	v_addc_co_u32_e64 v76, s[22:23], 0, v76, s[4:5]
	v_addc_co_u32_e64 v69, s[24:25], 0, v69, s[14:15]
	v_addc_co_u32_e64 v76, s[22:23], 0, v76, s[16:17]
	v_addc_co_u32_e64 v69, s[24:25], 0, v69, s[18:19]
	v_cmp_le_u32_e64 s[4:5], s12, v120
	v_cmp_le_u32_e64 s[14:15], s12, v123
	v_cmp_le_u32_e64 s[16:17], s12, v122
	v_cmp_le_u32_e64 s[18:19], s12, v124
	v_addc_co_u32_e64 v76, s[22:23], 0, v76, s[4:5]
	v_addc_co_u32_e64 v69, s[24:25], 0, v69, s[14:15]
	v_addc_co_u32_e64 v76, s[22:23], 0, v76, s[16:17]
	v_addc_co_u32_e64 v69, s[24:25], 0, v69, s[18:19]
	v_cmp_le_u32_e64 s[4:5], s12, v125
	v_cmp_le_u32_e64 s[14:15], s12, v127
	v_cmp_le_u32_e64 s[16:17], s12, v126
	v_cmp_le_u32_e64 s[18:19], s12, v128
	v_addc_co_u32_e64 v76, s[22:23], 0, v76, s[4:5]
	v_addc_co_u32_e64 v69, s[24:25], 0, v69, s[14:15]
	v_addc_co_u32_e64 v76, s[22:23], 0, v76, s[16:17]
	v_addc_co_u32_e64 v69, s[24:25], 0, v69, s[18:19]
	v_cmp_le_u32_e64 s[4:5], s12, v129
	v_cmp_le_u32_e64 s[14:15], s12, v131
	v_cmp_le_u32_e64 s[16:17], s12, v130
	v_cmp_le_u32_e64 s[18:19], s12, v132
	v_addc_co_u32_e64 v76, s[22:23], 0, v76, s[4:5]
	v_addc_co_u32_e64 v69, s[24:25], 0, v69, s[14:15]
	v_addc_co_u32_e64 v76, s[22:23], 0, v76, s[16:17]
	v_addc_co_u32_e64 v69, s[24:25], 0, v69, s[18:19]
	v_cmp_le_u32_e64 s[4:5], s12, v133
	v_cmp_le_u32_e64 s[14:15], s12, v134
	v_cmp_le_u32_e64 s[16:17], s12, v136
	v_cmp_le_u32_e64 s[18:19], s12, v137
	v_addc_co_u32_e64 v76, s[22:23], 0, v76, s[4:5]
	v_addc_co_u32_e64 v69, s[24:25], 0, v69, s[14:15]
	v_addc_co_u32_e64 v76, s[22:23], 0, v76, s[16:17]
	v_addc_co_u32_e64 v69, s[24:25], 0, v69, s[18:19]
.LBB0_221:
	s_or_b64 exec, exec, s[10:11]
	s_and_saveexec_b64 s[4:5], s[6:7]
	s_cbranch_execz .LBB0_223
	v_cmp_le_u32_e64 s[6:7], s12, v46
	v_cmp_le_u32_e64 s[10:11], s12, v48
	v_cmp_le_u32_e64 s[14:15], s12, v47
	v_cmp_le_u32_e64 s[16:17], s12, v49
	v_addc_co_u32_e64 v76, s[18:19], 0, v76, s[6:7]
	v_addc_co_u32_e64 v69, s[22:23], 0, v69, s[10:11]
	v_addc_co_u32_e64 v76, s[18:19], 0, v76, s[14:15]
	v_addc_co_u32_e64 v69, s[22:23], 0, v69, s[16:17]
	v_cmp_le_u32_e64 s[6:7], s12, v42
	v_cmp_le_u32_e64 s[10:11], s12, v50
	v_cmp_le_u32_e64 s[14:15], s12, v43
	v_cmp_le_u32_e64 s[16:17], s12, v44
	v_addc_co_u32_e64 v76, s[18:19], 0, v76, s[6:7]
	v_addc_co_u32_e64 v69, s[22:23], 0, v69, s[10:11]
	v_addc_co_u32_e64 v76, s[18:19], 0, v76, s[14:15]
	v_addc_co_u32_e64 v69, s[22:23], 0, v69, s[16:17]
	v_cmp_le_u32_e64 s[6:7], s12, v38
	v_cmp_le_u32_e64 s[10:11], s12, v45
	v_cmp_le_u32_e64 s[14:15], s12, v39
	v_cmp_le_u32_e64 s[16:17], s12, v40
	v_addc_co_u32_e64 v76, s[18:19], 0, v76, s[6:7]
	v_addc_co_u32_e64 v69, s[22:23], 0, v69, s[10:11]
	v_addc_co_u32_e64 v76, s[18:19], 0, v76, s[14:15]
	v_addc_co_u32_e64 v69, s[22:23], 0, v69, s[16:17]
	v_cmp_le_u32_e64 s[6:7], s12, v41
	v_cmp_le_u32_e64 s[10:11], s12, v52
	v_cmp_le_u32_e64 s[14:15], s12, v51
	v_cmp_le_u32_e64 s[16:17], s12, v54
	v_addc_co_u32_e64 v76, s[18:19], 0, v76, s[6:7]
	v_addc_co_u32_e64 v69, s[22:23], 0, v69, s[10:11]
	v_addc_co_u32_e64 v76, s[18:19], 0, v76, s[14:15]
	v_addc_co_u32_e64 v69, s[22:23], 0, v69, s[16:17]
	v_cmp_le_u32_e64 s[6:7], s12, v53
	v_cmp_le_u32_e64 s[10:11], s12, v56
	v_cmp_le_u32_e64 s[14:15], s12, v55
	v_cmp_le_u32_e64 s[16:17], s12, v57
	v_addc_co_u32_e64 v76, s[18:19], 0, v76, s[6:7]
	v_addc_co_u32_e64 v69, s[22:23], 0, v69, s[10:11]
	v_addc_co_u32_e64 v76, s[18:19], 0, v76, s[14:15]
	v_addc_co_u32_e64 v69, s[22:23], 0, v69, s[16:17]
	v_cmp_le_u32_e64 s[6:7], s12, v58
	v_cmp_le_u32_e64 s[10:11], s12, v60
	v_cmp_le_u32_e64 s[14:15], s12, v59
	v_cmp_le_u32_e64 s[16:17], s12, v61
	v_addc_co_u32_e64 v76, s[18:19], 0, v76, s[6:7]
	v_addc_co_u32_e64 v69, s[22:23], 0, v69, s[10:11]
	v_addc_co_u32_e64 v76, s[18:19], 0, v76, s[14:15]
	v_addc_co_u32_e64 v69, s[22:23], 0, v69, s[16:17]
	v_cmp_le_u32_e64 s[6:7], s12, v62
	v_cmp_le_u32_e64 s[10:11], s12, v64
	v_cmp_le_u32_e64 s[14:15], s12, v63
	v_cmp_le_u32_e64 s[16:17], s12, v65
	v_addc_co_u32_e64 v76, s[18:19], 0, v76, s[6:7]
	v_addc_co_u32_e64 v69, s[22:23], 0, v69, s[10:11]
	v_addc_co_u32_e64 v76, s[18:19], 0, v76, s[14:15]
	v_addc_co_u32_e64 v69, s[22:23], 0, v69, s[16:17]
	v_cmp_le_u32_e64 s[6:7], s12, v72
	v_cmp_le_u32_e64 s[10:11], s12, v73
	v_cmp_le_u32_e64 s[14:15], s12, v74
	v_cmp_le_u32_e64 s[16:17], s12, v75
	v_addc_co_u32_e64 v76, s[18:19], 0, v76, s[6:7]
	v_addc_co_u32_e64 v69, s[22:23], 0, v69, s[10:11]
	v_addc_co_u32_e64 v76, s[18:19], 0, v76, s[14:15]
	v_addc_co_u32_e64 v69, s[22:23], 0, v69, s[16:17]

; __device__ __forceinline__ void select_query(const unsigned (&u)[64], unsigned vmax, int q, int b, int lane, unsigned* MASKb) {
;     ...
;     int tbase = 0;
; #pragma unroll
;     for (int B = 0; B < 2; ++B) {
;         if (B < nblk) {
;             unsigned w = 0u; const unsigned tgs = __builtin_amdgcn_readfirstlane(TG);
; #pragma unroll
;             for (int e = 31; e >= 3; e -= 4) BIT4(w, tgs, u[B * 32 + e], u[B * 32 + e - 1], u[B * 32 + e - 2], u[B * 32 + e - 3]);
;             if (rrem > 0) {
;                 int ec = 0;
; #pragma unroll
;                 for (int e = 0; e < 32; ++e) ec += (u[B * 32 + e] == T) ? 1 : 0;
;                 int incl = ec;
; #pragma unroll
;                 for (int o = 1; o < 64; o <<= 1) { const int t = __shfl_up(incl, o); if (lane >= o) incl += t; }
;                 const int total = __builtin_amdgcn_readlane(incl, 63);
;                 const int quota = rrem - tbase - (incl - ec);
.LBB0_227:
	s_or_b64 exec, exec, s[8:9]
	v_mov_b32_e32 v79, 0
	v_cmp_lt_i32_e32 vcc, 0, v69
	v_cmp_lt_i32_e64 s[4:5], 0, v0
	s_and_saveexec_b64 s[72:73], s[4:5]
	s_cbranch_execz .LBB0_233
	v_mov_b32_e32 v78, 0
	v_readfirstlane_b32 s14, v77
	v_cmp_gt_u32_e64 s[4:5], v137, s14
	v_cmp_gt_u32_e64 s[6:7], v136, s14
	v_cmp_gt_u32_e64 s[8:9], v134, s14
	v_cmp_gt_u32_e64 s[10:11], v133, s14
	v_addc_co_u32_e64 v78, s[12:13], v78, v78, s[4:5]
	v_addc_co_u32_e64 v78, s[12:13], v78, v78, s[6:7]
	v_addc_co_u32_e64 v78, s[12:13], v78, v78, s[8:9]
	v_addc_co_u32_e64 v78, s[12:13], v78, v78, s[10:11]
	v_mov_b32_e32 v79, 0
	v_cmp_gt_u32_e64 s[4:5], v132, s14
	v_cmp_gt_u32_e64 s[6:7], v130, s14
	v_cmp_gt_u32_e64 s[8:9], v131, s14
	v_cmp_gt_u32_e64 s[10:11], v129, s14
	v_addc_co_u32_e64 v78, s[12:13], v78, v78, s[4:5]
	v_addc_co_u32_e64 v78, s[12:13], v78, v78, s[6:7]
	v_addc_co_u32_e64 v78, s[12:13], v78, v78, s[8:9]
	v_addc_co_u32_e64 v78, s[12:13], v78, v78, s[10:11]
	v_cmp_gt_u32_e64 s[4:5], v128, s14
	v_cmp_gt_u32_e64 s[6:7], v126, s14
	v_cmp_gt_u32_e64 s[8:9], v127, s14
	v_cmp_gt_u32_e64 s[10:11], v125, s14
	v_addc_co_u32_e64 v78, s[12:13], v78, v78, s[4:5]
	v_addc_co_u32_e64 v78, s[12:13], v78, v78, s[6:7]
	v_addc_co_u32_e64 v78, s[12:13], v78, v78, s[8:9]
	v_addc_co_u32_e64 v78, s[12:13], v78, v78, s[10:11]
	v_cmp_gt_u32_e64 s[4:5], v124, s14
	v_cmp_gt_u32_e64 s[6:7], v122, s14
	v_cmp_gt_u32_e64 s[8:9], v123, s14
	v_cmp_gt_u32_e64 s[10:11], v120, s14
	v_addc_co_u32_e64 v78, s[12:13], v78, v78, s[4:5]
	v_addc_co_u32_e64 v78, s[12:13], v78, v78, s[6:7]
	v_addc_co_u32_e64 v78, s[12:13], v78, v78, s[8:9]
	v_addc_co_u32_e64 v78, s[12:13], v78, v78, s[10:11]
	v_cmp_gt_u32_e64 s[4:5], v121, s14
	v_cmp_gt_u32_e64 s[6:7], v118, s14
	v_cmp_gt_u32_e64 s[8:9], v119, s14
	v_cmp_gt_u32_e64 s[10:11], v117, s14
	v_addc_co_u32_e64 v78, s[12:13], v78, v78, s[4:5]
	v_addc_co_u32_e64 v78, s[12:13], v78, v78, s[6:7]
	v_addc_co_u32_e64 v78, s[12:13], v78, v78, s[8:9]
	v_addc_co_u32_e64 v78, s[12:13], v78, v78, s[10:11]
	v_cmp_gt_u32_e64 s[4:5], v116, s14
	v_cmp_gt_u32_e64 s[6:7], v112, s14
	v_cmp_gt_u32_e64 s[8:9], v115, s14
	v_cmp_gt_u32_e64 s[10:11], v111, s14
	v_addc_co_u32_e64 v78, s[12:13], v78, v78, s[4:5]
	v_addc_co_u32_e64 v78, s[12:13], v78, v78, s[6:7]
	v_addc_co_u32_e64 v78, s[12:13], v78, v78, s[8:9]
	v_addc_co_u32_e64 v78, s[12:13], v78, v78, s[10:11]
	v_cmp_gt_u32_e64 s[4:5], v114, s14
	v_cmp_gt_u32_e64 s[6:7], v110, s14
	v_cmp_gt_u32_e64 s[8:9], v113, s14
	v_cmp_gt_u32_e64 s[10:11], v109, s14
	v_addc_co_u32_e64 v78, s[12:13], v78, v78, s[4:5]
	v_addc_co_u32_e64 v78, s[12:13], v78, v78, s[6:7]
	v_addc_co_u32_e64 v78, s[12:13], v78, v78, s[8:9]
	v_addc_co_u32_e64 v78, s[12:13], v78, v78, s[10:11]
	v_cmp_gt_u32_e64 s[4:5], v108, s14
	v_cmp_gt_u32_e64 s[6:7], v99, s14
	v_cmp_gt_u32_e64 s[8:9], v107, s14
	v_cmp_gt_u32_e64 s[10:11], v98, s14
	v_addc_co_u32_e64 v78, s[12:13], v78, v78, s[4:5]
	v_addc_co_u32_e64 v78, s[12:13], v78, v78, s[6:7]
	v_addc_co_u32_e64 v78, s[12:13], v78, v78, s[8:9]
	v_addc_co_u32_e64 v78, s[12:13], v78, v78, s[10:11]
	s_and_saveexec_b64 s[90:91], vcc
	s_cbranch_execz .LBB0_230
	v_cmp_eq_u32_e64 s[4:5], v137, v76
	v_cmp_eq_u32_e64 s[8:9], v136, v76
	v_cmp_eq_u32_e64 s[6:7], v134, v76
	v_cndmask_b32_e64 v95, 0, 1, s[4:5]
	v_addc_co_u32_e64 v95, s[12:13], 0, v95, s[8:9]
	v_cndmask_b32_e64 v94, 0, 1, s[6:7]
	v_cmp_eq_u32_e64 s[12:13], v133, v76
	v_cmp_eq_u32_e64 s[10:11], v132, v76
	v_cmp_eq_u32_e64 s[14:15], v131, v76
	v_addc_co_u32_e64 v94, s[18:19], v95, v94, s[12:13]
	v_cndmask_b32_e64 v93, 0, 1, s[10:11]
	v_cmp_eq_u32_e64 s[18:19], v130, v76
	v_cndmask_b32_e64 v92, 0, 1, s[14:15]
	v_cmp_eq_u32_e64 s[16:17], v128, v76
	v_addc_co_u32_e64 v93, s[24:25], v94, v93, s[18:19]
	v_cmp_eq_u32_e64 s[24:25], v129, v76
	v_cndmask_b32_e64 v91, 0, 1, s[16:17]
	v_cmp_eq_u32_e64 s[20:21], v127, v76
	v_addc_co_u32_e64 v92, s[28:29], v93, v92, s[24:25]
	v_cmp_eq_u32_e64 s[28:29], v126, v76
	v_cndmask_b32_e64 v90, 0, 1, s[20:21]
	v_cmp_eq_u32_e64 s[22:23], v124, v76
	v_addc_co_u32_e64 v91, s[36:37], v92, v91, s[28:29]
	v_cmp_eq_u32_e64 s[36:37], v125, v76
	v_cndmask_b32_e64 v89, 0, 1, s[22:23]
	v_cmp_eq_u32_e64 s[26:27], v123, v76
	v_addc_co_u32_e64 v90, s[42:43], v91, v90, s[36:37]
	v_cmp_eq_u32_e64 s[42:43], v122, v76
	v_cndmask_b32_e64 v87, 0, 1, s[26:27]
	v_cmp_eq_u32_e64 s[30:31], v121, v76
	v_addc_co_u32_e64 v89, s[48:49], v90, v89, s[42:43]
	v_cmp_eq_u32_e64 s[48:49], v120, v76
	v_cndmask_b32_e64 v86, 0, 1, s[30:31]
	v_cmp_eq_u32_e64 s[34:35], v119, v76
	v_addc_co_u32_e64 v87, s[52:53], v89, v87, s[48:49]
	v_cmp_eq_u32_e64 s[52:53], v118, v76
	v_cndmask_b32_e64 v85, 0, 1, s[34:35]
	s_mov_b32 s82, s38
	v_addc_co_u32_e64 v86, s[56:57], v87, v86, s[52:53]
	v_cmp_eq_u32_e64 s[56:57], v117, v76
	v_cmp_eq_u32_e64 s[38:39], v116, v76
	v_cmp_eq_u32_e64 s[40:41], v115, v76
	v_addc_co_u32_e64 v85, s[58:59], v86, v85, s[56:57]
	v_cndmask_b32_e64 v84, 0, 1, s[38:39]
	v_cmp_eq_u32_e64 s[58:59], v112, v76
	v_cndmask_b32_e64 v83, 0, 1, s[40:41]
	v_cmp_eq_u32_e64 s[44:45], v114, v76
	v_addc_co_u32_e64 v84, s[60:61], v85, v84, s[58:59]
	v_cmp_eq_u32_e64 s[60:61], v111, v76
	v_cndmask_b32_e64 v82, 0, 1, s[44:45]
	v_cmp_eq_u32_e64 s[46:47], v113, v76
	v_addc_co_u32_e64 v83, s[62:63], v84, v83, s[60:61]
	v_cmp_eq_u32_e64 s[62:63], v110, v76
	v_cndmask_b32_e64 v81, 0, 1, s[46:47]
	v_cmp_eq_u32_e64 s[50:51], v108, v76
	v_addc_co_u32_e64 v82, s[64:65], v83, v82, s[62:63]
	v_cmp_eq_u32_e64 s[64:65], v109, v76
	v_cndmask_b32_e64 v80, 0, 1, s[50:51]
	v_cmp_eq_u32_e64 s[54:55], v107, v76
	v_addc_co_u32_e64 v81, s[66:67], v82, v81, s[64:65]
	v_cmp_eq_u32_e64 s[66:67], v99, v76
	v_cndmask_b32_e64 v79, 0, 1, s[54:55]
	s_nop 0
	v_addc_co_u32_e64 v80, s[68:69], v81, v80, s[66:67]
	v_cmp_eq_u32_e64 s[68:69], v98, v76
	s_nop 1
	v_addc_co_u32_e64 v79, s[70:71], v80, v79, s[68:69]
	ds_bpermute_b32 v80, v100, v79
	v_cmp_lt_i32_e64 s[70:71], 0, v68
	s_waitcnt lgkmcnt(0)
; __device__ __forceinline__ void select_query(const unsigned (&u)[64], unsigned vmax, int q, int b, int lane, unsigned* MASKb) {
;     ...
;                 int incl = ec;
; #pragma unroll
;                 for (int o = 1; o < 64; o <<= 1) { const int t = __shfl_up(incl, o); if (lane >= o) incl += t; }
;                 const int total = __builtin_amdgcn_readlane(incl, 63);
;                 const int quota = rrem - tbase - (incl - ec);
;                 int taken = 0;
; #pragma unroll
;                 for (int e = 0; e < 32; ++e) { const bool is = (u[B * 32 + e] == T) && (taken < quota); w |= is ? (1u << e) : 0u; taken += is ? 1 : 0; }
	s_nop 0
	v_cndmask_b32_e64 v80, 0, v80, s[70:71]
	v_add_u32_e32 v80, v80, v79
	ds_bpermute_b32 v81, v101, v80
	v_cmp_lt_i32_e64 s[70:71], 1, v68
	v_add_u32_e32 v79, v79, v69
	s_waitcnt lgkmcnt(0)
	v_cndmask_b32_e64 v81, 0, v81, s[70:71]
	v_add_u32_e32 v80, v81, v80
	ds_bpermute_b32 v81, v102, v80
	v_cmp_lt_i32_e64 s[70:71], 3, v68
	s_waitcnt lgkmcnt(0)
	s_nop 0
	v_cndmask_b32_e64 v81, 0, v81, s[70:71]
	v_add_u32_e32 v80, v81, v80
	ds_bpermute_b32 v81, v103, v80
	v_cmp_lt_i32_e64 s[70:71], 7, v68
	s_waitcnt lgkmcnt(0)
	s_nop 0
	v_cndmask_b32_e64 v81, 0, v81, s[70:71]
	v_add_u32_e32 v80, v81, v80
	ds_bpermute_b32 v81, v104, v80
	v_cmp_lt_i32_e64 s[70:71], 15, v68
	s_waitcnt lgkmcnt(0)
	s_nop 0
	v_cndmask_b32_e64 v81, 0, v81, s[70:71]
	v_add_u32_e32 v80, v81, v80
	ds_bpermute_b32 v81, v105, v80
	v_cmp_lt_i32_e64 s[70:71], 31, v68
	s_waitcnt lgkmcnt(0)
	s_nop 0
	v_cndmask_b32_e64 v81, 0, v81, s[70:71]
	v_add_u32_e32 v80, v81, v80
	v_sub_u32_e32 v79, v79, v80
	v_cmp_lt_i32_e64 s[70:71], 0, v79
	s_and_b64 s[68:69], s[68:69], s[70:71]
	v_cndmask_b32_e64 v81, 0, 1, s[68:69]
	v_cmp_gt_i32_e64 s[68:69], v79, v81
	s_and_b64 s[54:55], s[54:55], s[68:69]
	v_cndmask_b32_e64 v82, 0, 2, s[54:55]
	v_cndmask_b32_e64 v83, 0, 1, s[54:55]
	v_addc_co_u32_e64 v84, s[54:55], 0, v81, s[54:55]
	v_cmp_lt_i32_e64 s[54:55], v84, v79
	s_and_b64 s[54:55], s[66:67], s[54:55]
	s_nop 0
	v_cndmask_b32_e64 v84, 0, 4, s[54:55]
	v_addc_co_u32_e64 v83, s[54:55], v83, v81, s[54:55]
	v_cmp_lt_i32_e64 s[54:55], v83, v79
	s_and_b64 s[50:51], s[50:51], s[54:55]
	v_cndmask_b32_e64 v85, 0, 8, s[50:51]
	v_cndmask_b32_e64 v86, 0, 1, s[50:51]
	v_addc_co_u32_e64 v87, s[50:51], 0, v83, s[50:51]
	v_cmp_lt_i32_e64 s[50:51], v87, v79
	s_and_b64 s[50:51], s[64:65], s[50:51]
	v_or3_b32 v82, v82, v84, v85
	v_cndmask_b32_e64 v89, 0, 16, s[50:51]
	v_cndmask_b32_e64 v90, 0, 1, s[50:51]
	v_addc_co_u32_e64 v83, s[50:51], v83, v86, s[50:51]
	v_cmp_lt_i32_e64 s[50:51], v83, v79
	s_and_b64 s[46:47], s[46:47], s[50:51]
	v_cndmask_b32_e64 v86, 0, 32, s[46:47]
	v_cndmask_b32_e64 v91, 0, 1, s[46:47]
	v_addc_co_u32_e64 v87, s[46:47], v87, v90, s[46:47]
	v_cmp_lt_i32_e64 s[46:47], v87, v79
	s_and_b64 s[46:47], s[62:63], s[46:47]
	v_or3_b32 v82, v82, v89, v86
	v_cndmask_b32_e64 v90, 0, 64, s[46:47]
	v_cndmask_b32_e64 v92, 0, 1, s[46:47]
	v_addc_co_u32_e64 v83, s[46:47], v83, v91, s[46:47]
	v_cmp_lt_i32_e64 s[46:47], v83, v79
	s_and_b64 s[44:45], s[44:45], s[46:47]
	v_mov_b32_e32 v91, 0x80
	v_cndmask_b32_e64 v91, 0, v91, s[44:45]
	v_cndmask_b32_e64 v93, 0, 1, s[44:45]
	v_addc_co_u32_e64 v87, s[44:45], v87, v92, s[44:45]
	v_cmp_lt_i32_e64 s[44:45], v87, v79
	s_and_b64 s[44:45], s[60:61], s[44:45]
	v_mov_b32_e32 v92, 0x100
	v_cndmask_b32_e64 v92, 0, v92, s[44:45]
	v_cndmask_b32_e64 v94, 0, 1, s[44:45]
	v_addc_co_u32_e64 v83, s[44:45], v83, v93, s[44:45]
	v_cmp_lt_i32_e64 s[44:45], v83, v79
	s_and_b64 s[40:41], s[40:41], s[44:45]
	v_mov_b32_e32 v93, 0x200
	v_cndmask_b32_e64 v93, 0, v93, s[40:41]
	v_cndmask_b32_e64 v95, 0, 1, s[40:41]
	v_addc_co_u32_e64 v87, s[40:41], v87, v94, s[40:41]
	v_cmp_lt_i32_e64 s[40:41], v87, v79
	s_and_b64 s[40:41], s[58:59], s[40:41]
	v_mov_b32_e32 v94, 0x400
	v_cndmask_b32_e64 v94, 0, v94, s[40:41]
	v_cndmask_b32_e64 v96, 0, 1, s[40:41]
	v_addc_co_u32_e64 v83, s[40:41], v83, v95, s[40:41]
	v_cmp_lt_i32_e64 s[40:41], v83, v79
	s_and_b64 s[38:39], s[38:39], s[40:41]
	v_mov_b32_e32 v95, 0x800
	v_cndmask_b32_e64 v95, 0, v95, s[38:39]
	v_cndmask_b32_e64 v97, 0, 1, s[38:39]
	v_addc_co_u32_e64 v87, s[38:39], v87, v96, s[38:39]
	v_cmp_lt_i32_e64 s[38:39], v87, v79
	s_and_b64 s[38:39], s[56:57], s[38:39]
	v_mov_b32_e32 v96, 0x1000
	v_cndmask_b32_e64 v96, 0, v96, s[38:39]
	v_cndmask_b32_e64 v98, 0, 1, s[38:39]
	v_addc_co_u32_e64 v83, s[38:39], v83, v97, s[38:39]
	v_cmp_lt_i32_e64 s[38:39], v83, v79
	s_and_b64 s[34:35], s[34:35], s[38:39]
	v_cndmask_b32_e64 v97, 0, v240, s[34:35]
	v_cndmask_b32_e64 v99, 0, 1, s[34:35]
	v_addc_co_u32_e64 v87, s[34:35], v87, v98, s[34:35]
	v_cmp_lt_i32_e64 s[34:35], v87, v79
	s_and_b64 s[34:35], s[52:53], s[34:35]
	v_mov_b32_e32 v98, 0x4000
	v_cndmask_b32_e64 v98, 0, v98, s[34:35]
	v_cndmask_b32_e64 v106, 0, 1, s[34:35]
	v_addc_co_u32_e64 v83, s[34:35], v83, v99, s[34:35]
	v_cmp_lt_i32_e64 s[34:35], v83, v79
	s_and_b64 s[30:31], s[30:31], s[34:35]
	v_mov_b32_e32 v99, 0x8000
; __device__ __forceinline__ void select_query(const unsigned (&u)[64], unsigned vmax, int q, int b, int lane, unsigned* MASKb) {
;     ...
;                 const int total = __builtin_amdgcn_readlane(incl, 63);
;                 const int quota = rrem - tbase - (incl - ec);
;                 int taken = 0;
; #pragma unroll
;                 for (int e = 0; e < 32; ++e) { const bool is = (u[B * 32 + e] == T) && (taken < quota); w |= is ? (1u << e) : 0u; taken += is ? 1 : 0; }
;                 tbase += total;
	v_cndmask_b32_e64 v99, 0, v99, s[30:31]
	v_cndmask_b32_e64 v107, 0, 1, s[30:31]
	v_addc_co_u32_e64 v87, s[30:31], v87, v106, s[30:31]
	v_cmp_lt_i32_e64 s[30:31], v87, v79
	s_and_b64 s[30:31], s[48:49], s[30:31]
	v_mov_b32_e32 v106, 0x10000
	v_cndmask_b32_e64 v106, 0, v106, s[30:31]
	v_cndmask_b32_e64 v108, 0, 1, s[30:31]
	v_addc_co_u32_e64 v83, s[30:31], v83, v107, s[30:31]
	v_cmp_lt_i32_e64 s[30:31], v83, v79
	s_and_b64 s[26:27], s[26:27], s[30:31]
	v_mov_b32_e32 v107, 0x20000
	v_cndmask_b32_e64 v107, 0, v107, s[26:27]
	v_cndmask_b32_e64 v109, 0, 1, s[26:27]
	v_addc_co_u32_e64 v87, s[26:27], v87, v108, s[26:27]
	v_cmp_lt_i32_e64 s[26:27], v87, v79
	s_and_b64 s[26:27], s[42:43], s[26:27]
	v_mov_b32_e32 v108, 0x40000
	v_cndmask_b32_e64 v108, 0, v108, s[26:27]
	v_cndmask_b32_e64 v110, 0, 1, s[26:27]
	v_addc_co_u32_e64 v83, s[26:27], v83, v109, s[26:27]
	v_cmp_lt_i32_e64 s[26:27], v83, v79
	s_and_b64 s[22:23], s[22:23], s[26:27]
	v_mov_b32_e32 v109, 0x80000
	v_cndmask_b32_e64 v109, 0, v109, s[22:23]
	v_cndmask_b32_e64 v111, 0, 1, s[22:23]
	v_addc_co_u32_e64 v87, s[22:23], v87, v110, s[22:23]
	v_cmp_lt_i32_e64 s[22:23], v87, v79
	s_and_b64 s[22:23], s[36:37], s[22:23]
	v_mov_b32_e32 v110, 0x100000
	v_cndmask_b32_e64 v110, 0, v110, s[22:23]
	v_cndmask_b32_e64 v112, 0, 1, s[22:23]
	v_addc_co_u32_e64 v83, s[22:23], v83, v111, s[22:23]
	v_cmp_lt_i32_e64 s[22:23], v83, v79
	s_and_b64 s[20:21], s[20:21], s[22:23]
	v_mov_b32_e32 v111, 0x200000
	v_cndmask_b32_e64 v111, 0, v111, s[20:21]
	v_cndmask_b32_e64 v113, 0, 1, s[20:21]
	v_addc_co_u32_e64 v87, s[20:21], v87, v112, s[20:21]
	v_cmp_lt_i32_e64 s[20:21], v87, v79
	s_and_b64 s[20:21], s[28:29], s[20:21]
	v_mov_b32_e32 v112, 0x400000
	v_cndmask_b32_e64 v112, 0, v112, s[20:21]
	v_cndmask_b32_e64 v114, 0, 1, s[20:21]
	v_addc_co_u32_e64 v83, s[20:21], v83, v113, s[20:21]
	v_cmp_lt_i32_e64 s[20:21], v83, v79
	s_and_b64 s[16:17], s[16:17], s[20:21]
	v_mov_b32_e32 v113, 0x800000
	v_cndmask_b32_e64 v113, 0, v113, s[16:17]
	v_cndmask_b32_e64 v115, 0, 1, s[16:17]
	v_addc_co_u32_e64 v87, s[16:17], v87, v114, s[16:17]
	v_cmp_lt_i32_e64 s[16:17], v87, v79
	s_and_b64 s[16:17], s[24:25], s[16:17]
	v_mov_b32_e32 v114, 0x1000000
	v_cndmask_b32_e64 v114, 0, v114, s[16:17]
	v_cndmask_b32_e64 v116, 0, 1, s[16:17]
	v_addc_co_u32_e64 v83, s[16:17], v83, v115, s[16:17]
	v_cmp_lt_i32_e64 s[16:17], v83, v79
	s_and_b64 s[14:15], s[14:15], s[16:17]
	v_bfrev_b32_e32 v115, 64
	v_cndmask_b32_e64 v115, 0, v115, s[14:15]
	v_cndmask_b32_e64 v117, 0, 1, s[14:15]
	v_addc_co_u32_e64 v87, s[14:15], v87, v116, s[14:15]
	v_cmp_lt_i32_e64 s[14:15], v87, v79
	s_and_b64 s[14:15], s[18:19], s[14:15]
	v_bfrev_b32_e32 v116, 32
	v_cndmask_b32_e64 v116, 0, v116, s[14:15]
	v_cndmask_b32_e64 v118, 0, 1, s[14:15]
	v_addc_co_u32_e64 v83, s[14:15], v83, v117, s[14:15]
	v_cmp_lt_i32_e64 s[14:15], v83, v79
	s_and_b64 s[10:11], s[10:11], s[14:15]
	v_bfrev_b32_e32 v117, 16
	v_cndmask_b32_e64 v117, 0, v117, s[10:11]
	v_cndmask_b32_e64 v119, 0, 1, s[10:11]
	v_addc_co_u32_e64 v87, s[10:11], v87, v118, s[10:11]
	v_cmp_lt_i32_e64 s[10:11], v87, v79
	v_or3_b32 v82, v82, v90, v91
	s_and_b64 s[10:11], s[12:13], s[10:11]
	v_bfrev_b32_e32 v118, 8
	v_or3_b32 v82, v82, v92, v93
	v_cndmask_b32_e64 v118, 0, v118, s[10:11]
	v_cndmask_b32_e64 v120, 0, 1, s[10:11]
	v_addc_co_u32_e64 v83, s[10:11], v83, v119, s[10:11]
	v_or3_b32 v82, v82, v94, v95
	v_cmp_lt_i32_e64 s[10:11], v83, v79
	v_or3_b32 v82, v82, v96, v97
	s_and_b64 s[6:7], s[6:7], s[10:11]
	v_bfrev_b32_e32 v119, 4
	v_or3_b32 v82, v82, v98, v99
	v_cndmask_b32_e64 v119, 0, v119, s[6:7]
	v_cndmask_b32_e64 v121, 0, 1, s[6:7]
	v_addc_co_u32_e64 v87, s[6:7], v87, v120, s[6:7]
	v_or3_b32 v82, v82, v106, v107
	v_cmp_lt_i32_e64 s[6:7], v87, v79
	v_or3_b32 v82, v82, v108, v109
	s_and_b64 s[6:7], s[8:9], s[6:7]
	v_or3_b32 v82, v82, v110, v111
	v_cndmask_b32_e64 v87, 0, 2.0, s[6:7]
	v_addc_co_u32_e64 v83, s[6:7], v83, v121, s[6:7]
	v_or3_b32 v82, v82, v112, v113
	v_cmp_lt_i32_e64 s[6:7], v83, v79
	v_or3_b32 v82, v82, v114, v115
	s_and_b64 s[4:5], s[4:5], s[6:7]
	v_bfrev_b32_e32 v79, 1
	v_or3_b32 v82, v82, v116, v117
	v_cndmask_b32_e64 v79, 0, v79, s[4:5]
	v_or3_b32 v82, v82, v118, v119
	v_or3_b32 v79, v82, v87, v79
	v_readlane_b32 s4, v80, 63
	s_mov_b32 s38, s82
	v_or3_b32 v78, v79, v81, v78
	v_mov_b32_e32 v79, s4

; __device__ __forceinline__ void select_query(const unsigned (&u)[64], unsigned vmax, int q, int b, int lane, unsigned* MASKb) {
;     ...
;     for (int B = 0; B < 2; ++B) {
;         if (B < nblk) {
;             unsigned w = 0u; const unsigned tgs = __builtin_amdgcn_readfirstlane(TG);
; #pragma unroll
;             for (int e = 31; e >= 3; e -= 4) BIT4(w, tgs, u[B * 32 + e], u[B * 32 + e - 1], u[B * 32 + e - 2], u[B * 32 + e - 3]);
;             if (rrem > 0) {
;                 int ec = 0;
; #pragma unroll
;                 for (int e = 0; e < 32; ++e) ec += (u[B * 32 + e] == T) ? 1 : 0;
;                 int incl = ec;
; #pragma unroll
;                 for (int o = 1; o < 64; o <<= 1) { const int t = __shfl_up(incl, o); if (lane >= o) incl += t; }
.LBB0_233:
	s_or_b64 exec, exec, s[72:73]
	v_cmp_lt_i32_e64 s[4:5], 1, v0
	s_and_saveexec_b64 s[70:71], s[4:5]
	s_cbranch_execz .LBB0_238
	v_mov_b32_e32 v0, v1
	v_readfirstlane_b32 s14, v77
	v_cmp_gt_u32_e64 s[4:5], v75, s14
	v_cmp_gt_u32_e64 s[6:7], v74, s14
	v_cmp_gt_u32_e64 s[8:9], v73, s14
	v_cmp_gt_u32_e64 s[10:11], v72, s14
	v_addc_co_u32_e64 v0, s[12:13], v0, v0, s[4:5]
	v_addc_co_u32_e64 v0, s[12:13], v0, v0, s[6:7]
	v_addc_co_u32_e64 v0, s[12:13], v0, v0, s[8:9]
	v_addc_co_u32_e64 v0, s[12:13], v0, v0, s[10:11]
	v_cmp_gt_u32_e64 s[4:5], v65, s14
	v_cmp_gt_u32_e64 s[6:7], v63, s14
	v_cmp_gt_u32_e64 s[8:9], v64, s14
	v_cmp_gt_u32_e64 s[10:11], v62, s14
	v_addc_co_u32_e64 v0, s[12:13], v0, v0, s[4:5]
	v_addc_co_u32_e64 v0, s[12:13], v0, v0, s[6:7]
	v_addc_co_u32_e64 v0, s[12:13], v0, v0, s[8:9]
	v_addc_co_u32_e64 v0, s[12:13], v0, v0, s[10:11]
	v_cmp_gt_u32_e64 s[4:5], v61, s14
	v_cmp_gt_u32_e64 s[6:7], v59, s14
	v_cmp_gt_u32_e64 s[8:9], v60, s14
	v_cmp_gt_u32_e64 s[10:11], v58, s14
	v_addc_co_u32_e64 v0, s[12:13], v0, v0, s[4:5]
	v_addc_co_u32_e64 v0, s[12:13], v0, v0, s[6:7]
	v_addc_co_u32_e64 v0, s[12:13], v0, v0, s[8:9]
	v_addc_co_u32_e64 v0, s[12:13], v0, v0, s[10:11]
	v_cmp_gt_u32_e64 s[4:5], v57, s14
	v_cmp_gt_u32_e64 s[6:7], v55, s14
	v_cmp_gt_u32_e64 s[8:9], v56, s14
	v_cmp_gt_u32_e64 s[10:11], v53, s14
	v_addc_co_u32_e64 v0, s[12:13], v0, v0, s[4:5]
	v_addc_co_u32_e64 v0, s[12:13], v0, v0, s[6:7]
	v_addc_co_u32_e64 v0, s[12:13], v0, v0, s[8:9]
	v_addc_co_u32_e64 v0, s[12:13], v0, v0, s[10:11]
	v_cmp_gt_u32_e64 s[4:5], v54, s14
	v_cmp_gt_u32_e64 s[6:7], v51, s14
	v_cmp_gt_u32_e64 s[8:9], v52, s14
	v_cmp_gt_u32_e64 s[10:11], v41, s14
	v_addc_co_u32_e64 v0, s[12:13], v0, v0, s[4:5]
	v_addc_co_u32_e64 v0, s[12:13], v0, v0, s[6:7]
	v_addc_co_u32_e64 v0, s[12:13], v0, v0, s[8:9]
	v_addc_co_u32_e64 v0, s[12:13], v0, v0, s[10:11]
	v_cmp_gt_u32_e64 s[4:5], v40, s14
	v_cmp_gt_u32_e64 s[6:7], v39, s14
	v_cmp_gt_u32_e64 s[8:9], v45, s14
	v_cmp_gt_u32_e64 s[10:11], v38, s14
	v_addc_co_u32_e64 v0, s[12:13], v0, v0, s[4:5]
	v_addc_co_u32_e64 v0, s[12:13], v0, v0, s[6:7]
	v_addc_co_u32_e64 v0, s[12:13], v0, v0, s[8:9]
	v_addc_co_u32_e64 v0, s[12:13], v0, v0, s[10:11]
	v_cmp_gt_u32_e64 s[4:5], v44, s14
	v_cmp_gt_u32_e64 s[6:7], v43, s14
	v_cmp_gt_u32_e64 s[8:9], v50, s14
	v_cmp_gt_u32_e64 s[10:11], v42, s14
	v_addc_co_u32_e64 v0, s[12:13], v0, v0, s[4:5]
	v_addc_co_u32_e64 v0, s[12:13], v0, v0, s[6:7]
	v_addc_co_u32_e64 v0, s[12:13], v0, v0, s[8:9]
	v_addc_co_u32_e64 v0, s[12:13], v0, v0, s[10:11]
	v_cmp_gt_u32_e64 s[4:5], v49, s14
	v_cmp_gt_u32_e64 s[6:7], v47, s14
	v_cmp_gt_u32_e64 s[8:9], v48, s14
	v_cmp_gt_u32_e64 s[10:11], v46, s14
	v_addc_co_u32_e64 v0, s[12:13], v0, v0, s[4:5]
	v_addc_co_u32_e64 v0, s[12:13], v0, v0, s[6:7]
	v_addc_co_u32_e64 v0, s[12:13], v0, v0, s[8:9]
	v_addc_co_u32_e64 v0, s[12:13], v0, v0, s[10:11]
	s_and_saveexec_b64 s[72:73], vcc
	s_cbranch_execz .LBB0_236
	v_cmp_eq_u32_e32 vcc, v75, v76
	v_cmp_eq_u32_e64 s[6:7], v74, v76
	v_cmp_eq_u32_e64 s[4:5], v73, v76
	v_cndmask_b32_e64 v75, 0, 1, vcc
	v_addc_co_u32_e64 v74, s[10:11], 0, v75, s[6:7]
	v_cndmask_b32_e64 v73, 0, 1, s[4:5]
	v_cmp_eq_u32_e64 s[10:11], v72, v76
	v_cmp_eq_u32_e64 s[8:9], v65, v76
	v_cmp_eq_u32_e64 s[12:13], v64, v76
	v_addc_co_u32_e64 v72, s[16:17], v74, v73, s[10:11]
	v_cndmask_b32_e64 v65, 0, 1, s[8:9]
	v_cmp_eq_u32_e64 s[16:17], v63, v76
	v_cndmask_b32_e64 v64, 0, 1, s[12:13]
	v_cmp_eq_u32_e64 s[14:15], v61, v76
	v_addc_co_u32_e64 v63, s[22:23], v72, v65, s[16:17]
	v_cmp_eq_u32_e64 s[22:23], v62, v76
	v_cndmask_b32_e64 v61, 0, 1, s[14:15]
	v_cmp_eq_u32_e64 s[18:19], v60, v76
	v_addc_co_u32_e64 v62, s[26:27], v63, v64, s[22:23]
	v_cmp_eq_u32_e64 s[26:27], v59, v76
	v_cndmask_b32_e64 v60, 0, 1, s[18:19]
	v_cmp_eq_u32_e64 s[20:21], v57, v76
	v_addc_co_u32_e64 v59, s[34:35], v62, v61, s[26:27]
	v_cmp_eq_u32_e64 s[34:35], v58, v76
	v_cndmask_b32_e64 v57, 0, 1, s[20:21]
	v_cmp_eq_u32_e64 s[24:25], v56, v76
	v_addc_co_u32_e64 v58, s[40:41], v59, v60, s[34:35]
	v_cmp_eq_u32_e64 s[40:41], v55, v76
	v_cndmask_b32_e64 v56, 0, 1, s[24:25]
	v_cmp_eq_u32_e64 s[28:29], v54, v76
	v_addc_co_u32_e64 v55, s[46:47], v58, v57, s[40:41]
	v_cmp_eq_u32_e64 s[46:47], v53, v76
	v_cndmask_b32_e64 v54, 0, 1, s[28:29]
	v_cmp_eq_u32_e64 s[30:31], v52, v76
	v_addc_co_u32_e64 v53, s[50:51], v55, v56, s[46:47]
	v_cmp_eq_u32_e64 s[50:51], v51, v76
	v_cndmask_b32_e64 v52, 0, 1, s[30:31]
	v_cmp_eq_u32_e64 s[36:37], v40, v76
	v_addc_co_u32_e64 v51, s[54:55], v53, v54, s[50:51]
	v_cmp_eq_u32_e64 s[54:55], v41, v76
	v_cndmask_b32_e64 v40, 0, 1, s[36:37]
	s_mov_b32 s82, s38
	v_addc_co_u32_e64 v41, s[56:57], v51, v52, s[54:55]
	v_cmp_eq_u32_e64 s[56:57], v39, v76
	v_cmp_eq_u32_e64 s[38:39], v45, v76
	v_cmp_eq_u32_e64 s[42:43], v44, v76
	v_addc_co_u32_e64 v39, s[58:59], v41, v40, s[56:57]
	v_cndmask_b32_e64 v45, 0, 1, s[38:39]
	v_cmp_eq_u32_e64 s[58:59], v38, v76
	v_cndmask_b32_e64 v44, 0, 1, s[42:43]
	v_cmp_eq_u32_e64 s[44:45], v50, v76
	v_addc_co_u32_e64 v38, s[60:61], v39, v45, s[58:59]
	v_cmp_eq_u32_e64 s[60:61], v43, v76
	v_cndmask_b32_e64 v50, 0, 1, s[44:45]
	v_cmp_eq_u32_e64 s[48:49], v49, v76
	v_addc_co_u32_e64 v38, s[62:63], v38, v44, s[60:61]
	v_cmp_eq_u32_e64 s[62:63], v42, v76
	v_cndmask_b32_e64 v49, 0, 1, s[48:49]
	v_cmp_eq_u32_e64 s[52:53], v48, v76
	v_addc_co_u32_e64 v38, s[64:65], v38, v50, s[62:63]
	v_cmp_eq_u32_e64 s[64:65], v47, v76
	v_cndmask_b32_e64 v48, 0, 1, s[52:53]
	s_nop 0
	v_addc_co_u32_e64 v38, s[66:67], v38, v49, s[64:65]
	v_cmp_eq_u32_e64 s[66:67], v46, v76
	s_nop 1
	v_addc_co_u32_e64 v38, s[68:69], v38, v48, s[66:67]
	ds_bpermute_b32 v39, v100, v38
	v_cmp_lt_i32_e64 s[68:69], 0, v68
	s_waitcnt lgkmcnt(0)
; __device__ __forceinline__ void select_query(const unsigned (&u)[64], unsigned vmax, int q, int b, int lane, unsigned* MASKb) {
;     ...
;                 int incl = ec;
; #pragma unroll
;                 for (int o = 1; o < 64; o <<= 1) { const int t = __shfl_up(incl, o); if (lane >= o) incl += t; }
;                 const int total = __builtin_amdgcn_readlane(incl, 63);
;                 const int quota = rrem - tbase - (incl - ec);
;                 int taken = 0;
; #pragma unroll
;                 for (int e = 0; e < 32; ++e) { const bool is = (u[B * 32 + e] == T) && (taken < quota); w |= is ? (1u << e) : 0u; taken += is ? 1 : 0; }
	s_nop 0
	v_cndmask_b32_e64 v39, 0, v39, s[68:69]
	v_add_u32_e32 v39, v39, v38
	ds_bpermute_b32 v40, v101, v39
	v_cmp_lt_i32_e64 s[68:69], 1, v68
	v_add_u32_e32 v38, v38, v69
	s_waitcnt lgkmcnt(0)
	v_cndmask_b32_e64 v40, 0, v40, s[68:69]
	v_add_u32_e32 v39, v40, v39
	ds_bpermute_b32 v40, v102, v39
	v_cmp_lt_i32_e64 s[68:69], 3, v68
	s_waitcnt lgkmcnt(0)
	s_nop 0
	v_cndmask_b32_e64 v40, 0, v40, s[68:69]
	v_add_u32_e32 v39, v40, v39
	ds_bpermute_b32 v40, v103, v39
	v_cmp_lt_i32_e64 s[68:69], 7, v68
	s_waitcnt lgkmcnt(0)
	s_nop 0
	v_cndmask_b32_e64 v40, 0, v40, s[68:69]
	v_add_u32_e32 v39, v40, v39
	ds_bpermute_b32 v40, v104, v39
	v_cmp_lt_i32_e64 s[68:69], 15, v68
	s_waitcnt lgkmcnt(0)
	s_nop 0
	v_cndmask_b32_e64 v40, 0, v40, s[68:69]
	v_add_u32_e32 v39, v40, v39
	ds_bpermute_b32 v40, v105, v39
	v_cmp_lt_i32_e64 s[68:69], 31, v68
	s_waitcnt lgkmcnt(0)
	s_nop 0
	v_cndmask_b32_e64 v40, 0, v40, s[68:69]
	v_add3_u32 v39, v79, v39, v40
	v_sub_u32_e32 v38, v38, v39
	v_cmp_lt_i32_e64 s[68:69], 0, v38
	s_and_b64 s[66:67], s[66:67], s[68:69]
	v_cndmask_b32_e64 v39, 0, 1, s[66:67]
	v_cmp_gt_i32_e64 s[66:67], v38, v39
	s_and_b64 s[52:53], s[52:53], s[66:67]
	v_cndmask_b32_e64 v40, 0, 2, s[52:53]
	v_cndmask_b32_e64 v41, 0, 1, s[52:53]
	v_addc_co_u32_e64 v42, s[52:53], 0, v39, s[52:53]
	v_cmp_lt_i32_e64 s[52:53], v42, v38
	s_and_b64 s[52:53], s[64:65], s[52:53]
	s_nop 0
	v_cndmask_b32_e64 v42, 0, 4, s[52:53]
	v_addc_co_u32_e64 v41, s[52:53], v41, v39, s[52:53]
	v_cmp_lt_i32_e64 s[52:53], v41, v38
	s_and_b64 s[48:49], s[48:49], s[52:53]
	v_cndmask_b32_e64 v43, 0, 8, s[48:49]
	v_cndmask_b32_e64 v44, 0, 1, s[48:49]
	v_addc_co_u32_e64 v45, s[48:49], 0, v41, s[48:49]
	v_cmp_lt_i32_e64 s[48:49], v45, v38
	s_and_b64 s[48:49], s[62:63], s[48:49]
	v_or3_b32 v40, v40, v42, v43
	v_cndmask_b32_e64 v46, 0, 16, s[48:49]
	v_cndmask_b32_e64 v47, 0, 1, s[48:49]
	v_addc_co_u32_e64 v41, s[48:49], v41, v44, s[48:49]
	v_cmp_lt_i32_e64 s[48:49], v41, v38
	s_and_b64 s[44:45], s[44:45], s[48:49]
	v_cndmask_b32_e64 v44, 0, 32, s[44:45]
	v_cndmask_b32_e64 v48, 0, 1, s[44:45]
	v_addc_co_u32_e64 v45, s[44:45], v45, v47, s[44:45]
	v_cmp_lt_i32_e64 s[44:45], v45, v38
	s_and_b64 s[44:45], s[60:61], s[44:45]
	v_or3_b32 v40, v40, v46, v44
	v_cndmask_b32_e64 v47, 0, 64, s[44:45]
	v_cndmask_b32_e64 v49, 0, 1, s[44:45]
	v_addc_co_u32_e64 v41, s[44:45], v41, v48, s[44:45]
	v_cmp_lt_i32_e64 s[44:45], v41, v38
	s_and_b64 s[42:43], s[42:43], s[44:45]
	v_mov_b32_e32 v48, 0x80
	v_cndmask_b32_e64 v48, 0, v48, s[42:43]
	v_cndmask_b32_e64 v50, 0, 1, s[42:43]
	v_addc_co_u32_e64 v45, s[42:43], v45, v49, s[42:43]
	v_cmp_lt_i32_e64 s[42:43], v45, v38
	s_and_b64 s[42:43], s[58:59], s[42:43]
	v_mov_b32_e32 v49, 0x100
	v_cndmask_b32_e64 v49, 0, v49, s[42:43]
	v_cndmask_b32_e64 v51, 0, 1, s[42:43]
	v_addc_co_u32_e64 v41, s[42:43], v41, v50, s[42:43]
	v_cmp_lt_i32_e64 s[42:43], v41, v38
	s_and_b64 s[38:39], s[38:39], s[42:43]
	v_mov_b32_e32 v50, 0x200
	v_cndmask_b32_e64 v50, 0, v50, s[38:39]
	v_cndmask_b32_e64 v52, 0, 1, s[38:39]
	v_addc_co_u32_e64 v45, s[38:39], v45, v51, s[38:39]
	v_cmp_lt_i32_e64 s[38:39], v45, v38
	s_and_b64 s[38:39], s[56:57], s[38:39]
	v_mov_b32_e32 v51, 0x400
	v_cndmask_b32_e64 v51, 0, v51, s[38:39]
	v_cndmask_b32_e64 v53, 0, 1, s[38:39]
	v_addc_co_u32_e64 v41, s[38:39], v41, v52, s[38:39]
	v_cmp_lt_i32_e64 s[38:39], v41, v38
	s_and_b64 s[36:37], s[36:37], s[38:39]
	v_mov_b32_e32 v52, 0x800
	v_cndmask_b32_e64 v52, 0, v52, s[36:37]
	v_cndmask_b32_e64 v54, 0, 1, s[36:37]
	v_addc_co_u32_e64 v45, s[36:37], v45, v53, s[36:37]
	v_cmp_lt_i32_e64 s[36:37], v45, v38
	s_and_b64 s[36:37], s[54:55], s[36:37]
	v_mov_b32_e32 v53, 0x1000
	v_cndmask_b32_e64 v53, 0, v53, s[36:37]
	v_cndmask_b32_e64 v55, 0, 1, s[36:37]
	v_addc_co_u32_e64 v41, s[36:37], v41, v54, s[36:37]
	v_cmp_lt_i32_e64 s[36:37], v41, v38
	s_and_b64 s[30:31], s[30:31], s[36:37]
	v_cndmask_b32_e64 v54, 0, v240, s[30:31]
	v_cndmask_b32_e64 v56, 0, 1, s[30:31]
	v_addc_co_u32_e64 v45, s[30:31], v45, v55, s[30:31]
	v_cmp_lt_i32_e64 s[30:31], v45, v38
	s_and_b64 s[30:31], s[50:51], s[30:31]
	v_mov_b32_e32 v55, 0x4000
	v_cndmask_b32_e64 v55, 0, v55, s[30:31]
	v_cndmask_b32_e64 v57, 0, 1, s[30:31]
	v_addc_co_u32_e64 v41, s[30:31], v41, v56, s[30:31]
; __device__ __forceinline__ void select_query(const unsigned (&u)[64], unsigned vmax, int q, int b, int lane, unsigned* MASKb) {
;     ...
;                 const int quota = rrem - tbase - (incl - ec);
;                 int taken = 0;
; #pragma unroll
;                 for (int e = 0; e < 32; ++e) { const bool is = (u[B * 32 + e] == T) && (taken < quota); w |= is ? (1u << e) : 0u; taken += is ? 1 : 0; }
;                 tbase += total;
	v_cmp_lt_i32_e64 s[30:31], v41, v38
	s_and_b64 s[28:29], s[28:29], s[30:31]
	v_mov_b32_e32 v56, 0x8000
	v_cndmask_b32_e64 v56, 0, v56, s[28:29]
	v_cndmask_b32_e64 v58, 0, 1, s[28:29]
	v_addc_co_u32_e64 v45, s[28:29], v45, v57, s[28:29]
	v_cmp_lt_i32_e64 s[28:29], v45, v38
	s_and_b64 s[28:29], s[46:47], s[28:29]
	v_mov_b32_e32 v57, 0x10000
	v_cndmask_b32_e64 v57, 0, v57, s[28:29]
	v_cndmask_b32_e64 v59, 0, 1, s[28:29]
	v_addc_co_u32_e64 v41, s[28:29], v41, v58, s[28:29]
	v_cmp_lt_i32_e64 s[28:29], v41, v38
	s_and_b64 s[24:25], s[24:25], s[28:29]
	v_mov_b32_e32 v58, 0x20000
	v_cndmask_b32_e64 v58, 0, v58, s[24:25]
	v_cndmask_b32_e64 v60, 0, 1, s[24:25]
	v_addc_co_u32_e64 v45, s[24:25], v45, v59, s[24:25]
	v_cmp_lt_i32_e64 s[24:25], v45, v38
	s_and_b64 s[24:25], s[40:41], s[24:25]
	v_mov_b32_e32 v59, 0x40000
	v_cndmask_b32_e64 v59, 0, v59, s[24:25]
	v_cndmask_b32_e64 v61, 0, 1, s[24:25]
	v_addc_co_u32_e64 v41, s[24:25], v41, v60, s[24:25]
	v_cmp_lt_i32_e64 s[24:25], v41, v38
	s_and_b64 s[20:21], s[20:21], s[24:25]
	v_mov_b32_e32 v60, 0x80000
	v_cndmask_b32_e64 v60, 0, v60, s[20:21]
	v_cndmask_b32_e64 v62, 0, 1, s[20:21]
	v_addc_co_u32_e64 v45, s[20:21], v45, v61, s[20:21]
	v_cmp_lt_i32_e64 s[20:21], v45, v38
	s_and_b64 s[20:21], s[34:35], s[20:21]
	v_mov_b32_e32 v61, 0x100000
	v_cndmask_b32_e64 v61, 0, v61, s[20:21]
	v_cndmask_b32_e64 v63, 0, 1, s[20:21]
	v_addc_co_u32_e64 v41, s[20:21], v41, v62, s[20:21]
	v_cmp_lt_i32_e64 s[20:21], v41, v38
	s_and_b64 s[18:19], s[18:19], s[20:21]
	v_mov_b32_e32 v62, 0x200000
	v_cndmask_b32_e64 v62, 0, v62, s[18:19]
	v_cndmask_b32_e64 v64, 0, 1, s[18:19]
	v_addc_co_u32_e64 v45, s[18:19], v45, v63, s[18:19]
	v_cmp_lt_i32_e64 s[18:19], v45, v38
	s_and_b64 s[18:19], s[26:27], s[18:19]
	v_mov_b32_e32 v63, 0x400000
	v_cndmask_b32_e64 v63, 0, v63, s[18:19]
	v_cndmask_b32_e64 v65, 0, 1, s[18:19]
	v_addc_co_u32_e64 v41, s[18:19], v41, v64, s[18:19]
	v_cmp_lt_i32_e64 s[18:19], v41, v38
	s_and_b64 s[14:15], s[14:15], s[18:19]
	v_mov_b32_e32 v64, 0x800000
	v_cndmask_b32_e64 v64, 0, v64, s[14:15]
	v_cndmask_b32_e64 v69, 0, 1, s[14:15]
	v_addc_co_u32_e64 v45, s[14:15], v45, v65, s[14:15]
	v_cmp_lt_i32_e64 s[14:15], v45, v38
	s_and_b64 s[14:15], s[22:23], s[14:15]
	v_mov_b32_e32 v65, 0x1000000
	v_cndmask_b32_e64 v65, 0, v65, s[14:15]
	v_cndmask_b32_e64 v72, 0, 1, s[14:15]
	v_addc_co_u32_e64 v41, s[14:15], v41, v69, s[14:15]
	v_cmp_lt_i32_e64 s[14:15], v41, v38
	s_and_b64 s[12:13], s[12:13], s[14:15]
	v_bfrev_b32_e32 v69, 64
	v_cndmask_b32_e64 v69, 0, v69, s[12:13]
	v_cndmask_b32_e64 v73, 0, 1, s[12:13]
	v_addc_co_u32_e64 v45, s[12:13], v45, v72, s[12:13]
	v_cmp_lt_i32_e64 s[12:13], v45, v38
	s_and_b64 s[12:13], s[16:17], s[12:13]
	v_bfrev_b32_e32 v72, 32
	v_cndmask_b32_e64 v72, 0, v72, s[12:13]
	v_cndmask_b32_e64 v74, 0, 1, s[12:13]
	v_addc_co_u32_e64 v41, s[12:13], v41, v73, s[12:13]
	v_cmp_lt_i32_e64 s[12:13], v41, v38
	s_and_b64 s[8:9], s[8:9], s[12:13]
	v_bfrev_b32_e32 v73, 16
	v_cndmask_b32_e64 v73, 0, v73, s[8:9]
	v_cndmask_b32_e64 v75, 0, 1, s[8:9]
	v_addc_co_u32_e64 v45, s[8:9], v45, v74, s[8:9]
	v_cmp_lt_i32_e64 s[8:9], v45, v38
	v_or3_b32 v40, v40, v47, v48
	s_and_b64 s[8:9], s[10:11], s[8:9]
	v_bfrev_b32_e32 v74, 8
	v_or3_b32 v40, v40, v49, v50
	v_cndmask_b32_e64 v74, 0, v74, s[8:9]
	v_cndmask_b32_e64 v76, 0, 1, s[8:9]
	v_addc_co_u32_e64 v41, s[8:9], v41, v75, s[8:9]
	v_or3_b32 v40, v40, v51, v52
	v_cmp_lt_i32_e64 s[8:9], v41, v38
	v_or3_b32 v40, v40, v53, v54
	s_and_b64 s[4:5], s[4:5], s[8:9]
	v_bfrev_b32_e32 v75, 4
	v_or3_b32 v40, v40, v55, v56
	v_cndmask_b32_e64 v75, 0, v75, s[4:5]
	v_cndmask_b32_e64 v77, 0, 1, s[4:5]
	v_addc_co_u32_e64 v45, s[4:5], v45, v76, s[4:5]
	v_or3_b32 v40, v40, v57, v58
	v_cmp_lt_i32_e64 s[4:5], v45, v38
	v_or3_b32 v40, v40, v59, v60
	s_and_b64 s[4:5], s[6:7], s[4:5]
	v_or3_b32 v40, v40, v61, v62
	v_cndmask_b32_e64 v45, 0, 2.0, s[4:5]
	v_addc_co_u32_e64 v41, s[4:5], v41, v77, s[4:5]
	v_or3_b32 v40, v40, v63, v64
	v_cmp_lt_i32_e64 s[4:5], v41, v38
	v_or3_b32 v40, v40, v65, v69
	s_and_b64 vcc, vcc, s[4:5]
	v_bfrev_b32_e32 v38, 1
	v_or3_b32 v40, v40, v72, v73
	v_cndmask_b32_e32 v38, 0, v38, vcc
	v_or3_b32 v40, v40, v74, v75
	v_or3_b32 v38, v40, v45, v38
	s_mov_b32 s38, s82
	v_or3_b32 v0, v38, v39, v0

; #define PG8_STAGE(bufoff, gbase, voff) do { _Pragma("unroll") for (int _i = 0; _i < 2; ++_i) \
;         __builtin_amdgcn_global_load_lds((const unsigned*)((const char*)(gbase) + (voff)[_i]), (PG8_LAS unsigned*)(lds + (bufoff) + ldsw + _i * 8192), 16, 0, 0); } while (0)
; #define PG8_LDA(dst, b, h) do { _Pragma("unroll") for (int m = 0; m < 4; ++m) _Pragma("unroll") for (int k = 0; k < 2; ++k) dst[m][k] = *(const PG8_LAS bf16x8*)(lds + PG8_SA(b, h) + aoff + m * 2048 + k * 1024); } while (0)
; #define PG8_LDB(dst, b, h) do { _Pragma("unroll") for (int n = 0; n < 2; ++n) _Pragma("unroll") for (int k = 0; k < 2; ++k) dst[n][k] = *(const PG8_LAS bf16x8*)(lds + PG8_SB(b, h) + boff + n * 2048 + k * 1024); } while (0)
; #define PG8_MMA(ai, bj, At, Bt) do { __builtin_amdgcn_s_setprio(1); _Pragma("unroll") for (int m = 0; m < 4; ++m) _Pragma("unroll") for (int n = 0; n < 2; ++n) _Pragma("unroll") for (int k = 0; k < 2; ++k) \
;         acc[ai][bj][m][n] = __builtin_amdgcn_mfma_f32_16x16x32_bf16(Bt[n][k], At[m][k], acc[ai][bj][m][n], 0, 0, 0); __builtin_amdgcn_s_setprio(0); } while (0)
; #define PG8_WAIT_V(n) asm volatile("s_waitcnt vmcnt(" #n ")" ::: "memory")
; #define PG8_WAIT_L(n) asm volatile("s_waitcnt lgkmcnt(" #n ")" ::: "memory")
; template <class Epi, class Sched, bool ALIGN_EPI = false, bool SP2 = false>
; __device__ __forceinline__ void gemm_phase(PG8_LAS unsigned char* lds, const Gemm g, const Sched& S, const Epi& E, int tid_in) {
;     ...
;             const bool last = (t == nt - 2);
;             const char* a1 = cA + (size_t)(t + 1) * kstep;
;             const char* a2 = last ? nA : cA + (size_t)(t + 2) * kstep; const char* b2 = last ? nB : cB + (size_t)(t + 2) * kstep;
;             const char* a3 = a2 + kstep; const char* b3 = b2 + kstep;
;             if (last && has_next) S.a_ready(nxt);
;             if constexpr (SP2) {
;             PG8_LDB(B0, 0, 0); PG8_LDB(B1, 0, 1); PG8_SCHED; PG8_LDA(At, 0, 0); PG8_STAGE(PG8_SA(1, 1), a1 + hstep, voffA);
;             PG8_WAIT_V(8); PG8_WAIT_L(0); PG8_BAR; PG8_MMA(0, 0, At, B0); PG8_MMA(0, 1, At, B1); PG8_BAR; PG8_SCHED;
;             PG8_LDA(At, 0, 1); PG8_STAGE(PG8_SB(0, 0), b2, voffB); PG8_STAGE(PG8_SB(0, 1), b2 + hstep, voffB); PG8_STAGE(PG8_SA(0, 0), a2, voffA);
;             PG8_WAIT_V(8); PG8_WAIT_L(0); PG8_BAR; PG8_MMA(1, 0, At, B0); PG8_MMA(1, 1, At, B1); PG8_BAR; PG8_SCHED;
.LBB0_269:
	s_add_u32 s26, s24, 0xfffc0080
	s_addc_u32 s27, s25, -1
	s_add_i32 s51, 0, 0x10000
	s_cmp_eq_u32 s50, 12
	s_cselect_b32 s29, s17, s27
	s_cselect_b32 s28, s46, s26
	v_add_u32_e32 v148, s51, v153
	s_cselect_b32 s27, s15, s49
	s_cselect_b32 s26, s47, s48
	s_add_i32 s54, 0, 0x14000
	ds_read_b128 v[144:147], v148
	ds_read_b128 v[158:161], v148 offset:1024
	ds_read_b128 v[168:171], v148 offset:2048
	ds_read_b128 v[172:175], v148 offset:3072
	v_add_u32_e32 v148, s54, v153
	ds_read_b128 v[182:185], v148
	ds_read_b128 v[186:189], v148 offset:1024
	ds_read_b128 v[190:193], v148 offset:2048
	ds_read_b128 v[198:201], v148 offset:3072
	v_lshl_add_u64 v[150:151], s[24:25], 0, v[140:141]
	s_add_i32 m0, s38, 0xc000
	ds_read_b128 v[202:205], v157
	ds_read_b128 v[206:209], v157 offset:1024
	ds_read_b128 v[210:213], v157 offset:2048
	ds_read_b128 v[220:223], v157 offset:3072
	ds_read_b128 v[224:227], v157 offset:4096
	ds_read_b128 v[228:231], v157 offset:5120
	ds_read_b128 v[232:235], v157 offset:6144
	ds_read_b128 v[248:251], v157 offset:7168
	global_load_lds_dwordx4 v[150:151], off
	v_lshl_add_u64 v[150:151], s[24:25], 0, v[142:143]
	s_add_i32 m0, s38, 0xe000
	s_nop 0
	global_load_lds_dwordx4 v[150:151], off
	s_waitcnt vmcnt(8) lgkmcnt(0)
	s_barrier
	s_setprio 1
	v_mfma_f32_16x16x32_bf16 v[126:129], v[144:147], v[202:205], v[126:129]
	v_mfma_f32_16x16x32_bf16 v[118:121], v[168:171], v[202:205], v[118:121]
	v_mfma_f32_16x16x32_bf16 v[110:113], v[144:147], v[210:213], v[110:113]
	v_mfma_f32_16x16x32_bf16 v[102:105], v[168:171], v[210:213], v[102:105]
	v_mfma_f32_16x16x32_bf16 v[94:97], v[144:147], v[224:227], v[94:97]
	v_mfma_f32_16x16x32_bf16 v[86:89], v[168:171], v[224:227], v[86:89]
	v_mfma_f32_16x16x32_bf16 v[78:81], v[144:147], v[232:235], v[78:81]
	v_mfma_f32_16x16x32_bf16 v[70:73], v[168:171], v[232:235], v[70:73]
	v_mfma_f32_16x16x32_bf16 v[126:129], v[158:161], v[206:209], v[126:129]
	v_mfma_f32_16x16x32_bf16 v[118:121], v[172:175], v[206:209], v[118:121]
	v_mfma_f32_16x16x32_bf16 v[110:113], v[158:161], v[220:223], v[110:113]
	v_mfma_f32_16x16x32_bf16 v[102:105], v[172:175], v[220:223], v[102:105]
	v_mfma_f32_16x16x32_bf16 v[94:97], v[158:161], v[228:231], v[94:97]
	v_mfma_f32_16x16x32_bf16 v[86:89], v[172:175], v[228:231], v[86:89]
	v_mfma_f32_16x16x32_bf16 v[78:81], v[158:161], v[248:251], v[78:81]
	v_mfma_f32_16x16x32_bf16 v[70:73], v[172:175], v[248:251], v[70:73]
	v_mfma_f32_16x16x32_bf16 v[122:125], v[182:185], v[202:205], v[122:125]
	v_mfma_f32_16x16x32_bf16 v[114:117], v[190:193], v[202:205], v[114:117]
	v_mfma_f32_16x16x32_bf16 v[106:109], v[182:185], v[210:213], v[106:109]
	v_mfma_f32_16x16x32_bf16 v[98:101], v[190:193], v[210:213], v[98:101]
	v_mfma_f32_16x16x32_bf16 v[90:93], v[182:185], v[224:227], v[90:93]
	v_mfma_f32_16x16x32_bf16 v[82:85], v[190:193], v[224:227], v[82:85]
	v_mfma_f32_16x16x32_bf16 v[74:77], v[182:185], v[232:235], v[74:77]
	v_mfma_f32_16x16x32_bf16 v[66:69], v[190:193], v[232:235], v[66:69]
	v_mfma_f32_16x16x32_bf16 v[122:125], v[186:189], v[206:209], v[122:125]
	v_mfma_f32_16x16x32_bf16 v[114:117], v[198:201], v[206:209], v[114:117]
	v_mfma_f32_16x16x32_bf16 v[106:109], v[186:189], v[220:223], v[106:109]
	v_mfma_f32_16x16x32_bf16 v[98:101], v[198:201], v[220:223], v[98:101]
	v_mfma_f32_16x16x32_bf16 v[90:93], v[186:189], v[228:231], v[90:93]
	v_mfma_f32_16x16x32_bf16 v[82:85], v[198:201], v[228:231], v[82:85]
	v_mfma_f32_16x16x32_bf16 v[74:77], v[186:189], v[248:251], v[74:77]
	v_mfma_f32_16x16x32_bf16 v[66:69], v[198:201], v[248:251], v[66:69]
	s_setprio 0
	s_barrier
	s_add_i32 s51, s51, s36
	v_lshl_add_u64 v[150:151], s[26:27], 0, v[134:135]
	s_mov_b32 m0, s51
	ds_read_b128 v[202:205], v157 offset:16384
	ds_read_b128 v[206:209], v157 offset:17408
	ds_read_b128 v[210:213], v157 offset:18432
	ds_read_b128 v[220:223], v157 offset:19456
	ds_read_b128 v[224:227], v157 offset:20480
	ds_read_b128 v[228:231], v157 offset:21504
	ds_read_b128 v[232:235], v157 offset:22528
	ds_read_b128 v[248:251], v157 offset:23552
	global_load_lds_dwordx4 v[150:151], off
	s_add_i32 m0, s51, 0x2000
	s_add_u32 s52, s26, 0x40000
	v_lshl_add_u64 v[154:155], s[26:27], 0, v[130:131]
	s_addc_u32 s53, s27, 0
	s_add_i32 s51, s54, s36
	global_load_lds_dwordx4 v[154:155], off
	v_lshl_add_u64 v[176:177], s[52:53], 0, v[134:135]
	s_mov_b32 m0, s51
	v_lshl_add_u64 v[194:195], s[28:29], 0, v[132:133]
	global_load_lds_dwordx4 v[176:177], off
	v_lshl_add_u64 v[176:177], s[52:53], 0, v[130:131]
	s_add_i32 m0, s51, 0x2000
	s_nop 0
	global_load_lds_dwordx4 v[176:177], off
	v_lshl_add_u64 v[176:177], s[28:29], 0, v[136:137]
	s_mov_b32 m0, s38
	s_nop 0
	global_load_lds_dwordx4 v[176:177], off
	s_mov_b32 m0, s39
	s_nop 0
	global_load_lds_dwordx4 v[194:195], off
	s_waitcnt vmcnt(8) lgkmcnt(0)
	s_barrier
; #define PG8_STAGE(bufoff, gbase, voff) do { _Pragma("unroll") for (int _i = 0; _i < 2; ++_i) \
;         __builtin_amdgcn_global_load_lds((const unsigned*)((const char*)(gbase) + (voff)[_i]), (PG8_LAS unsigned*)(lds + (bufoff) + ldsw + _i * 8192), 16, 0, 0); } while (0)
; #define PG8_LDA(dst, b, h) do { _Pragma("unroll") for (int m = 0; m < 4; ++m) _Pragma("unroll") for (int k = 0; k < 2; ++k) dst[m][k] = *(const PG8_LAS bf16x8*)(lds + PG8_SA(b, h) + aoff + m * 2048 + k * 1024); } while (0)
; #define PG8_LDB(dst, b, h) do { _Pragma("unroll") for (int n = 0; n < 2; ++n) _Pragma("unroll") for (int k = 0; k < 2; ++k) dst[n][k] = *(const PG8_LAS bf16x8*)(lds + PG8_SB(b, h) + boff + n * 2048 + k * 1024); } while (0)
; #define PG8_MMA(ai, bj, At, Bt) do { __builtin_amdgcn_s_setprio(1); _Pragma("unroll") for (int m = 0; m < 4; ++m) _Pragma("unroll") for (int n = 0; n < 2; ++n) _Pragma("unroll") for (int k = 0; k < 2; ++k) \
;         acc[ai][bj][m][n] = __builtin_amdgcn_mfma_f32_16x16x32_bf16(Bt[n][k], At[m][k], acc[ai][bj][m][n], 0, 0, 0); __builtin_amdgcn_s_setprio(0); } while (0)
; #define PG8_WAIT_V(n) asm volatile("s_waitcnt vmcnt(" #n ")" ::: "memory")
; #define PG8_WAIT_L(n) asm volatile("s_waitcnt lgkmcnt(" #n ")" ::: "memory")
; #define PG8_BAR __builtin_amdgcn_s_barrier()
; #define PG8_SCHED __builtin_amdgcn_sched_barrier(0)
; template <class Epi, class Sched, bool ALIGN_EPI = false, bool SP2 = false>
; __device__ __forceinline__ void gemm_phase(PG8_LAS unsigned char* lds, const Gemm g, const Sched& S, const Epi& E, int tid_in) {
;     ...
;             PG8_WAIT_V(8); PG8_WAIT_L(0); PG8_BAR; PG8_MMA(1, 0, At, B0); PG8_MMA(1, 1, At, B1); PG8_BAR; PG8_SCHED;
;             PG8_LDB(B0, 1, 0); PG8_LDB(B1, 1, 1); PG8_SCHED; PG8_LDA(At, 1, 0); PG8_STAGE(PG8_SA(0, 1), a2 + hstep, voffA);
;             PG8_WAIT_V(8); PG8_WAIT_L(0); PG8_BAR; PG8_MMA(0, 0, At, B0); PG8_MMA(0, 1, At, B1); PG8_BAR; PG8_SCHED;
	s_setprio 1
	v_mfma_f32_16x16x32_bf16 v[62:65], v[144:147], v[202:205], v[62:65]
	v_mfma_f32_16x16x32_bf16 v[54:57], v[168:171], v[202:205], v[54:57]
	v_mfma_f32_16x16x32_bf16 v[46:49], v[144:147], v[210:213], v[46:49]
	v_mfma_f32_16x16x32_bf16 v[38:41], v[168:171], v[210:213], v[38:41]
	v_mfma_f32_16x16x32_bf16 v[30:33], v[144:147], v[224:227], v[30:33]
	v_mfma_f32_16x16x32_bf16 v[22:25], v[168:171], v[224:227], v[22:25]
	v_mfma_f32_16x16x32_bf16 v[14:17], v[144:147], v[232:235], v[14:17]
	v_mfma_f32_16x16x32_bf16 v[6:9], v[168:171], v[232:235], v[6:9]
	v_mfma_f32_16x16x32_bf16 v[62:65], v[158:161], v[206:209], v[62:65]
	v_mfma_f32_16x16x32_bf16 v[54:57], v[172:175], v[206:209], v[54:57]
	v_mfma_f32_16x16x32_bf16 v[46:49], v[158:161], v[220:223], v[46:49]
	v_mfma_f32_16x16x32_bf16 v[38:41], v[172:175], v[220:223], v[38:41]
	v_mfma_f32_16x16x32_bf16 v[30:33], v[158:161], v[228:231], v[30:33]
	v_mfma_f32_16x16x32_bf16 v[22:25], v[172:175], v[228:231], v[22:25]
	v_mfma_f32_16x16x32_bf16 v[14:17], v[158:161], v[248:251], v[14:17]
	v_mfma_f32_16x16x32_bf16 v[6:9], v[172:175], v[248:251], v[6:9]
	v_mfma_f32_16x16x32_bf16 v[58:61], v[182:185], v[202:205], v[58:61]
	v_mfma_f32_16x16x32_bf16 v[50:53], v[190:193], v[202:205], v[50:53]
	v_mfma_f32_16x16x32_bf16 v[42:45], v[182:185], v[210:213], v[42:45]
	v_mfma_f32_16x16x32_bf16 v[34:37], v[190:193], v[210:213], v[34:37]
	v_mfma_f32_16x16x32_bf16 v[26:29], v[182:185], v[224:227], v[26:29]
	v_mfma_f32_16x16x32_bf16 v[18:21], v[190:193], v[224:227], v[18:21]
	v_mfma_f32_16x16x32_bf16 v[10:13], v[182:185], v[232:235], v[10:13]
	v_mfma_f32_16x16x32_bf16 v[2:5], v[190:193], v[232:235], v[2:5]
	v_mfma_f32_16x16x32_bf16 v[58:61], v[186:189], v[206:209], v[58:61]
	v_mfma_f32_16x16x32_bf16 v[50:53], v[198:201], v[206:209], v[50:53]
	v_mfma_f32_16x16x32_bf16 v[42:45], v[186:189], v[220:223], v[42:45]
	v_mfma_f32_16x16x32_bf16 v[34:37], v[198:201], v[220:223], v[34:37]
	v_mfma_f32_16x16x32_bf16 v[26:29], v[186:189], v[228:231], v[26:29]
	v_mfma_f32_16x16x32_bf16 v[18:21], v[198:201], v[228:231], v[18:21]
	v_mfma_f32_16x16x32_bf16 v[10:13], v[186:189], v[248:251], v[10:13]
	v_mfma_f32_16x16x32_bf16 v[2:5], v[198:201], v[248:251], v[2:5]
	s_setprio 0
	s_barrier
	s_add_i32 s51, 0, 0x18000
	v_add_u32_e32 v148, s51, v153
	s_add_i32 s52, 0, 0x1c000
	ds_read_b128 v[144:147], v148
	ds_read_b128 v[158:161], v148 offset:1024
	ds_read_b128 v[168:171], v148 offset:2048
	ds_read_b128 v[172:175], v148 offset:3072
	v_add_u32_e32 v148, s52, v153
	ds_read_b128 v[182:185], v148
	ds_read_b128 v[186:189], v148 offset:1024
	ds_read_b128 v[190:193], v148 offset:2048
	ds_read_b128 v[198:201], v148 offset:3072
	s_add_u32 s28, s28, 0x40000
	s_addc_u32 s29, s29, 0
	s_mov_b32 m0, s40
	v_lshl_add_u64 v[214:215], s[28:29], 0, v[136:137]
	ds_read_b128 v[202:205], v157 offset:32768
	ds_read_b128 v[206:209], v157 offset:33792
	ds_read_b128 v[210:213], v157 offset:34816
	ds_read_b128 v[220:223], v157 offset:35840
	ds_read_b128 v[224:227], v157 offset:36864
	ds_read_b128 v[228:231], v157 offset:37888
	ds_read_b128 v[232:235], v157 offset:38912
	ds_read_b128 v[248:251], v157 offset:39936
	global_load_lds_dwordx4 v[214:215], off
	v_lshl_add_u64 v[214:215], s[28:29], 0, v[132:133]
	s_mov_b32 m0, s41
	s_nop 0
	global_load_lds_dwordx4 v[214:215], off
	s_waitcnt vmcnt(8) lgkmcnt(0)
	s_barrier
	s_setprio 1
	v_mfma_f32_16x16x32_bf16 v[126:129], v[144:147], v[202:205], v[126:129]
	v_mfma_f32_16x16x32_bf16 v[118:121], v[168:171], v[202:205], v[118:121]
	v_mfma_f32_16x16x32_bf16 v[110:113], v[144:147], v[210:213], v[110:113]
	v_mfma_f32_16x16x32_bf16 v[102:105], v[168:171], v[210:213], v[102:105]
	v_mfma_f32_16x16x32_bf16 v[94:97], v[144:147], v[224:227], v[94:97]
	v_mfma_f32_16x16x32_bf16 v[86:89], v[168:171], v[224:227], v[86:89]
	v_mfma_f32_16x16x32_bf16 v[78:81], v[144:147], v[232:235], v[78:81]
	v_mfma_f32_16x16x32_bf16 v[70:73], v[168:171], v[232:235], v[70:73]
	v_mfma_f32_16x16x32_bf16 v[126:129], v[158:161], v[206:209], v[126:129]
	v_mfma_f32_16x16x32_bf16 v[118:121], v[172:175], v[206:209], v[118:121]
	v_mfma_f32_16x16x32_bf16 v[110:113], v[158:161], v[220:223], v[110:113]
	v_mfma_f32_16x16x32_bf16 v[102:105], v[172:175], v[220:223], v[102:105]
	v_mfma_f32_16x16x32_bf16 v[94:97], v[158:161], v[228:231], v[94:97]
	v_mfma_f32_16x16x32_bf16 v[86:89], v[172:175], v[228:231], v[86:89]
	v_mfma_f32_16x16x32_bf16 v[78:81], v[158:161], v[248:251], v[78:81]
	v_mfma_f32_16x16x32_bf16 v[70:73], v[172:175], v[248:251], v[70:73]
	v_mfma_f32_16x16x32_bf16 v[122:125], v[182:185], v[202:205], v[122:125]
	v_mfma_f32_16x16x32_bf16 v[114:117], v[190:193], v[202:205], v[114:117]
	v_mfma_f32_16x16x32_bf16 v[106:109], v[182:185], v[210:213], v[106:109]
	v_mfma_f32_16x16x32_bf16 v[98:101], v[190:193], v[210:213], v[98:101]
	v_mfma_f32_16x16x32_bf16 v[90:93], v[182:185], v[224:227], v[90:93]
	v_mfma_f32_16x16x32_bf16 v[82:85], v[190:193], v[224:227], v[82:85]
	v_mfma_f32_16x16x32_bf16 v[74:77], v[182:185], v[232:235], v[74:77]
	v_mfma_f32_16x16x32_bf16 v[66:69], v[190:193], v[232:235], v[66:69]
	v_mfma_f32_16x16x32_bf16 v[122:125], v[186:189], v[206:209], v[122:125]
	v_mfma_f32_16x16x32_bf16 v[114:117], v[198:201], v[206:209], v[114:117]
	v_mfma_f32_16x16x32_bf16 v[106:109], v[186:189], v[220:223], v[106:109]
	v_mfma_f32_16x16x32_bf16 v[98:101], v[198:201], v[220:223], v[98:101]
	v_mfma_f32_16x16x32_bf16 v[90:93], v[186:189], v[228:231], v[90:93]
	v_mfma_f32_16x16x32_bf16 v[82:85], v[198:201], v[228:231], v[82:85]
	v_mfma_f32_16x16x32_bf16 v[74:77], v[186:189], v[248:251], v[74:77]
	v_mfma_f32_16x16x32_bf16 v[66:69], v[198:201], v[248:251], v[66:69]
	s_setprio 0
	s_barrier
; #define PG8_STAGE(bufoff, gbase, voff) do { _Pragma("unroll") for (int _i = 0; _i < 2; ++_i) \
;         __builtin_amdgcn_global_load_lds((const unsigned*)((const char*)(gbase) + (voff)[_i]), (PG8_LAS unsigned*)(lds + (bufoff) + ldsw + _i * 8192), 16, 0, 0); } while (0)
; #define PG8_LDA(dst, b, h) do { _Pragma("unroll") for (int m = 0; m < 4; ++m) _Pragma("unroll") for (int k = 0; k < 2; ++k) dst[m][k] = *(const PG8_LAS bf16x8*)(lds + PG8_SA(b, h) + aoff + m * 2048 + k * 1024); } while (0)
; #define PG8_MMA(ai, bj, At, Bt) do { __builtin_amdgcn_s_setprio(1); _Pragma("unroll") for (int m = 0; m < 4; ++m) _Pragma("unroll") for (int n = 0; n < 2; ++n) _Pragma("unroll") for (int k = 0; k < 2; ++k) \
;         acc[ai][bj][m][n] = __builtin_amdgcn_mfma_f32_16x16x32_bf16(Bt[n][k], At[m][k], acc[ai][bj][m][n], 0, 0, 0); __builtin_amdgcn_s_setprio(0); } while (0)
; #define PG8_WAIT_V(n) asm volatile("s_waitcnt vmcnt(" #n ")" ::: "memory")
; #define PG8_WAIT_L(n) asm volatile("s_waitcnt lgkmcnt(" #n ")" ::: "memory")
; #define PG8_BAR __builtin_amdgcn_s_barrier()
; #define PG8_SCHED __builtin_amdgcn_sched_barrier(0)
; template <class Epi, class Sched, bool ALIGN_EPI = false, bool SP2 = false>
; __device__ __forceinline__ void gemm_phase(PG8_LAS unsigned char* lds, const Gemm g, const Sched& S, const Epi& E, int tid_in) {
;     ...
;             PG8_LDA(At, 1, 1); PG8_STAGE(PG8_SB(1, 0), b3, voffB); PG8_STAGE(PG8_SB(1, 1), b3 + hstep, voffB); PG8_STAGE(PG8_SA(1, 0), a3, voffA);
;             PG8_WAIT_V(8); PG8_WAIT_L(0); PG8_BAR; PG8_MMA(1, 0, At, B0); PG8_MMA(1, 1, At, B1); PG8_BAR; PG8_SCHED;
;     ...
;         if constexpr (ALIGN_EPI) { if (wr == 0) PG8_BAR; }
	s_add_i32 s28, s51, s36
	v_lshl_add_u64 v[150:151], v[150:151], 0, s[92:93]
	s_mov_b32 m0, s28
	ds_read_b128 v[202:205], v157 offset:49152
	ds_read_b128 v[206:209], v157 offset:50176
	ds_read_b128 v[210:213], v157 offset:51200
	ds_read_b128 v[220:223], v157 offset:52224
	ds_read_b128 v[224:227], v157 offset:53248
	ds_read_b128 v[228:231], v157 offset:54272
	ds_read_b128 v[232:235], v157 offset:55296
	ds_read_b128 v[248:251], v157 offset:56320
	global_load_lds_dwordx4 v[150:151], off
	s_add_i32 m0, s28, 0x2000
	s_add_u32 s26, s26, 0x40080
	v_lshl_add_u64 v[150:151], v[154:155], 0, s[92:93]
	s_addc_u32 s27, s27, 0
	s_add_i32 s28, s52, s36
	global_load_lds_dwordx4 v[150:151], off
	v_lshl_add_u64 v[150:151], s[26:27], 0, v[134:135]
	s_mov_b32 m0, s28
	s_nop 0
	global_load_lds_dwordx4 v[150:151], off
	v_lshl_add_u64 v[150:151], s[26:27], 0, v[130:131]
	s_add_i32 m0, s28, 0x2000
	s_nop 0
	global_load_lds_dwordx4 v[150:151], off
	v_lshl_add_u64 v[150:151], v[176:177], 0, s[92:93]
	s_mov_b32 m0, s42
	s_nop 0
	global_load_lds_dwordx4 v[150:151], off
	v_lshl_add_u64 v[150:151], v[194:195], 0, s[92:93]
	s_mov_b32 m0, s43
	s_nop 0
	global_load_lds_dwordx4 v[150:151], off
	s_waitcnt vmcnt(8) lgkmcnt(0)
	s_barrier
	s_setprio 1
	v_mfma_f32_16x16x32_bf16 v[62:65], v[144:147], v[202:205], v[62:65]
	v_mfma_f32_16x16x32_bf16 v[54:57], v[168:171], v[202:205], v[54:57]
	v_mfma_f32_16x16x32_bf16 v[46:49], v[144:147], v[210:213], v[46:49]
	v_mfma_f32_16x16x32_bf16 v[38:41], v[168:171], v[210:213], v[38:41]
	v_mfma_f32_16x16x32_bf16 v[30:33], v[144:147], v[224:227], v[30:33]
	v_mfma_f32_16x16x32_bf16 v[22:25], v[168:171], v[224:227], v[22:25]
	v_mfma_f32_16x16x32_bf16 v[14:17], v[144:147], v[232:235], v[14:17]
	v_mfma_f32_16x16x32_bf16 v[6:9], v[168:171], v[232:235], v[6:9]
	v_mfma_f32_16x16x32_bf16 v[62:65], v[158:161], v[206:209], v[62:65]
	v_mfma_f32_16x16x32_bf16 v[54:57], v[172:175], v[206:209], v[54:57]
	v_mfma_f32_16x16x32_bf16 v[46:49], v[158:161], v[220:223], v[46:49]
	v_mfma_f32_16x16x32_bf16 v[38:41], v[172:175], v[220:223], v[38:41]
	v_mfma_f32_16x16x32_bf16 v[30:33], v[158:161], v[228:231], v[30:33]
	v_mfma_f32_16x16x32_bf16 v[22:25], v[172:175], v[228:231], v[22:25]
	v_mfma_f32_16x16x32_bf16 v[14:17], v[158:161], v[248:251], v[14:17]
	v_mfma_f32_16x16x32_bf16 v[6:9], v[172:175], v[248:251], v[6:9]
	v_mfma_f32_16x16x32_bf16 v[58:61], v[182:185], v[202:205], v[58:61]
	v_mfma_f32_16x16x32_bf16 v[50:53], v[190:193], v[202:205], v[50:53]
	v_mfma_f32_16x16x32_bf16 v[42:45], v[182:185], v[210:213], v[42:45]
	v_mfma_f32_16x16x32_bf16 v[34:37], v[190:193], v[210:213], v[34:37]
	v_mfma_f32_16x16x32_bf16 v[26:29], v[182:185], v[224:227], v[26:29]
	v_mfma_f32_16x16x32_bf16 v[18:21], v[190:193], v[224:227], v[18:21]
	v_mfma_f32_16x16x32_bf16 v[10:13], v[182:185], v[232:235], v[10:13]
	v_mfma_f32_16x16x32_bf16 v[2:5], v[190:193], v[232:235], v[2:5]
	v_mfma_f32_16x16x32_bf16 v[58:61], v[186:189], v[206:209], v[58:61]
	v_mfma_f32_16x16x32_bf16 v[50:53], v[198:201], v[206:209], v[50:53]
	v_mfma_f32_16x16x32_bf16 v[42:45], v[186:189], v[220:223], v[42:45]
	v_mfma_f32_16x16x32_bf16 v[34:37], v[198:201], v[220:223], v[34:37]
	v_mfma_f32_16x16x32_bf16 v[26:29], v[186:189], v[228:231], v[26:29]
	v_mfma_f32_16x16x32_bf16 v[18:21], v[198:201], v[228:231], v[18:21]
	v_mfma_f32_16x16x32_bf16 v[10:13], v[186:189], v[248:251], v[10:13]
	v_mfma_f32_16x16x32_bf16 v[2:5], v[198:201], v[248:251], v[2:5]
	s_setprio 0
	s_barrier
	s_add_i32 s50, s50, 2
	s_add_u32 s24, s24, 0x100
	s_addc_u32 s25, s25, 0
	s_add_u32 s48, s48, 0x100
	s_addc_u32 s49, s49, 0
	s_cmp_gt_u32 s50, 13
	s_cbranch_scc0 .LBB0_269
	s_and_b64 vcc, exec, s[12:13]
	s_cbranch_vccz .LBB0_272
	s_barrier

; #define PG8_STAGE(bufoff, gbase, voff) do { _Pragma("unroll") for (int _i = 0; _i < 2; ++_i) \
;         __builtin_amdgcn_global_load_lds((const unsigned*)((const char*)(gbase) + (voff)[_i]), (PG8_LAS unsigned*)(lds + (bufoff) + ldsw + _i * 8192), 16, 0, 0); } while (0)
; #define PG8_LDA(dst, b, h) do { _Pragma("unroll") for (int m = 0; m < 4; ++m) _Pragma("unroll") for (int k = 0; k < 2; ++k) dst[m][k] = *(const PG8_LAS bf16x8*)(lds + PG8_SA(b, h) + aoff + m * 2048 + k * 1024); } while (0)
; #define PG8_LDB(dst, b, h) do { _Pragma("unroll") for (int n = 0; n < 2; ++n) _Pragma("unroll") for (int k = 0; k < 2; ++k) dst[n][k] = *(const PG8_LAS bf16x8*)(lds + PG8_SB(b, h) + boff + n * 2048 + k * 1024); } while (0)
; #define PG8_MMA(ai, bj, At, Bt) do { __builtin_amdgcn_s_setprio(1); _Pragma("unroll") for (int m = 0; m < 4; ++m) _Pragma("unroll") for (int n = 0; n < 2; ++n) _Pragma("unroll") for (int k = 0; k < 2; ++k) \
;         acc[ai][bj][m][n] = __builtin_amdgcn_mfma_f32_16x16x32_bf16(Bt[n][k], At[m][k], acc[ai][bj][m][n], 0, 0, 0); __builtin_amdgcn_s_setprio(0); } while (0)
; #define PG8_WAIT_V(n) asm volatile("s_waitcnt vmcnt(" #n ")" ::: "memory")
; #define PG8_WAIT_L(n) asm volatile("s_waitcnt lgkmcnt(" #n ")" ::: "memory")
; template <class Epi, class Sched, bool ALIGN_EPI = false, bool SP2 = false>
; __device__ __forceinline__ void gemm_phase(PG8_LAS unsigned char* lds, const Gemm g, const Sched& S, const Epi& E, int tid_in) {
;     ...
;             const bool last = (t == nt - 2);
;             const char* a1 = cA + (size_t)(t + 1) * kstep;
;             const char* a2 = last ? nA : cA + (size_t)(t + 2) * kstep; const char* b2 = last ? nB : cB + (size_t)(t + 2) * kstep;
;             const char* a3 = a2 + kstep; const char* b3 = b2 + kstep;
;             if (last && has_next) S.a_ready(nxt);
;             if constexpr (SP2) {
;             PG8_LDB(B0, 0, 0); PG8_LDB(B1, 0, 1); PG8_SCHED; PG8_LDA(At, 0, 0); PG8_STAGE(PG8_SA(1, 1), a1 + hstep, voffA);
;             PG8_WAIT_V(8); PG8_WAIT_L(0); PG8_BAR; PG8_MMA(0, 0, At, B0); PG8_MMA(0, 1, At, B1); PG8_BAR; PG8_SCHED;
;             PG8_LDA(At, 0, 1); PG8_STAGE(PG8_SB(0, 0), b2, voffB); PG8_STAGE(PG8_SB(0, 1), b2 + hstep, voffB); PG8_STAGE(PG8_SA(0, 0), a2, voffA);
;             PG8_WAIT_V(8); PG8_WAIT_L(0); PG8_BAR; PG8_MMA(1, 0, At, B0); PG8_MMA(1, 1, At, B1); PG8_BAR; PG8_SCHED;
.LBB0_406:
	s_add_i32 s54, s28, 2
	s_add_u32 s55, s26, 0x80
	s_addc_u32 s29, s27, 0
	s_add_i32 s58, 0, 0x10000
	s_cmp_eq_u32 s45, s28
	s_cselect_b32 s29, s9, s29
	s_cselect_b32 s28, s8, s55
	v_add_u32_e32 v144, s58, v147
	s_cselect_b32 s57, s25, s53
	s_cselect_b32 s56, s24, s52
	s_add_i32 s55, 0, 0x14000
	ds_read_b128 v[140:143], v144
	ds_read_b128 v[150:153], v144 offset:1024
	ds_read_b128 v[154:157], v144 offset:2048
	ds_read_b128 v[158:161], v144 offset:3072
	v_add_u32_e32 v144, s55, v147
	ds_read_b128 v[168:171], v144
	ds_read_b128 v[172:175], v144 offset:1024
	ds_read_b128 v[182:185], v144 offset:2048
	ds_read_b128 v[186:189], v144 offset:3072
	v_lshl_add_u64 v[144:145], s[26:27], 0, v[136:137]
	s_add_i32 m0, s37, 0xc000
	ds_read_b128 v[190:193], v149
	ds_read_b128 v[198:201], v149 offset:1024
	ds_read_b128 v[202:205], v149 offset:2048
	ds_read_b128 v[206:209], v149 offset:3072
	ds_read_b128 v[210:213], v149 offset:4096
	ds_read_b128 v[220:223], v149 offset:5120
	ds_read_b128 v[224:227], v149 offset:6144
	ds_read_b128 v[228:231], v149 offset:7168
	global_load_lds_dwordx4 v[144:145], off
	v_lshl_add_u64 v[144:145], s[26:27], 0, v[138:139]
	s_add_i32 m0, s37, 0xe000
	s_nop 0
	global_load_lds_dwordx4 v[144:145], off
	s_waitcnt vmcnt(8) lgkmcnt(0)
	s_barrier
	s_setprio 1
	v_mfma_f32_16x16x32_bf16 v[126:129], v[140:143], v[190:193], v[126:129]
	v_mfma_f32_16x16x32_bf16 v[122:125], v[154:157], v[190:193], v[122:125]
	v_mfma_f32_16x16x32_bf16 v[110:113], v[140:143], v[202:205], v[110:113]
	v_mfma_f32_16x16x32_bf16 v[106:109], v[154:157], v[202:205], v[106:109]
	v_mfma_f32_16x16x32_bf16 v[94:97], v[140:143], v[210:213], v[94:97]
	v_mfma_f32_16x16x32_bf16 v[90:93], v[154:157], v[210:213], v[90:93]
	v_mfma_f32_16x16x32_bf16 v[78:81], v[140:143], v[224:227], v[78:81]
	v_mfma_f32_16x16x32_bf16 v[74:77], v[154:157], v[224:227], v[74:77]
	v_mfma_f32_16x16x32_bf16 v[126:129], v[150:153], v[198:201], v[126:129]
	v_mfma_f32_16x16x32_bf16 v[122:125], v[158:161], v[198:201], v[122:125]
	v_mfma_f32_16x16x32_bf16 v[110:113], v[150:153], v[206:209], v[110:113]
	v_mfma_f32_16x16x32_bf16 v[106:109], v[158:161], v[206:209], v[106:109]
	v_mfma_f32_16x16x32_bf16 v[94:97], v[150:153], v[220:223], v[94:97]
	v_mfma_f32_16x16x32_bf16 v[90:93], v[158:161], v[220:223], v[90:93]
	v_mfma_f32_16x16x32_bf16 v[78:81], v[150:153], v[228:231], v[78:81]
	v_mfma_f32_16x16x32_bf16 v[74:77], v[158:161], v[228:231], v[74:77]
	v_mfma_f32_16x16x32_bf16 v[118:121], v[168:171], v[190:193], v[118:121]
	v_mfma_f32_16x16x32_bf16 v[114:117], v[182:185], v[190:193], v[114:117]
	v_mfma_f32_16x16x32_bf16 v[102:105], v[168:171], v[202:205], v[102:105]
	v_mfma_f32_16x16x32_bf16 v[98:101], v[182:185], v[202:205], v[98:101]
	v_mfma_f32_16x16x32_bf16 v[86:89], v[168:171], v[210:213], v[86:89]
	v_mfma_f32_16x16x32_bf16 v[82:85], v[182:185], v[210:213], v[82:85]
	v_mfma_f32_16x16x32_bf16 v[70:73], v[168:171], v[224:227], v[70:73]
	v_mfma_f32_16x16x32_bf16 v[66:69], v[182:185], v[224:227], v[66:69]
	v_mfma_f32_16x16x32_bf16 v[118:121], v[172:175], v[198:201], v[118:121]
	v_mfma_f32_16x16x32_bf16 v[114:117], v[186:189], v[198:201], v[114:117]
	v_mfma_f32_16x16x32_bf16 v[102:105], v[172:175], v[206:209], v[102:105]
	v_mfma_f32_16x16x32_bf16 v[98:101], v[186:189], v[206:209], v[98:101]
	v_mfma_f32_16x16x32_bf16 v[86:89], v[172:175], v[220:223], v[86:89]
	v_mfma_f32_16x16x32_bf16 v[82:85], v[186:189], v[220:223], v[82:85]
	v_mfma_f32_16x16x32_bf16 v[70:73], v[172:175], v[228:231], v[70:73]
	v_mfma_f32_16x16x32_bf16 v[66:69], v[186:189], v[228:231], v[66:69]
	s_setprio 0
	s_barrier
	s_add_i32 s58, s58, s36
	v_lshl_add_u64 v[144:145], s[56:57], 0, v[0:1]
	s_mov_b32 m0, s58
	ds_read_b128 v[190:193], v149 offset:16384
	ds_read_b128 v[198:201], v149 offset:17408
	ds_read_b128 v[202:205], v149 offset:18432
	ds_read_b128 v[206:209], v149 offset:19456
	ds_read_b128 v[210:213], v149 offset:20480
	ds_read_b128 v[220:223], v149 offset:21504
	ds_read_b128 v[224:227], v149 offset:22528
	ds_read_b128 v[228:231], v149 offset:23552
	global_load_lds_dwordx4 v[144:145], off
	s_add_i32 m0, s58, 0x2000
	v_lshl_add_u64 v[176:177], s[56:57], 0, v[134:135]
	s_add_u32 s56, s56, s16
	s_addc_u32 s57, s57, 0
	s_add_i32 s55, s55, s36
	global_load_lds_dwordx4 v[176:177], off
	v_lshl_add_u64 v[194:195], s[56:57], 0, v[0:1]
	s_mov_b32 m0, s55
	v_lshl_add_u64 v[214:215], s[56:57], 0, v[134:135]
	global_load_lds_dwordx4 v[194:195], off
	s_add_i32 m0, s55, 0x2000
	v_lshl_add_u64 v[216:217], s[28:29], 0, v[130:131]
	global_load_lds_dwordx4 v[214:215], off
	s_mov_b32 m0, s37
	v_lshl_add_u64 v[232:233], s[28:29], 0, v[132:133]
	global_load_lds_dwordx4 v[216:217], off
	s_mov_b32 m0, s38
	s_nop 0
	global_load_lds_dwordx4 v[232:233], off
	s_waitcnt vmcnt(8) lgkmcnt(0)
	s_barrier
; #define PG8_STAGE(bufoff, gbase, voff) do { _Pragma("unroll") for (int _i = 0; _i < 2; ++_i) \
;         __builtin_amdgcn_global_load_lds((const unsigned*)((const char*)(gbase) + (voff)[_i]), (PG8_LAS unsigned*)(lds + (bufoff) + ldsw + _i * 8192), 16, 0, 0); } while (0)
; #define PG8_LDA(dst, b, h) do { _Pragma("unroll") for (int m = 0; m < 4; ++m) _Pragma("unroll") for (int k = 0; k < 2; ++k) dst[m][k] = *(const PG8_LAS bf16x8*)(lds + PG8_SA(b, h) + aoff + m * 2048 + k * 1024); } while (0)
; #define PG8_LDB(dst, b, h) do { _Pragma("unroll") for (int n = 0; n < 2; ++n) _Pragma("unroll") for (int k = 0; k < 2; ++k) dst[n][k] = *(const PG8_LAS bf16x8*)(lds + PG8_SB(b, h) + boff + n * 2048 + k * 1024); } while (0)
; #define PG8_MMA(ai, bj, At, Bt) do { __builtin_amdgcn_s_setprio(1); _Pragma("unroll") for (int m = 0; m < 4; ++m) _Pragma("unroll") for (int n = 0; n < 2; ++n) _Pragma("unroll") for (int k = 0; k < 2; ++k) \
;         acc[ai][bj][m][n] = __builtin_amdgcn_mfma_f32_16x16x32_bf16(Bt[n][k], At[m][k], acc[ai][bj][m][n], 0, 0, 0); __builtin_amdgcn_s_setprio(0); } while (0)
; #define PG8_WAIT_V(n) asm volatile("s_waitcnt vmcnt(" #n ")" ::: "memory")
; #define PG8_WAIT_L(n) asm volatile("s_waitcnt lgkmcnt(" #n ")" ::: "memory")
; #define PG8_BAR __builtin_amdgcn_s_barrier()
; #define PG8_SCHED __builtin_amdgcn_sched_barrier(0)
; template <class Epi, class Sched, bool ALIGN_EPI = false, bool SP2 = false>
; __device__ __forceinline__ void gemm_phase(PG8_LAS unsigned char* lds, const Gemm g, const Sched& S, const Epi& E, int tid_in) {
;     ...
;             PG8_WAIT_V(8); PG8_WAIT_L(0); PG8_BAR; PG8_MMA(1, 0, At, B0); PG8_MMA(1, 1, At, B1); PG8_BAR; PG8_SCHED;
;             PG8_LDB(B0, 1, 0); PG8_LDB(B1, 1, 1); PG8_SCHED; PG8_LDA(At, 1, 0); PG8_STAGE(PG8_SA(0, 1), a2 + hstep, voffA);
;             PG8_WAIT_V(8); PG8_WAIT_L(0); PG8_BAR; PG8_MMA(0, 0, At, B0); PG8_MMA(0, 1, At, B1); PG8_BAR; PG8_SCHED;
	s_setprio 1
	v_mfma_f32_16x16x32_bf16 v[62:65], v[140:143], v[190:193], v[62:65]
	v_mfma_f32_16x16x32_bf16 v[58:61], v[154:157], v[190:193], v[58:61]
	v_mfma_f32_16x16x32_bf16 v[46:49], v[140:143], v[202:205], v[46:49]
	v_mfma_f32_16x16x32_bf16 v[42:45], v[154:157], v[202:205], v[42:45]
	v_mfma_f32_16x16x32_bf16 v[30:33], v[140:143], v[210:213], v[30:33]
	v_mfma_f32_16x16x32_bf16 v[26:29], v[154:157], v[210:213], v[26:29]
	v_mfma_f32_16x16x32_bf16 v[14:17], v[140:143], v[224:227], v[14:17]
	v_mfma_f32_16x16x32_bf16 v[10:13], v[154:157], v[224:227], v[10:13]
	v_mfma_f32_16x16x32_bf16 v[62:65], v[150:153], v[198:201], v[62:65]
	v_mfma_f32_16x16x32_bf16 v[58:61], v[158:161], v[198:201], v[58:61]
	v_mfma_f32_16x16x32_bf16 v[46:49], v[150:153], v[206:209], v[46:49]
	v_mfma_f32_16x16x32_bf16 v[42:45], v[158:161], v[206:209], v[42:45]
	v_mfma_f32_16x16x32_bf16 v[30:33], v[150:153], v[220:223], v[30:33]
	v_mfma_f32_16x16x32_bf16 v[26:29], v[158:161], v[220:223], v[26:29]
	v_mfma_f32_16x16x32_bf16 v[14:17], v[150:153], v[228:231], v[14:17]
	v_mfma_f32_16x16x32_bf16 v[10:13], v[158:161], v[228:231], v[10:13]
	v_mfma_f32_16x16x32_bf16 v[54:57], v[168:171], v[190:193], v[54:57]
	v_mfma_f32_16x16x32_bf16 v[50:53], v[182:185], v[190:193], v[50:53]
	v_mfma_f32_16x16x32_bf16 v[38:41], v[168:171], v[202:205], v[38:41]
	v_mfma_f32_16x16x32_bf16 v[34:37], v[182:185], v[202:205], v[34:37]
	v_mfma_f32_16x16x32_bf16 v[22:25], v[168:171], v[210:213], v[22:25]
	v_mfma_f32_16x16x32_bf16 v[18:21], v[182:185], v[210:213], v[18:21]
	v_mfma_f32_16x16x32_bf16 v[6:9], v[168:171], v[224:227], v[6:9]
	v_mfma_f32_16x16x32_bf16 v[2:5], v[182:185], v[224:227], v[2:5]
	v_mfma_f32_16x16x32_bf16 v[54:57], v[172:175], v[198:201], v[54:57]
	v_mfma_f32_16x16x32_bf16 v[50:53], v[186:189], v[198:201], v[50:53]
	v_mfma_f32_16x16x32_bf16 v[38:41], v[172:175], v[206:209], v[38:41]
	v_mfma_f32_16x16x32_bf16 v[34:37], v[186:189], v[206:209], v[34:37]
	v_mfma_f32_16x16x32_bf16 v[22:25], v[172:175], v[220:223], v[22:25]
	v_mfma_f32_16x16x32_bf16 v[18:21], v[186:189], v[220:223], v[18:21]
	v_mfma_f32_16x16x32_bf16 v[6:9], v[172:175], v[228:231], v[6:9]
	v_mfma_f32_16x16x32_bf16 v[2:5], v[186:189], v[228:231], v[2:5]
	s_setprio 0
	s_barrier
	s_add_i32 s55, 0, 0x18000
	s_add_i32 s56, 0, 0x1c000
	v_add_u32_e32 v158, s55, v147
	v_add_u32_e32 v167, s56, v147
	ds_read_b128 v[140:143], v158
	ds_read_b128 v[150:153], v158 offset:1024
	ds_read_b128 v[154:157], v158 offset:2048
	ds_read_b128 v[158:161], v158 offset:3072
	ds_read_b128 v[168:171], v167
	ds_read_b128 v[172:175], v167 offset:1024
	ds_read_b128 v[182:185], v167 offset:2048
	ds_read_b128 v[186:189], v167 offset:3072
	s_add_u32 s28, s28, s16
	s_addc_u32 s29, s29, 0
	s_mov_b32 m0, s39
	v_lshl_add_u64 v[234:235], s[28:29], 0, v[130:131]
	ds_read_b128 v[190:193], v149 offset:32768
	ds_read_b128 v[198:201], v149 offset:33792
	ds_read_b128 v[202:205], v149 offset:34816
	ds_read_b128 v[206:209], v149 offset:35840
	ds_read_b128 v[210:213], v149 offset:36864
	ds_read_b128 v[220:223], v149 offset:37888
	ds_read_b128 v[224:227], v149 offset:38912
	ds_read_b128 v[228:231], v149 offset:39936
	global_load_lds_dwordx4 v[234:235], off
	v_lshl_add_u64 v[234:235], s[28:29], 0, v[132:133]
	s_mov_b32 m0, s40
	s_nop 0
	global_load_lds_dwordx4 v[234:235], off
	s_waitcnt vmcnt(8) lgkmcnt(0)
	s_barrier
	s_setprio 1
	v_mfma_f32_16x16x32_bf16 v[126:129], v[140:143], v[190:193], v[126:129]
	v_mfma_f32_16x16x32_bf16 v[122:125], v[154:157], v[190:193], v[122:125]
	v_mfma_f32_16x16x32_bf16 v[110:113], v[140:143], v[202:205], v[110:113]
	v_mfma_f32_16x16x32_bf16 v[106:109], v[154:157], v[202:205], v[106:109]
	v_mfma_f32_16x16x32_bf16 v[94:97], v[140:143], v[210:213], v[94:97]
	v_mfma_f32_16x16x32_bf16 v[90:93], v[154:157], v[210:213], v[90:93]
	v_mfma_f32_16x16x32_bf16 v[78:81], v[140:143], v[224:227], v[78:81]
	v_mfma_f32_16x16x32_bf16 v[74:77], v[154:157], v[224:227], v[74:77]
	v_mfma_f32_16x16x32_bf16 v[126:129], v[150:153], v[198:201], v[126:129]
	v_mfma_f32_16x16x32_bf16 v[122:125], v[158:161], v[198:201], v[122:125]
	v_mfma_f32_16x16x32_bf16 v[110:113], v[150:153], v[206:209], v[110:113]
	v_mfma_f32_16x16x32_bf16 v[106:109], v[158:161], v[206:209], v[106:109]
	v_mfma_f32_16x16x32_bf16 v[94:97], v[150:153], v[220:223], v[94:97]
	v_mfma_f32_16x16x32_bf16 v[90:93], v[158:161], v[220:223], v[90:93]
	v_mfma_f32_16x16x32_bf16 v[78:81], v[150:153], v[228:231], v[78:81]
	v_mfma_f32_16x16x32_bf16 v[74:77], v[158:161], v[228:231], v[74:77]
	v_mfma_f32_16x16x32_bf16 v[118:121], v[168:171], v[190:193], v[118:121]
	v_mfma_f32_16x16x32_bf16 v[114:117], v[182:185], v[190:193], v[114:117]
	v_mfma_f32_16x16x32_bf16 v[102:105], v[168:171], v[202:205], v[102:105]
	v_mfma_f32_16x16x32_bf16 v[98:101], v[182:185], v[202:205], v[98:101]
	v_mfma_f32_16x16x32_bf16 v[86:89], v[168:171], v[210:213], v[86:89]
	v_mfma_f32_16x16x32_bf16 v[82:85], v[182:185], v[210:213], v[82:85]
	v_mfma_f32_16x16x32_bf16 v[70:73], v[168:171], v[224:227], v[70:73]
	v_mfma_f32_16x16x32_bf16 v[66:69], v[182:185], v[224:227], v[66:69]
	v_mfma_f32_16x16x32_bf16 v[118:121], v[172:175], v[198:201], v[118:121]
	v_mfma_f32_16x16x32_bf16 v[114:117], v[186:189], v[198:201], v[114:117]
	v_mfma_f32_16x16x32_bf16 v[102:105], v[172:175], v[206:209], v[102:105]
	v_mfma_f32_16x16x32_bf16 v[98:101], v[186:189], v[206:209], v[98:101]
	v_mfma_f32_16x16x32_bf16 v[86:89], v[172:175], v[220:223], v[86:89]
	v_mfma_f32_16x16x32_bf16 v[82:85], v[186:189], v[220:223], v[82:85]
	v_mfma_f32_16x16x32_bf16 v[70:73], v[172:175], v[228:231], v[70:73]
	v_mfma_f32_16x16x32_bf16 v[66:69], v[186:189], v[228:231], v[66:69]
	s_setprio 0
	s_barrier
; #define PG8_STAGE(bufoff, gbase, voff) do { _Pragma("unroll") for (int _i = 0; _i < 2; ++_i) \
;         __builtin_amdgcn_global_load_lds((const unsigned*)((const char*)(gbase) + (voff)[_i]), (PG8_LAS unsigned*)(lds + (bufoff) + ldsw + _i * 8192), 16, 0, 0); } while (0)
; #define PG8_LDA(dst, b, h) do { _Pragma("unroll") for (int m = 0; m < 4; ++m) _Pragma("unroll") for (int k = 0; k < 2; ++k) dst[m][k] = *(const PG8_LAS bf16x8*)(lds + PG8_SA(b, h) + aoff + m * 2048 + k * 1024); } while (0)
; #define PG8_MMA(ai, bj, At, Bt) do { __builtin_amdgcn_s_setprio(1); _Pragma("unroll") for (int m = 0; m < 4; ++m) _Pragma("unroll") for (int n = 0; n < 2; ++n) _Pragma("unroll") for (int k = 0; k < 2; ++k) \
;         acc[ai][bj][m][n] = __builtin_amdgcn_mfma_f32_16x16x32_bf16(Bt[n][k], At[m][k], acc[ai][bj][m][n], 0, 0, 0); __builtin_amdgcn_s_setprio(0); } while (0)
; #define PG8_WAIT_V(n) asm volatile("s_waitcnt vmcnt(" #n ")" ::: "memory")
; #define PG8_WAIT_L(n) asm volatile("s_waitcnt lgkmcnt(" #n ")" ::: "memory")
; #define PG8_BAR __builtin_amdgcn_s_barrier()
; #define PG8_SCHED __builtin_amdgcn_sched_barrier(0)
; template <class Epi, class Sched, bool ALIGN_EPI = false, bool SP2 = false>
; __device__ __forceinline__ void gemm_phase(PG8_LAS unsigned char* lds, const Gemm g, const Sched& S, const Epi& E, int tid_in) {
;     ...
;             PG8_LDA(At, 1, 1); PG8_STAGE(PG8_SB(1, 0), b3, voffB); PG8_STAGE(PG8_SB(1, 1), b3 + hstep, voffB); PG8_STAGE(PG8_SA(1, 0), a3, voffA);
;             PG8_WAIT_V(8); PG8_WAIT_L(0); PG8_BAR; PG8_MMA(1, 0, At, B0); PG8_MMA(1, 1, At, B1); PG8_BAR; PG8_SCHED;
;     ...
;         if constexpr (ALIGN_EPI) { if (wr == 0) PG8_BAR; }
	s_add_i32 s28, s55, s36
	v_lshl_add_u64 v[144:145], v[144:145], 0, s[92:93]
	s_mov_b32 m0, s28
	ds_read_b128 v[190:193], v149 offset:49152
	ds_read_b128 v[198:201], v149 offset:50176
	ds_read_b128 v[202:205], v149 offset:51200
	ds_read_b128 v[206:209], v149 offset:52224
	ds_read_b128 v[210:213], v149 offset:53248
	ds_read_b128 v[220:223], v149 offset:54272
	ds_read_b128 v[224:227], v149 offset:55296
	ds_read_b128 v[228:231], v149 offset:56320
	global_load_lds_dwordx4 v[144:145], off
	v_lshl_add_u64 v[144:145], v[176:177], 0, s[92:93]
	s_add_i32 m0, s28, 0x2000
	s_add_i32 s28, s56, s36
	global_load_lds_dwordx4 v[144:145], off
	v_lshl_add_u64 v[144:145], v[194:195], 0, s[92:93]
	s_mov_b32 m0, s28
	s_nop 0
	global_load_lds_dwordx4 v[144:145], off
	v_lshl_add_u64 v[144:145], v[214:215], 0, s[92:93]
	s_add_i32 m0, s28, 0x2000
	s_nop 0
	global_load_lds_dwordx4 v[144:145], off
	v_lshl_add_u64 v[144:145], v[216:217], 0, s[92:93]
	s_mov_b32 m0, s41
	s_nop 0
	global_load_lds_dwordx4 v[144:145], off
	v_lshl_add_u64 v[144:145], v[232:233], 0, s[92:93]
	s_mov_b32 m0, s42
	s_nop 0
	global_load_lds_dwordx4 v[144:145], off
	s_waitcnt vmcnt(8) lgkmcnt(0)
	s_barrier
	s_setprio 1
	v_mfma_f32_16x16x32_bf16 v[62:65], v[140:143], v[190:193], v[62:65]
	v_mfma_f32_16x16x32_bf16 v[58:61], v[154:157], v[190:193], v[58:61]
	v_mfma_f32_16x16x32_bf16 v[46:49], v[140:143], v[202:205], v[46:49]
	v_mfma_f32_16x16x32_bf16 v[42:45], v[154:157], v[202:205], v[42:45]
	v_mfma_f32_16x16x32_bf16 v[30:33], v[140:143], v[210:213], v[30:33]
	v_mfma_f32_16x16x32_bf16 v[26:29], v[154:157], v[210:213], v[26:29]
	v_mfma_f32_16x16x32_bf16 v[14:17], v[140:143], v[224:227], v[14:17]
	v_mfma_f32_16x16x32_bf16 v[10:13], v[154:157], v[224:227], v[10:13]
	v_mfma_f32_16x16x32_bf16 v[62:65], v[150:153], v[198:201], v[62:65]
	v_mfma_f32_16x16x32_bf16 v[58:61], v[158:161], v[198:201], v[58:61]
	v_mfma_f32_16x16x32_bf16 v[46:49], v[150:153], v[206:209], v[46:49]
	v_mfma_f32_16x16x32_bf16 v[42:45], v[158:161], v[206:209], v[42:45]
	v_mfma_f32_16x16x32_bf16 v[30:33], v[150:153], v[220:223], v[30:33]
	v_mfma_f32_16x16x32_bf16 v[26:29], v[158:161], v[220:223], v[26:29]
	v_mfma_f32_16x16x32_bf16 v[14:17], v[150:153], v[228:231], v[14:17]
	v_mfma_f32_16x16x32_bf16 v[10:13], v[158:161], v[228:231], v[10:13]
	v_mfma_f32_16x16x32_bf16 v[54:57], v[168:171], v[190:193], v[54:57]
	v_mfma_f32_16x16x32_bf16 v[50:53], v[182:185], v[190:193], v[50:53]
	v_mfma_f32_16x16x32_bf16 v[38:41], v[168:171], v[202:205], v[38:41]
	v_mfma_f32_16x16x32_bf16 v[34:37], v[182:185], v[202:205], v[34:37]
	v_mfma_f32_16x16x32_bf16 v[22:25], v[168:171], v[210:213], v[22:25]
	v_mfma_f32_16x16x32_bf16 v[18:21], v[182:185], v[210:213], v[18:21]
	v_mfma_f32_16x16x32_bf16 v[6:9], v[168:171], v[224:227], v[6:9]
	v_mfma_f32_16x16x32_bf16 v[2:5], v[182:185], v[224:227], v[2:5]
	v_mfma_f32_16x16x32_bf16 v[54:57], v[172:175], v[198:201], v[54:57]
	v_mfma_f32_16x16x32_bf16 v[50:53], v[186:189], v[198:201], v[50:53]
	v_mfma_f32_16x16x32_bf16 v[38:41], v[172:175], v[206:209], v[38:41]
	v_mfma_f32_16x16x32_bf16 v[34:37], v[186:189], v[206:209], v[34:37]
	v_mfma_f32_16x16x32_bf16 v[22:25], v[172:175], v[220:223], v[22:25]
	v_mfma_f32_16x16x32_bf16 v[18:21], v[186:189], v[220:223], v[18:21]
	v_mfma_f32_16x16x32_bf16 v[6:9], v[172:175], v[228:231], v[6:9]
	v_mfma_f32_16x16x32_bf16 v[2:5], v[186:189], v[228:231], v[2:5]
	s_setprio 0
	s_barrier
	s_add_u32 s26, s26, 0x100
	s_addc_u32 s27, s27, 0
	s_add_u32 s52, s52, 0x100
	s_addc_u32 s53, s53, 0
	s_cmp_ge_u32 s54, s44
	s_mov_b32 s28, s54
	s_cbranch_scc0 .LBB0_406
	s_and_b64 vcc, exec, s[22:23]
	s_cbranch_vccz .LBB0_409
	s_barrier

; #define PG8_STAGE(bufoff, gbase, voff) do { _Pragma("unroll") for (int _i = 0; _i < 2; ++_i) \
;         __builtin_amdgcn_global_load_lds((const unsigned*)((const char*)(gbase) + (voff)[_i]), (PG8_LAS unsigned*)(lds + (bufoff) + ldsw + _i * 8192), 16, 0, 0); } while (0)
; #define PG8_LDA(dst, b, h) do { _Pragma("unroll") for (int m = 0; m < 4; ++m) _Pragma("unroll") for (int k = 0; k < 2; ++k) dst[m][k] = *(const PG8_LAS bf16x8*)(lds + PG8_SA(b, h) + aoff + m * 2048 + k * 1024); } while (0)
; #define PG8_LDB(dst, b, h) do { _Pragma("unroll") for (int n = 0; n < 2; ++n) _Pragma("unroll") for (int k = 0; k < 2; ++k) dst[n][k] = *(const PG8_LAS bf16x8*)(lds + PG8_SB(b, h) + boff + n * 2048 + k * 1024); } while (0)
; #define PG8_MMA(ai, bj, At, Bt) do { __builtin_amdgcn_s_setprio(1); _Pragma("unroll") for (int m = 0; m < 4; ++m) _Pragma("unroll") for (int n = 0; n < 2; ++n) _Pragma("unroll") for (int k = 0; k < 2; ++k) \
;         acc[ai][bj][m][n] = __builtin_amdgcn_mfma_f32_16x16x32_bf16(Bt[n][k], At[m][k], acc[ai][bj][m][n], 0, 0, 0); __builtin_amdgcn_s_setprio(0); } while (0)
; #define PG8_WAIT_V(n) asm volatile("s_waitcnt vmcnt(" #n ")" ::: "memory")
; #define PG8_WAIT_L(n) asm volatile("s_waitcnt lgkmcnt(" #n ")" ::: "memory")
; template <class Epi, class Sched, bool ALIGN_EPI = false, bool SP2 = false>
; __device__ __forceinline__ void gemm_phase(PG8_LAS unsigned char* lds, const Gemm g, const Sched& S, const Epi& E, int tid_in) {
;     ...
;             const bool last = (t == nt - 2);
;             const char* a1 = cA + (size_t)(t + 1) * kstep;
;             const char* a2 = last ? nA : cA + (size_t)(t + 2) * kstep; const char* b2 = last ? nB : cB + (size_t)(t + 2) * kstep;
;             const char* a3 = a2 + kstep; const char* b3 = b2 + kstep;
;             if (last && has_next) S.a_ready(nxt);
;             if constexpr (SP2) {
;             PG8_LDB(B0, 0, 0); PG8_LDB(B1, 0, 1); PG8_SCHED; PG8_LDA(At, 0, 0); PG8_STAGE(PG8_SA(1, 1), a1 + hstep, voffA);
;             PG8_WAIT_V(8); PG8_WAIT_L(0); PG8_BAR; PG8_MMA(0, 0, At, B0); PG8_MMA(0, 1, At, B1); PG8_BAR; PG8_SCHED;
;             PG8_LDA(At, 0, 1); PG8_STAGE(PG8_SB(0, 0), b2, voffB); PG8_STAGE(PG8_SB(0, 1), b2 + hstep, voffB); PG8_STAGE(PG8_SA(0, 0), a2, voffA);
;             PG8_WAIT_V(8); PG8_WAIT_L(0); PG8_BAR; PG8_MMA(1, 0, At, B0); PG8_MMA(1, 1, At, B1); PG8_BAR; PG8_SCHED;
.LBB0_451:
	s_add_i32 s51, s23, 2
	s_add_u32 s28, s20, s26
	s_addc_u32 s29, s21, s27
	s_add_u32 s52, s18, s26
	s_addc_u32 s53, s19, s27
	s_add_i32 s54, 0, 0x10000
	s_cmp_eq_u32 s47, s23
	s_cselect_b32 s29, s9, s29
	s_cselect_b32 s28, s8, s28
	v_add_u32_e32 v147, s54, v145
	s_cselect_b32 s53, s25, s53
	s_cselect_b32 s52, s24, s52
	s_add_i32 s23, 0, 0x14000
	ds_read_b128 v[152:155], v147
	ds_read_b128 v[156:159], v147 offset:1024
	ds_read_b128 v[168:171], v147 offset:2048
	ds_read_b128 v[172:175], v147 offset:3072
	v_add_u32_e32 v147, s23, v145
	ds_read_b128 v[182:185], v147
	ds_read_b128 v[186:189], v147 offset:1024
	ds_read_b128 v[190:193], v147 offset:2048
	ds_read_b128 v[198:201], v147 offset:3072
	v_lshl_add_u64 v[148:149], s[20:21], 0, v[142:143]
	s_add_i32 m0, s41, 0xc000
	ds_read_b128 v[202:205], v146
	ds_read_b128 v[206:209], v146 offset:1024
	ds_read_b128 v[210:213], v146 offset:2048
	ds_read_b128 v[220:223], v146 offset:3072
	ds_read_b128 v[224:227], v146 offset:4096
	ds_read_b128 v[228:231], v146 offset:5120
	ds_read_b128 v[232:235], v146 offset:6144
	ds_read_b128 v[248:251], v146 offset:7168
	global_load_lds_dwordx4 v[148:149], off
	v_lshl_add_u64 v[148:149], s[20:21], 0, v[140:141]
	s_add_i32 m0, s41, 0xe000
	s_nop 0
	global_load_lds_dwordx4 v[148:149], off
	s_waitcnt vmcnt(8) lgkmcnt(0)
	s_barrier
	s_setprio 1
	v_mfma_f32_16x16x32_bf16 v[126:129], v[152:155], v[202:205], v[126:129]
	v_mfma_f32_16x16x32_bf16 v[122:125], v[168:171], v[202:205], v[122:125]
	v_mfma_f32_16x16x32_bf16 v[110:113], v[152:155], v[210:213], v[110:113]
	v_mfma_f32_16x16x32_bf16 v[106:109], v[168:171], v[210:213], v[106:109]
	v_mfma_f32_16x16x32_bf16 v[94:97], v[152:155], v[224:227], v[94:97]
	v_mfma_f32_16x16x32_bf16 v[90:93], v[168:171], v[224:227], v[90:93]
	v_mfma_f32_16x16x32_bf16 v[78:81], v[152:155], v[232:235], v[78:81]
	v_mfma_f32_16x16x32_bf16 v[74:77], v[168:171], v[232:235], v[74:77]
	v_mfma_f32_16x16x32_bf16 v[126:129], v[156:159], v[206:209], v[126:129]
	v_mfma_f32_16x16x32_bf16 v[122:125], v[172:175], v[206:209], v[122:125]
	v_mfma_f32_16x16x32_bf16 v[110:113], v[156:159], v[220:223], v[110:113]
	v_mfma_f32_16x16x32_bf16 v[106:109], v[172:175], v[220:223], v[106:109]
	v_mfma_f32_16x16x32_bf16 v[94:97], v[156:159], v[228:231], v[94:97]
	v_mfma_f32_16x16x32_bf16 v[90:93], v[172:175], v[228:231], v[90:93]
	v_mfma_f32_16x16x32_bf16 v[78:81], v[156:159], v[248:251], v[78:81]
	v_mfma_f32_16x16x32_bf16 v[74:77], v[172:175], v[248:251], v[74:77]
	v_mfma_f32_16x16x32_bf16 v[118:121], v[182:185], v[202:205], v[118:121]
	v_mfma_f32_16x16x32_bf16 v[114:117], v[190:193], v[202:205], v[114:117]
	v_mfma_f32_16x16x32_bf16 v[102:105], v[182:185], v[210:213], v[102:105]
	v_mfma_f32_16x16x32_bf16 v[98:101], v[190:193], v[210:213], v[98:101]
	v_mfma_f32_16x16x32_bf16 v[86:89], v[182:185], v[224:227], v[86:89]
	v_mfma_f32_16x16x32_bf16 v[82:85], v[190:193], v[224:227], v[82:85]
	v_mfma_f32_16x16x32_bf16 v[70:73], v[182:185], v[232:235], v[70:73]
	v_mfma_f32_16x16x32_bf16 v[66:69], v[190:193], v[232:235], v[66:69]
	v_mfma_f32_16x16x32_bf16 v[118:121], v[186:189], v[206:209], v[118:121]
	v_mfma_f32_16x16x32_bf16 v[114:117], v[198:201], v[206:209], v[114:117]
	v_mfma_f32_16x16x32_bf16 v[102:105], v[186:189], v[220:223], v[102:105]
	v_mfma_f32_16x16x32_bf16 v[98:101], v[198:201], v[220:223], v[98:101]
	v_mfma_f32_16x16x32_bf16 v[86:89], v[186:189], v[228:231], v[86:89]
	v_mfma_f32_16x16x32_bf16 v[82:85], v[198:201], v[228:231], v[82:85]
	v_mfma_f32_16x16x32_bf16 v[70:73], v[186:189], v[248:251], v[70:73]
	v_mfma_f32_16x16x32_bf16 v[66:69], v[198:201], v[248:251], v[66:69]
	s_setprio 0
	s_barrier
	s_add_i32 s54, s54, s40
	v_lshl_add_u64 v[148:149], s[52:53], 0, v[0:1]
	s_mov_b32 m0, s54
	ds_read_b128 v[202:205], v146 offset:16384
	ds_read_b128 v[206:209], v146 offset:17408
	ds_read_b128 v[210:213], v146 offset:18432
	ds_read_b128 v[220:223], v146 offset:19456
	ds_read_b128 v[224:227], v146 offset:20480
	ds_read_b128 v[228:231], v146 offset:21504
	ds_read_b128 v[232:235], v146 offset:22528
	ds_read_b128 v[248:251], v146 offset:23552
	global_load_lds_dwordx4 v[148:149], off
	s_add_i32 m0, s54, 0x2000
	v_lshl_add_u64 v[160:161], s[52:53], 0, v[134:135]
	s_add_u32 s52, s52, s38
	s_addc_u32 s53, s53, 0
	s_add_i32 s23, s23, s40
	global_load_lds_dwordx4 v[160:161], off
	v_lshl_add_u64 v[176:177], s[52:53], 0, v[0:1]
	s_mov_b32 m0, s23
	v_lshl_add_u64 v[194:195], s[52:53], 0, v[134:135]
	global_load_lds_dwordx4 v[176:177], off
	s_add_i32 m0, s23, 0x2000
	v_lshl_add_u64 v[214:215], s[28:29], 0, v[130:131]
	global_load_lds_dwordx4 v[194:195], off
	s_mov_b32 m0, s41
	v_lshl_add_u64 v[216:217], s[28:29], 0, v[132:133]
	global_load_lds_dwordx4 v[214:215], off
	s_mov_b32 m0, s42
	s_nop 0
	global_load_lds_dwordx4 v[216:217], off
	s_waitcnt vmcnt(8) lgkmcnt(0)
	s_barrier
; #define PG8_STAGE(bufoff, gbase, voff) do { _Pragma("unroll") for (int _i = 0; _i < 2; ++_i) \
;         __builtin_amdgcn_global_load_lds((const unsigned*)((const char*)(gbase) + (voff)[_i]), (PG8_LAS unsigned*)(lds + (bufoff) + ldsw + _i * 8192), 16, 0, 0); } while (0)
; #define PG8_LDA(dst, b, h) do { _Pragma("unroll") for (int m = 0; m < 4; ++m) _Pragma("unroll") for (int k = 0; k < 2; ++k) dst[m][k] = *(const PG8_LAS bf16x8*)(lds + PG8_SA(b, h) + aoff + m * 2048 + k * 1024); } while (0)
; #define PG8_LDB(dst, b, h) do { _Pragma("unroll") for (int n = 0; n < 2; ++n) _Pragma("unroll") for (int k = 0; k < 2; ++k) dst[n][k] = *(const PG8_LAS bf16x8*)(lds + PG8_SB(b, h) + boff + n * 2048 + k * 1024); } while (0)
; #define PG8_MMA(ai, bj, At, Bt) do { __builtin_amdgcn_s_setprio(1); _Pragma("unroll") for (int m = 0; m < 4; ++m) _Pragma("unroll") for (int n = 0; n < 2; ++n) _Pragma("unroll") for (int k = 0; k < 2; ++k) \
;         acc[ai][bj][m][n] = __builtin_amdgcn_mfma_f32_16x16x32_bf16(Bt[n][k], At[m][k], acc[ai][bj][m][n], 0, 0, 0); __builtin_amdgcn_s_setprio(0); } while (0)
; #define PG8_WAIT_V(n) asm volatile("s_waitcnt vmcnt(" #n ")" ::: "memory")
; #define PG8_WAIT_L(n) asm volatile("s_waitcnt lgkmcnt(" #n ")" ::: "memory")
; #define PG8_BAR __builtin_amdgcn_s_barrier()
; #define PG8_SCHED __builtin_amdgcn_sched_barrier(0)
; template <class Epi, class Sched, bool ALIGN_EPI = false, bool SP2 = false>
; __device__ __forceinline__ void gemm_phase(PG8_LAS unsigned char* lds, const Gemm g, const Sched& S, const Epi& E, int tid_in) {
;     ...
;             PG8_WAIT_V(8); PG8_WAIT_L(0); PG8_BAR; PG8_MMA(1, 0, At, B0); PG8_MMA(1, 1, At, B1); PG8_BAR; PG8_SCHED;
;             PG8_LDB(B0, 1, 0); PG8_LDB(B1, 1, 1); PG8_SCHED; PG8_LDA(At, 1, 0); PG8_STAGE(PG8_SA(0, 1), a2 + hstep, voffA);
;             PG8_WAIT_V(8); PG8_WAIT_L(0); PG8_BAR; PG8_MMA(0, 0, At, B0); PG8_MMA(0, 1, At, B1); PG8_BAR; PG8_SCHED;
	s_setprio 1
	v_mfma_f32_16x16x32_bf16 v[62:65], v[152:155], v[202:205], v[62:65]
	v_mfma_f32_16x16x32_bf16 v[58:61], v[168:171], v[202:205], v[58:61]
	v_mfma_f32_16x16x32_bf16 v[46:49], v[152:155], v[210:213], v[46:49]
	v_mfma_f32_16x16x32_bf16 v[42:45], v[168:171], v[210:213], v[42:45]
	v_mfma_f32_16x16x32_bf16 v[30:33], v[152:155], v[224:227], v[30:33]
	v_mfma_f32_16x16x32_bf16 v[26:29], v[168:171], v[224:227], v[26:29]
	v_mfma_f32_16x16x32_bf16 v[14:17], v[152:155], v[232:235], v[14:17]
	v_mfma_f32_16x16x32_bf16 v[10:13], v[168:171], v[232:235], v[10:13]
	v_mfma_f32_16x16x32_bf16 v[62:65], v[156:159], v[206:209], v[62:65]
	v_mfma_f32_16x16x32_bf16 v[58:61], v[172:175], v[206:209], v[58:61]
	v_mfma_f32_16x16x32_bf16 v[46:49], v[156:159], v[220:223], v[46:49]
	v_mfma_f32_16x16x32_bf16 v[42:45], v[172:175], v[220:223], v[42:45]
	v_mfma_f32_16x16x32_bf16 v[30:33], v[156:159], v[228:231], v[30:33]
	v_mfma_f32_16x16x32_bf16 v[26:29], v[172:175], v[228:231], v[26:29]
	v_mfma_f32_16x16x32_bf16 v[14:17], v[156:159], v[248:251], v[14:17]
	v_mfma_f32_16x16x32_bf16 v[10:13], v[172:175], v[248:251], v[10:13]
	v_mfma_f32_16x16x32_bf16 v[54:57], v[182:185], v[202:205], v[54:57]
	v_mfma_f32_16x16x32_bf16 v[50:53], v[190:193], v[202:205], v[50:53]
	v_mfma_f32_16x16x32_bf16 v[38:41], v[182:185], v[210:213], v[38:41]
	v_mfma_f32_16x16x32_bf16 v[34:37], v[190:193], v[210:213], v[34:37]
	v_mfma_f32_16x16x32_bf16 v[22:25], v[182:185], v[224:227], v[22:25]
	v_mfma_f32_16x16x32_bf16 v[18:21], v[190:193], v[224:227], v[18:21]
	v_mfma_f32_16x16x32_bf16 v[6:9], v[182:185], v[232:235], v[6:9]
	v_mfma_f32_16x16x32_bf16 v[2:5], v[190:193], v[232:235], v[2:5]
	v_mfma_f32_16x16x32_bf16 v[54:57], v[186:189], v[206:209], v[54:57]
	v_mfma_f32_16x16x32_bf16 v[50:53], v[198:201], v[206:209], v[50:53]
	v_mfma_f32_16x16x32_bf16 v[38:41], v[186:189], v[220:223], v[38:41]
	v_mfma_f32_16x16x32_bf16 v[34:37], v[198:201], v[220:223], v[34:37]
	v_mfma_f32_16x16x32_bf16 v[22:25], v[186:189], v[228:231], v[22:25]
	v_mfma_f32_16x16x32_bf16 v[18:21], v[198:201], v[228:231], v[18:21]
	v_mfma_f32_16x16x32_bf16 v[6:9], v[186:189], v[248:251], v[6:9]
	v_mfma_f32_16x16x32_bf16 v[2:5], v[198:201], v[248:251], v[2:5]
	s_setprio 0
	s_barrier
	s_add_i32 s23, 0, 0x18000
	v_add_u32_e32 v147, s23, v145
	s_add_i32 s52, 0, 0x1c000
	ds_read_b128 v[152:155], v147
	ds_read_b128 v[156:159], v147 offset:1024
	ds_read_b128 v[168:171], v147 offset:2048
	ds_read_b128 v[172:175], v147 offset:3072
	v_add_u32_e32 v147, s52, v145
	ds_read_b128 v[182:185], v147
	ds_read_b128 v[186:189], v147 offset:1024
	ds_read_b128 v[190:193], v147 offset:2048
	ds_read_b128 v[198:201], v147 offset:3072
	s_add_u32 s28, s28, s38
	s_addc_u32 s29, s29, 0
	s_mov_b32 m0, s43
	v_lshl_add_u64 v[236:237], s[28:29], 0, v[130:131]
	ds_read_b128 v[202:205], v146 offset:32768
	ds_read_b128 v[206:209], v146 offset:33792
	ds_read_b128 v[210:213], v146 offset:34816
	ds_read_b128 v[220:223], v146 offset:35840
	ds_read_b128 v[224:227], v146 offset:36864
	ds_read_b128 v[228:231], v146 offset:37888
	ds_read_b128 v[232:235], v146 offset:38912
	ds_read_b128 v[248:251], v146 offset:39936
	global_load_lds_dwordx4 v[236:237], off
	v_lshl_add_u64 v[236:237], s[28:29], 0, v[132:133]
	s_mov_b32 m0, s44
	s_nop 0
	global_load_lds_dwordx4 v[236:237], off
	s_waitcnt vmcnt(8) lgkmcnt(0)
	s_barrier
	s_setprio 1
	v_mfma_f32_16x16x32_bf16 v[126:129], v[152:155], v[202:205], v[126:129]
	v_mfma_f32_16x16x32_bf16 v[122:125], v[168:171], v[202:205], v[122:125]
	v_mfma_f32_16x16x32_bf16 v[110:113], v[152:155], v[210:213], v[110:113]
	v_mfma_f32_16x16x32_bf16 v[106:109], v[168:171], v[210:213], v[106:109]
	v_mfma_f32_16x16x32_bf16 v[94:97], v[152:155], v[224:227], v[94:97]
	v_mfma_f32_16x16x32_bf16 v[90:93], v[168:171], v[224:227], v[90:93]
	v_mfma_f32_16x16x32_bf16 v[78:81], v[152:155], v[232:235], v[78:81]
	v_mfma_f32_16x16x32_bf16 v[74:77], v[168:171], v[232:235], v[74:77]
	v_mfma_f32_16x16x32_bf16 v[126:129], v[156:159], v[206:209], v[126:129]
	v_mfma_f32_16x16x32_bf16 v[122:125], v[172:175], v[206:209], v[122:125]
	v_mfma_f32_16x16x32_bf16 v[110:113], v[156:159], v[220:223], v[110:113]
	v_mfma_f32_16x16x32_bf16 v[106:109], v[172:175], v[220:223], v[106:109]
	v_mfma_f32_16x16x32_bf16 v[94:97], v[156:159], v[228:231], v[94:97]
	v_mfma_f32_16x16x32_bf16 v[90:93], v[172:175], v[228:231], v[90:93]
	v_mfma_f32_16x16x32_bf16 v[78:81], v[156:159], v[248:251], v[78:81]
	v_mfma_f32_16x16x32_bf16 v[74:77], v[172:175], v[248:251], v[74:77]
	v_mfma_f32_16x16x32_bf16 v[118:121], v[182:185], v[202:205], v[118:121]
	v_mfma_f32_16x16x32_bf16 v[114:117], v[190:193], v[202:205], v[114:117]
	v_mfma_f32_16x16x32_bf16 v[102:105], v[182:185], v[210:213], v[102:105]
	v_mfma_f32_16x16x32_bf16 v[98:101], v[190:193], v[210:213], v[98:101]
	v_mfma_f32_16x16x32_bf16 v[86:89], v[182:185], v[224:227], v[86:89]
	v_mfma_f32_16x16x32_bf16 v[82:85], v[190:193], v[224:227], v[82:85]
	v_mfma_f32_16x16x32_bf16 v[70:73], v[182:185], v[232:235], v[70:73]
	v_mfma_f32_16x16x32_bf16 v[66:69], v[190:193], v[232:235], v[66:69]
	v_mfma_f32_16x16x32_bf16 v[118:121], v[186:189], v[206:209], v[118:121]
	v_mfma_f32_16x16x32_bf16 v[114:117], v[198:201], v[206:209], v[114:117]
	v_mfma_f32_16x16x32_bf16 v[102:105], v[186:189], v[220:223], v[102:105]
	v_mfma_f32_16x16x32_bf16 v[98:101], v[198:201], v[220:223], v[98:101]
	v_mfma_f32_16x16x32_bf16 v[86:89], v[186:189], v[228:231], v[86:89]
	v_mfma_f32_16x16x32_bf16 v[82:85], v[198:201], v[228:231], v[82:85]
	v_mfma_f32_16x16x32_bf16 v[70:73], v[186:189], v[248:251], v[70:73]
	v_mfma_f32_16x16x32_bf16 v[66:69], v[198:201], v[248:251], v[66:69]
	s_setprio 0
	s_barrier
; #define PG8_STAGE(bufoff, gbase, voff) do { _Pragma("unroll") for (int _i = 0; _i < 2; ++_i) \
;         __builtin_amdgcn_global_load_lds((const unsigned*)((const char*)(gbase) + (voff)[_i]), (PG8_LAS unsigned*)(lds + (bufoff) + ldsw + _i * 8192), 16, 0, 0); } while (0)
; #define PG8_LDA(dst, b, h) do { _Pragma("unroll") for (int m = 0; m < 4; ++m) _Pragma("unroll") for (int k = 0; k < 2; ++k) dst[m][k] = *(const PG8_LAS bf16x8*)(lds + PG8_SA(b, h) + aoff + m * 2048 + k * 1024); } while (0)
; #define PG8_MMA(ai, bj, At, Bt) do { __builtin_amdgcn_s_setprio(1); _Pragma("unroll") for (int m = 0; m < 4; ++m) _Pragma("unroll") for (int n = 0; n < 2; ++n) _Pragma("unroll") for (int k = 0; k < 2; ++k) \
;         acc[ai][bj][m][n] = __builtin_amdgcn_mfma_f32_16x16x32_bf16(Bt[n][k], At[m][k], acc[ai][bj][m][n], 0, 0, 0); __builtin_amdgcn_s_setprio(0); } while (0)
; #define PG8_WAIT_V(n) asm volatile("s_waitcnt vmcnt(" #n ")" ::: "memory")
; #define PG8_WAIT_L(n) asm volatile("s_waitcnt lgkmcnt(" #n ")" ::: "memory")
; #define PG8_BAR __builtin_amdgcn_s_barrier()
; #define PG8_SCHED __builtin_amdgcn_sched_barrier(0)
; template <class Epi, class Sched, bool ALIGN_EPI = false, bool SP2 = false>
; __device__ __forceinline__ void gemm_phase(PG8_LAS unsigned char* lds, const Gemm g, const Sched& S, const Epi& E, int tid_in) {
;     ...
;             PG8_LDA(At, 1, 1); PG8_STAGE(PG8_SB(1, 0), b3, voffB); PG8_STAGE(PG8_SB(1, 1), b3 + hstep, voffB); PG8_STAGE(PG8_SA(1, 0), a3, voffA);
;             PG8_WAIT_V(8); PG8_WAIT_L(0); PG8_BAR; PG8_MMA(1, 0, At, B0); PG8_MMA(1, 1, At, B1); PG8_BAR; PG8_SCHED;
;     ...
; #pragma unroll
;         for (int a = 0; a < 2; ++a)
; #pragma unroll
;             for (int b = 0; b < 2; ++b)
; #pragma unroll
;                 for (int m = 0; m < 4; ++m)
; #pragma unroll
;                     for (int n = 0; n < 2; ++n) acc[a][b][m][n] = (f32x4){0.f, 0.f, 0.f, 0.f};
;         cur = nxt; cA = nA; cB = nB; ++ui;
	s_add_i32 s23, s23, s40
	v_lshl_add_u64 v[148:149], v[148:149], 0, s[92:93]
	s_mov_b32 m0, s23
	ds_read_b128 v[202:205], v146 offset:49152
	ds_read_b128 v[206:209], v146 offset:50176
	ds_read_b128 v[210:213], v146 offset:51200
	ds_read_b128 v[220:223], v146 offset:52224
	ds_read_b128 v[224:227], v146 offset:53248
	ds_read_b128 v[228:231], v146 offset:54272
	ds_read_b128 v[232:235], v146 offset:55296
	ds_read_b128 v[248:251], v146 offset:56320
	global_load_lds_dwordx4 v[148:149], off
	v_lshl_add_u64 v[148:149], v[160:161], 0, s[92:93]
	s_add_i32 m0, s23, 0x2000
	s_add_i32 s23, s52, s40
	global_load_lds_dwordx4 v[148:149], off
	v_lshl_add_u64 v[148:149], v[176:177], 0, s[92:93]
	s_mov_b32 m0, s23
	s_nop 0
	global_load_lds_dwordx4 v[148:149], off
	v_lshl_add_u64 v[148:149], v[194:195], 0, s[92:93]
	s_add_i32 m0, s23, 0x2000
	s_nop 0
	global_load_lds_dwordx4 v[148:149], off
	v_lshl_add_u64 v[148:149], v[214:215], 0, s[92:93]
	s_mov_b32 m0, s45
	s_nop 0
	global_load_lds_dwordx4 v[148:149], off
	v_lshl_add_u64 v[148:149], v[216:217], 0, s[92:93]
	s_mov_b32 m0, s46
	s_nop 0
	global_load_lds_dwordx4 v[148:149], off
	s_waitcnt vmcnt(8) lgkmcnt(0)
	s_barrier
	s_setprio 1
	v_mfma_f32_16x16x32_bf16 v[62:65], v[152:155], v[202:205], v[62:65]
	v_mfma_f32_16x16x32_bf16 v[58:61], v[168:171], v[202:205], v[58:61]
	v_mfma_f32_16x16x32_bf16 v[46:49], v[152:155], v[210:213], v[46:49]
	v_mfma_f32_16x16x32_bf16 v[42:45], v[168:171], v[210:213], v[42:45]
	v_mfma_f32_16x16x32_bf16 v[30:33], v[152:155], v[224:227], v[30:33]
	v_mfma_f32_16x16x32_bf16 v[26:29], v[168:171], v[224:227], v[26:29]
	v_mfma_f32_16x16x32_bf16 v[14:17], v[152:155], v[232:235], v[14:17]
	v_mfma_f32_16x16x32_bf16 v[10:13], v[168:171], v[232:235], v[10:13]
	v_mfma_f32_16x16x32_bf16 v[62:65], v[156:159], v[206:209], v[62:65]
	v_mfma_f32_16x16x32_bf16 v[58:61], v[172:175], v[206:209], v[58:61]
	v_mfma_f32_16x16x32_bf16 v[46:49], v[156:159], v[220:223], v[46:49]
	v_mfma_f32_16x16x32_bf16 v[42:45], v[172:175], v[220:223], v[42:45]
	v_mfma_f32_16x16x32_bf16 v[30:33], v[156:159], v[228:231], v[30:33]
	v_mfma_f32_16x16x32_bf16 v[26:29], v[172:175], v[228:231], v[26:29]
	v_mfma_f32_16x16x32_bf16 v[14:17], v[156:159], v[248:251], v[14:17]
	v_mfma_f32_16x16x32_bf16 v[10:13], v[172:175], v[248:251], v[10:13]
	v_mfma_f32_16x16x32_bf16 v[54:57], v[182:185], v[202:205], v[54:57]
	v_mfma_f32_16x16x32_bf16 v[50:53], v[190:193], v[202:205], v[50:53]
	v_mfma_f32_16x16x32_bf16 v[38:41], v[182:185], v[210:213], v[38:41]
	v_mfma_f32_16x16x32_bf16 v[34:37], v[190:193], v[210:213], v[34:37]
	v_mfma_f32_16x16x32_bf16 v[22:25], v[182:185], v[224:227], v[22:25]
	v_mfma_f32_16x16x32_bf16 v[18:21], v[190:193], v[224:227], v[18:21]
	v_mfma_f32_16x16x32_bf16 v[6:9], v[182:185], v[232:235], v[6:9]
	v_mfma_f32_16x16x32_bf16 v[2:5], v[190:193], v[232:235], v[2:5]
	v_mfma_f32_16x16x32_bf16 v[54:57], v[186:189], v[206:209], v[54:57]
	v_mfma_f32_16x16x32_bf16 v[50:53], v[198:201], v[206:209], v[50:53]
	v_mfma_f32_16x16x32_bf16 v[38:41], v[186:189], v[220:223], v[38:41]
	v_mfma_f32_16x16x32_bf16 v[34:37], v[198:201], v[220:223], v[34:37]
	v_mfma_f32_16x16x32_bf16 v[22:25], v[186:189], v[228:231], v[22:25]
	v_mfma_f32_16x16x32_bf16 v[18:21], v[198:201], v[228:231], v[18:21]
	v_mfma_f32_16x16x32_bf16 v[6:9], v[186:189], v[248:251], v[6:9]
	v_mfma_f32_16x16x32_bf16 v[2:5], v[198:201], v[248:251], v[2:5]
	s_setprio 0
	s_barrier
	s_add_u32 s26, s26, 0x100
	s_addc_u32 s27, s27, 0
	v_lshl_add_u64 v[142:143], v[142:143], 0, s[94:95]
	v_lshl_add_u64 v[140:141], v[140:141], 0, s[94:95]
	s_cmp_ge_u32 s51, s34
	s_mov_b32 s23, s51
	s_cbranch_scc0 .LBB0_451
	s_and_b64 vcc, exec, s[6:7]
	s_cbranch_vccnz .LBB0_439
	v_mov_b32_e32 v2, 0
	s_mov_b32 s16, s49
	s_mov_b32 s36, s50
	s_mov_b64 s[18:19], s[24:25]
	s_mov_b64 s[20:21], s[8:9]
	s_mov_b32 s48, s22
	v_mov_b32_e32 v3, v2
	v_mov_b32_e32 v4, v2
	v_mov_b32_e32 v5, v2
	v_mov_b32_e32 v6, v2
	v_mov_b32_e32 v7, v2
	v_mov_b32_e32 v8, v2
	v_mov_b32_e32 v9, v2
	v_mov_b32_e32 v18, v2
	v_mov_b32_e32 v19, v2
	v_mov_b32_e32 v20, v2
	v_mov_b32_e32 v21, v2
	v_mov_b32_e32 v22, v2
	v_mov_b32_e32 v23, v2
	v_mov_b32_e32 v24, v2
	v_mov_b32_e32 v25, v2
	v_mov_b32_e32 v34, v2
	v_mov_b32_e32 v35, v2
	v_mov_b32_e32 v36, v2
	v_mov_b32_e32 v37, v2
	v_mov_b32_e32 v38, v2
	v_mov_b32_e32 v39, v2
	v_mov_b32_e32 v40, v2
	v_mov_b32_e32 v41, v2
	v_mov_b32_e32 v50, v2
	v_mov_b32_e32 v51, v2
	v_mov_b32_e32 v52, v2
	v_mov_b32_e32 v53, v2
	v_mov_b32_e32 v54, v2
	v_mov_b32_e32 v55, v2
	v_mov_b32_e32 v56, v2
	v_mov_b32_e32 v57, v2
	v_mov_b32_e32 v10, v2
	v_mov_b32_e32 v11, v2
	v_mov_b32_e32 v12, v2
	v_mov_b32_e32 v13, v2
	v_mov_b32_e32 v14, v2
	v_mov_b32_e32 v15, v2
	v_mov_b32_e32 v16, v2
	v_mov_b32_e32 v17, v2
	v_mov_b32_e32 v26, v2
	v_mov_b32_e32 v27, v2
	v_mov_b32_e32 v28, v2
	v_mov_b32_e32 v29, v2
	v_mov_b32_e32 v30, v2
	v_mov_b32_e32 v31, v2
	v_mov_b32_e32 v32, v2
	v_mov_b32_e32 v33, v2
	v_mov_b32_e32 v42, v2
	v_mov_b32_e32 v43, v2
	v_mov_b32_e32 v44, v2
	v_mov_b32_e32 v45, v2
	v_mov_b32_e32 v46, v2
	v_mov_b32_e32 v47, v2
	v_mov_b32_e32 v48, v2
	v_mov_b32_e32 v49, v2
	v_mov_b32_e32 v58, v2
	v_mov_b32_e32 v59, v2
	v_mov_b32_e32 v60, v2
	v_mov_b32_e32 v61, v2
	v_mov_b32_e32 v62, v2
	v_mov_b32_e32 v63, v2
	v_mov_b32_e32 v64, v2
	v_mov_b32_e32 v65, v2
	v_mov_b32_e32 v66, v2
	v_mov_b32_e32 v67, v2
	v_mov_b32_e32 v68, v2
	v_mov_b32_e32 v69, v2
	v_mov_b32_e32 v70, v2
	v_mov_b32_e32 v71, v2
	v_mov_b32_e32 v72, v2
	v_mov_b32_e32 v73, v2
	v_mov_b32_e32 v82, v2
	v_mov_b32_e32 v83, v2
	v_mov_b32_e32 v84, v2
	v_mov_b32_e32 v85, v2
	v_mov_b32_e32 v86, v2
	v_mov_b32_e32 v87, v2
	v_mov_b32_e32 v88, v2
	v_mov_b32_e32 v89, v2
	v_mov_b32_e32 v98, v2
	v_mov_b32_e32 v99, v2
	v_mov_b32_e32 v100, v2
	v_mov_b32_e32 v101, v2
	v_mov_b32_e32 v102, v2
	v_mov_b32_e32 v103, v2
	v_mov_b32_e32 v104, v2
	v_mov_b32_e32 v105, v2
	v_mov_b32_e32 v114, v2
	v_mov_b32_e32 v115, v2
	v_mov_b32_e32 v116, v2
	v_mov_b32_e32 v117, v2
	v_mov_b32_e32 v118, v2
	v_mov_b32_e32 v119, v2
	v_mov_b32_e32 v120, v2
	v_mov_b32_e32 v121, v2
	v_mov_b32_e32 v74, v2
	v_mov_b32_e32 v75, v2
	v_mov_b32_e32 v76, v2
	v_mov_b32_e32 v77, v2
	v_mov_b32_e32 v78, v2
	v_mov_b32_e32 v79, v2
	v_mov_b32_e32 v80, v2
	v_mov_b32_e32 v81, v2
	v_mov_b32_e32 v90, v2
	v_mov_b32_e32 v91, v2
	v_mov_b32_e32 v92, v2
	v_mov_b32_e32 v93, v2
	v_mov_b32_e32 v94, v2
	v_mov_b32_e32 v95, v2
	v_mov_b32_e32 v96, v2
	v_mov_b32_e32 v97, v2
	v_mov_b32_e32 v106, v2
	v_mov_b32_e32 v107, v2
	v_mov_b32_e32 v108, v2
	v_mov_b32_e32 v109, v2
	v_mov_b32_e32 v110, v2
	v_mov_b32_e32 v111, v2
	v_mov_b32_e32 v112, v2
	v_mov_b32_e32 v113, v2
	v_mov_b32_e32 v122, v2
	v_mov_b32_e32 v123, v2
	v_mov_b32_e32 v124, v2
	v_mov_b32_e32 v125, v2
	v_mov_b32_e32 v126, v2
	v_mov_b32_e32 v127, v2
	v_mov_b32_e32 v128, v2
	v_mov_b32_e32 v129, v2
	s_branch .LBB0_439

; #define PG8_STAGE(bufoff, gbase, voff) do { _Pragma("unroll") for (int _i = 0; _i < 2; ++_i) \
;         __builtin_amdgcn_global_load_lds((const unsigned*)((const char*)(gbase) + (voff)[_i]), (PG8_LAS unsigned*)(lds + (bufoff) + ldsw + _i * 8192), 16, 0, 0); } while (0)
; #define PG8_LDA(dst, b, h) do { _Pragma("unroll") for (int m = 0; m < 4; ++m) _Pragma("unroll") for (int k = 0; k < 2; ++k) dst[m][k] = *(const PG8_LAS bf16x8*)(lds + PG8_SA(b, h) + aoff + m * 2048 + k * 1024); } while (0)
; #define PG8_LDB(dst, b, h) do { _Pragma("unroll") for (int n = 0; n < 2; ++n) _Pragma("unroll") for (int k = 0; k < 2; ++k) dst[n][k] = *(const PG8_LAS bf16x8*)(lds + PG8_SB(b, h) + boff + n * 2048 + k * 1024); } while (0)
; #define PG8_MMA(ai, bj, At, Bt) do { __builtin_amdgcn_s_setprio(1); _Pragma("unroll") for (int m = 0; m < 4; ++m) _Pragma("unroll") for (int n = 0; n < 2; ++n) _Pragma("unroll") for (int k = 0; k < 2; ++k) \
;         acc[ai][bj][m][n] = __builtin_amdgcn_mfma_f32_16x16x32_bf16(Bt[n][k], At[m][k], acc[ai][bj][m][n], 0, 0, 0); __builtin_amdgcn_s_setprio(0); } while (0)
; #define PG8_WAIT_V(n) asm volatile("s_waitcnt vmcnt(" #n ")" ::: "memory")
; #define PG8_WAIT_L(n) asm volatile("s_waitcnt lgkmcnt(" #n ")" ::: "memory")
; template <class Epi, class Sched, bool ALIGN_EPI = false, bool SP2 = false>
; __device__ __forceinline__ void gemm_phase(PG8_LAS unsigned char* lds, const Gemm g, const Sched& S, const Epi& E, int tid_in) {
;     ...
;             const bool last = (t == nt - 2);
;             const char* a1 = cA + (size_t)(t + 1) * kstep;
;             const char* a2 = last ? nA : cA + (size_t)(t + 2) * kstep; const char* b2 = last ? nB : cB + (size_t)(t + 2) * kstep;
;             const char* a3 = a2 + kstep; const char* b3 = b2 + kstep;
;             if (last && has_next) S.a_ready(nxt);
;             if constexpr (SP2) {
;             PG8_LDB(B0, 0, 0); PG8_LDB(B1, 0, 1); PG8_SCHED; PG8_LDA(At, 0, 0); PG8_STAGE(PG8_SA(1, 1), a1 + hstep, voffA);
;             PG8_WAIT_V(8); PG8_WAIT_L(0); PG8_BAR; PG8_MMA(0, 0, At, B0); PG8_MMA(0, 1, At, B1); PG8_BAR; PG8_SCHED;
;             PG8_LDA(At, 0, 1); PG8_STAGE(PG8_SB(0, 0), b2, voffB); PG8_STAGE(PG8_SB(0, 1), b2 + hstep, voffB); PG8_STAGE(PG8_SA(0, 0), a2, voffA);
;             PG8_WAIT_V(8); PG8_WAIT_L(0); PG8_BAR; PG8_MMA(1, 0, At, B0); PG8_MMA(1, 1, At, B1); PG8_BAR; PG8_SCHED;
.LBB0_467:
	s_add_u32 s12, s10, 0xfffc0080
	s_addc_u32 s13, s11, -1
	s_add_i32 s40, 0, 0x10000
	s_cmp_eq_u32 s39, 12
	s_cselect_b32 s35, s9, s13
	s_cselect_b32 s34, s27, s12
	v_add_u32_e32 v0, s40, v177
	s_cselect_b32 s13, s25, s38
	s_cselect_b32 s12, s36, s37
	s_add_i32 s56, 0, 0x14000
	s_waitcnt vmcnt(0)
	ds_read_b128 v[42:45], v0
	ds_read_b128 v[46:49], v0 offset:1024
	ds_read_b128 v[66:69], v0 offset:2048
	ds_read_b128 v[70:73], v0 offset:3072
	v_add_u32_e32 v0, s56, v177
	ds_read_b128 v[82:85], v0
	ds_read_b128 v[86:89], v0 offset:1024
	ds_read_b128 v[106:109], v0 offset:2048
	ds_read_b128 v[110:113], v0 offset:3072
	v_lshl_add_u64 v[214:215], s[10:11], 0, v[198:199]
	s_add_i32 m0, s15, 0xc000
	ds_read_b128 v[202:205], v249
	ds_read_b128 v[206:209], v249 offset:1024
	ds_read_b128 v[210:213], v249 offset:2048
	ds_read_b128 v[250:253], v249 offset:3072
	ds_read_b128 v[220:223], v249 offset:4096
	ds_read_b128 v[224:227], v249 offset:5120
	ds_read_b128 v[228:231], v249 offset:6144
	ds_read_b128 v[232:235], v249 offset:7168
	global_load_lds_dwordx4 v[214:215], off
	v_lshl_add_u64 v[214:215], s[10:11], 0, v[200:201]
	s_add_i32 m0, s15, 0xe000
	s_nop 0
	global_load_lds_dwordx4 v[214:215], off
	s_waitcnt vmcnt(8) lgkmcnt(0)
	s_barrier
	s_setprio 1
	v_mfma_f32_16x16x32_bf16 v[158:161], v[42:45], v[202:205], v[158:161]
	v_mfma_f32_16x16x32_bf16 v[154:157], v[66:69], v[202:205], v[154:157]
	v_mfma_f32_16x16x32_bf16 v[142:145], v[42:45], v[210:213], v[142:145]
	v_mfma_f32_16x16x32_bf16 v[138:141], v[66:69], v[210:213], v[138:141]
	v_mfma_f32_16x16x32_bf16 v[126:129], v[42:45], v[220:223], v[126:129]
	v_mfma_f32_16x16x32_bf16 v[122:125], v[66:69], v[220:223], v[122:125]
	v_mfma_f32_16x16x32_bf16 v[102:105], v[42:45], v[228:231], v[102:105]
	v_mfma_f32_16x16x32_bf16 v[98:101], v[66:69], v[228:231], v[98:101]
	v_mfma_f32_16x16x32_bf16 v[158:161], v[46:49], v[206:209], v[158:161]
	v_mfma_f32_16x16x32_bf16 v[154:157], v[70:73], v[206:209], v[154:157]
	v_mfma_f32_16x16x32_bf16 v[142:145], v[46:49], v[250:253], v[142:145]
	v_mfma_f32_16x16x32_bf16 v[138:141], v[70:73], v[250:253], v[138:141]
	v_mfma_f32_16x16x32_bf16 v[126:129], v[46:49], v[224:227], v[126:129]
	v_mfma_f32_16x16x32_bf16 v[122:125], v[70:73], v[224:227], v[122:125]
	v_mfma_f32_16x16x32_bf16 v[102:105], v[46:49], v[232:235], v[102:105]
	v_mfma_f32_16x16x32_bf16 v[98:101], v[70:73], v[232:235], v[98:101]
	v_mfma_f32_16x16x32_bf16 v[150:153], v[82:85], v[202:205], v[150:153]
	v_mfma_f32_16x16x32_bf16 v[146:149], v[106:109], v[202:205], v[146:149]
	v_mfma_f32_16x16x32_bf16 v[134:137], v[82:85], v[210:213], v[134:137]
	v_mfma_f32_16x16x32_bf16 v[130:133], v[106:109], v[210:213], v[130:133]
	v_mfma_f32_16x16x32_bf16 v[118:121], v[82:85], v[220:223], v[118:121]
	v_mfma_f32_16x16x32_bf16 v[114:117], v[106:109], v[220:223], v[114:117]
	v_mfma_f32_16x16x32_bf16 v[94:97], v[82:85], v[228:231], v[94:97]
	v_mfma_f32_16x16x32_bf16 v[90:93], v[106:109], v[228:231], v[90:93]
	v_mfma_f32_16x16x32_bf16 v[150:153], v[86:89], v[206:209], v[150:153]
	v_mfma_f32_16x16x32_bf16 v[146:149], v[110:113], v[206:209], v[146:149]
	v_mfma_f32_16x16x32_bf16 v[134:137], v[86:89], v[250:253], v[134:137]
	v_mfma_f32_16x16x32_bf16 v[130:133], v[110:113], v[250:253], v[130:133]
	v_mfma_f32_16x16x32_bf16 v[118:121], v[86:89], v[224:227], v[118:121]
	v_mfma_f32_16x16x32_bf16 v[114:117], v[110:113], v[224:227], v[114:117]
	v_mfma_f32_16x16x32_bf16 v[94:97], v[86:89], v[232:235], v[94:97]
	v_mfma_f32_16x16x32_bf16 v[90:93], v[110:113], v[232:235], v[90:93]
	s_setprio 0
	s_barrier
	s_add_i32 s40, s40, s44
	v_lshl_add_u64 v[214:215], s[12:13], 0, v[170:171]
	s_mov_b32 m0, s40
	ds_read_b128 v[202:205], v249 offset:16384
	ds_read_b128 v[206:209], v249 offset:17408
	ds_read_b128 v[210:213], v249 offset:18432
	ds_read_b128 v[220:223], v249 offset:19456
	ds_read_b128 v[224:227], v249 offset:20480
	ds_read_b128 v[228:231], v249 offset:21504
	ds_read_b128 v[232:235], v249 offset:22528
	ds_read_b128 v[250:253], v249 offset:23552
	global_load_lds_dwordx4 v[214:215], off
	s_add_i32 m0, s40, 0x2000
	s_add_u32 s40, s12, 0x40000
	v_lshl_add_u64 v[244:245], s[12:13], 0, v[174:175]
	s_addc_u32 s41, s13, 0
	s_add_i32 s56, s56, s44
	global_load_lds_dwordx4 v[244:245], off
	v_lshl_add_u64 v[236:237], s[40:41], 0, v[170:171]
	s_mov_b32 m0, s56
	v_lshl_add_u64 v[238:239], s[34:35], 0, v[172:173]
	global_load_lds_dwordx4 v[236:237], off
	v_lshl_add_u64 v[236:237], s[40:41], 0, v[174:175]
	s_add_i32 m0, s56, 0x2000
	s_nop 0
	global_load_lds_dwordx4 v[236:237], off
	v_lshl_add_u64 v[236:237], s[34:35], 0, v[168:169]
	s_mov_b32 m0, s15
	s_nop 0
	global_load_lds_dwordx4 v[236:237], off
	s_mov_b32 m0, s45
	s_nop 0
	global_load_lds_dwordx4 v[238:239], off
	s_waitcnt vmcnt(8) lgkmcnt(0)
	s_barrier
; #define PG8_STAGE(bufoff, gbase, voff) do { _Pragma("unroll") for (int _i = 0; _i < 2; ++_i) \
;         __builtin_amdgcn_global_load_lds((const unsigned*)((const char*)(gbase) + (voff)[_i]), (PG8_LAS unsigned*)(lds + (bufoff) + ldsw + _i * 8192), 16, 0, 0); } while (0)
; #define PG8_LDA(dst, b, h) do { _Pragma("unroll") for (int m = 0; m < 4; ++m) _Pragma("unroll") for (int k = 0; k < 2; ++k) dst[m][k] = *(const PG8_LAS bf16x8*)(lds + PG8_SA(b, h) + aoff + m * 2048 + k * 1024); } while (0)
; #define PG8_LDB(dst, b, h) do { _Pragma("unroll") for (int n = 0; n < 2; ++n) _Pragma("unroll") for (int k = 0; k < 2; ++k) dst[n][k] = *(const PG8_LAS bf16x8*)(lds + PG8_SB(b, h) + boff + n * 2048 + k * 1024); } while (0)
; #define PG8_MMA(ai, bj, At, Bt) do { __builtin_amdgcn_s_setprio(1); _Pragma("unroll") for (int m = 0; m < 4; ++m) _Pragma("unroll") for (int n = 0; n < 2; ++n) _Pragma("unroll") for (int k = 0; k < 2; ++k) \
;         acc[ai][bj][m][n] = __builtin_amdgcn_mfma_f32_16x16x32_bf16(Bt[n][k], At[m][k], acc[ai][bj][m][n], 0, 0, 0); __builtin_amdgcn_s_setprio(0); } while (0)
; #define PG8_WAIT_V(n) asm volatile("s_waitcnt vmcnt(" #n ")" ::: "memory")
; #define PG8_WAIT_L(n) asm volatile("s_waitcnt lgkmcnt(" #n ")" ::: "memory")
; #define PG8_BAR __builtin_amdgcn_s_barrier()
; #define PG8_SCHED __builtin_amdgcn_sched_barrier(0)
; template <class Epi, class Sched, bool ALIGN_EPI = false, bool SP2 = false>
; __device__ __forceinline__ void gemm_phase(PG8_LAS unsigned char* lds, const Gemm g, const Sched& S, const Epi& E, int tid_in) {
;     ...
;             PG8_WAIT_V(8); PG8_WAIT_L(0); PG8_BAR; PG8_MMA(1, 0, At, B0); PG8_MMA(1, 1, At, B1); PG8_BAR; PG8_SCHED;
;             PG8_LDB(B0, 1, 0); PG8_LDB(B1, 1, 1); PG8_SCHED; PG8_LDA(At, 1, 0); PG8_STAGE(PG8_SA(0, 1), a2 + hstep, voffA);
;             PG8_WAIT_V(8); PG8_WAIT_L(0); PG8_BAR; PG8_MMA(0, 0, At, B0); PG8_MMA(0, 1, At, B1); PG8_BAR; PG8_SCHED;
	s_setprio 1
	v_mfma_f32_16x16x32_bf16 v[78:81], v[42:45], v[202:205], v[78:81]
	v_mfma_f32_16x16x32_bf16 v[74:77], v[66:69], v[202:205], v[74:77]
	v_mfma_f32_16x16x32_bf16 v[54:57], v[42:45], v[210:213], v[54:57]
	v_mfma_f32_16x16x32_bf16 v[50:53], v[66:69], v[210:213], v[50:53]
	v_mfma_f32_16x16x32_bf16 v[30:33], v[42:45], v[224:227], v[30:33]
	v_mfma_f32_16x16x32_bf16 v[26:29], v[66:69], v[224:227], v[26:29]
	v_mfma_f32_16x16x32_bf16 v[14:17], v[42:45], v[232:235], v[14:17]
	v_mfma_f32_16x16x32_bf16 v[10:13], v[66:69], v[232:235], v[10:13]
	v_mfma_f32_16x16x32_bf16 v[78:81], v[46:49], v[206:209], v[78:81]
	v_mfma_f32_16x16x32_bf16 v[74:77], v[70:73], v[206:209], v[74:77]
	v_mfma_f32_16x16x32_bf16 v[54:57], v[46:49], v[220:223], v[54:57]
	v_mfma_f32_16x16x32_bf16 v[50:53], v[70:73], v[220:223], v[50:53]
	v_mfma_f32_16x16x32_bf16 v[30:33], v[46:49], v[228:231], v[30:33]
	v_mfma_f32_16x16x32_bf16 v[26:29], v[70:73], v[228:231], v[26:29]
	v_mfma_f32_16x16x32_bf16 v[14:17], v[46:49], v[250:253], v[14:17]
	v_mfma_f32_16x16x32_bf16 v[10:13], v[70:73], v[250:253], v[10:13]
	v_mfma_f32_16x16x32_bf16 v[38:41], v[82:85], v[210:213], v[38:41]
	v_mfma_f32_16x16x32_bf16 v[34:37], v[106:109], v[210:213], v[34:37]
	v_mfma_f32_16x16x32_bf16 v[22:25], v[82:85], v[224:227], v[22:25]
	v_mfma_f32_16x16x32_bf16 v[18:21], v[106:109], v[224:227], v[18:21]
	v_mfma_f32_16x16x32_bf16 v[6:9], v[82:85], v[232:235], v[6:9]
	v_mfma_f32_16x16x32_bf16 v[2:5], v[106:109], v[232:235], v[2:5]
	v_mfma_f32_16x16x32_bf16 v[42:45], v[82:85], v[202:205], v[62:65]
	v_mfma_f32_16x16x32_bf16 v[46:49], v[106:109], v[202:205], v[58:61]
	v_mfma_f32_16x16x32_bf16 v[38:41], v[86:89], v[220:223], v[38:41]
	v_mfma_f32_16x16x32_bf16 v[34:37], v[110:113], v[220:223], v[34:37]
	v_mfma_f32_16x16x32_bf16 v[22:25], v[86:89], v[228:231], v[22:25]
	v_mfma_f32_16x16x32_bf16 v[18:21], v[110:113], v[228:231], v[18:21]
	v_mfma_f32_16x16x32_bf16 v[6:9], v[86:89], v[250:253], v[6:9]
	v_mfma_f32_16x16x32_bf16 v[2:5], v[110:113], v[250:253], v[2:5]
	v_mfma_f32_16x16x32_bf16 v[42:45], v[86:89], v[206:209], v[42:45]
	v_mfma_f32_16x16x32_bf16 v[46:49], v[110:113], v[206:209], v[46:49]
	s_setprio 0
	s_barrier
	s_add_i32 s40, 0, 0x18000
	v_add_u32_e32 v0, s40, v177
	s_add_i32 s41, 0, 0x1c000
	ds_read_b128 v[58:61], v0
	ds_read_b128 v[62:65], v0 offset:1024
	ds_read_b128 v[66:69], v0 offset:2048
	ds_read_b128 v[70:73], v0 offset:3072
	v_add_u32_e32 v0, s41, v177
	ds_read_b128 v[82:85], v0
	ds_read_b128 v[86:89], v0 offset:1024
	ds_read_b128 v[106:109], v0 offset:2048
	ds_read_b128 v[110:113], v0 offset:3072
	s_add_u32 s34, s34, 0x40000
	s_addc_u32 s35, s35, 0
	s_mov_b32 m0, s46
	v_lshl_add_u64 v[216:217], s[34:35], 0, v[168:169]
	ds_read_b128 v[202:205], v249 offset:32768
	ds_read_b128 v[206:209], v249 offset:33792
	ds_read_b128 v[210:213], v249 offset:34816
	ds_read_b128 v[220:223], v249 offset:35840
	ds_read_b128 v[224:227], v249 offset:36864
	ds_read_b128 v[228:231], v249 offset:37888
	ds_read_b128 v[232:235], v249 offset:38912
	ds_read_b128 v[250:253], v249 offset:39936
	global_load_lds_dwordx4 v[216:217], off
	v_lshl_add_u64 v[216:217], s[34:35], 0, v[172:173]
	s_mov_b32 m0, s47
	s_nop 0
	global_load_lds_dwordx4 v[216:217], off
	s_waitcnt vmcnt(8) lgkmcnt(0)
	s_barrier
	s_setprio 1
	v_mfma_f32_16x16x32_bf16 v[158:161], v[58:61], v[202:205], v[158:161]
	v_mfma_f32_16x16x32_bf16 v[154:157], v[66:69], v[202:205], v[154:157]
	v_mfma_f32_16x16x32_bf16 v[142:145], v[58:61], v[210:213], v[142:145]
	v_mfma_f32_16x16x32_bf16 v[138:141], v[66:69], v[210:213], v[138:141]
	v_mfma_f32_16x16x32_bf16 v[126:129], v[58:61], v[224:227], v[126:129]
	v_mfma_f32_16x16x32_bf16 v[122:125], v[66:69], v[224:227], v[122:125]
	v_mfma_f32_16x16x32_bf16 v[102:105], v[58:61], v[232:235], v[102:105]
	v_mfma_f32_16x16x32_bf16 v[98:101], v[66:69], v[232:235], v[98:101]
	v_mfma_f32_16x16x32_bf16 v[158:161], v[62:65], v[206:209], v[158:161]
	v_mfma_f32_16x16x32_bf16 v[154:157], v[70:73], v[206:209], v[154:157]
	v_mfma_f32_16x16x32_bf16 v[142:145], v[62:65], v[220:223], v[142:145]
	v_mfma_f32_16x16x32_bf16 v[138:141], v[70:73], v[220:223], v[138:141]
	v_mfma_f32_16x16x32_bf16 v[126:129], v[62:65], v[228:231], v[126:129]
	v_mfma_f32_16x16x32_bf16 v[122:125], v[70:73], v[228:231], v[122:125]
	v_mfma_f32_16x16x32_bf16 v[102:105], v[62:65], v[250:253], v[102:105]
	v_mfma_f32_16x16x32_bf16 v[98:101], v[70:73], v[250:253], v[98:101]
	v_mfma_f32_16x16x32_bf16 v[150:153], v[82:85], v[202:205], v[150:153]
	v_mfma_f32_16x16x32_bf16 v[146:149], v[106:109], v[202:205], v[146:149]
	v_mfma_f32_16x16x32_bf16 v[134:137], v[82:85], v[210:213], v[134:137]
	v_mfma_f32_16x16x32_bf16 v[130:133], v[106:109], v[210:213], v[130:133]
	v_mfma_f32_16x16x32_bf16 v[118:121], v[82:85], v[224:227], v[118:121]
	v_mfma_f32_16x16x32_bf16 v[114:117], v[106:109], v[224:227], v[114:117]
	v_mfma_f32_16x16x32_bf16 v[94:97], v[82:85], v[232:235], v[94:97]
	v_mfma_f32_16x16x32_bf16 v[90:93], v[106:109], v[232:235], v[90:93]
	v_mfma_f32_16x16x32_bf16 v[150:153], v[86:89], v[206:209], v[150:153]
	v_mfma_f32_16x16x32_bf16 v[146:149], v[110:113], v[206:209], v[146:149]
	v_mfma_f32_16x16x32_bf16 v[134:137], v[86:89], v[220:223], v[134:137]
	v_mfma_f32_16x16x32_bf16 v[130:133], v[110:113], v[220:223], v[130:133]
	v_mfma_f32_16x16x32_bf16 v[118:121], v[86:89], v[228:231], v[118:121]
	v_mfma_f32_16x16x32_bf16 v[114:117], v[110:113], v[228:231], v[114:117]
	v_mfma_f32_16x16x32_bf16 v[94:97], v[86:89], v[250:253], v[94:97]
	v_mfma_f32_16x16x32_bf16 v[90:93], v[110:113], v[250:253], v[90:93]
	s_setprio 0
	s_barrier
; #define PG8_STAGE(bufoff, gbase, voff) do { _Pragma("unroll") for (int _i = 0; _i < 2; ++_i) \
;         __builtin_amdgcn_global_load_lds((const unsigned*)((const char*)(gbase) + (voff)[_i]), (PG8_LAS unsigned*)(lds + (bufoff) + ldsw + _i * 8192), 16, 0, 0); } while (0)
; #define PG8_LDA(dst, b, h) do { _Pragma("unroll") for (int m = 0; m < 4; ++m) _Pragma("unroll") for (int k = 0; k < 2; ++k) dst[m][k] = *(const PG8_LAS bf16x8*)(lds + PG8_SA(b, h) + aoff + m * 2048 + k * 1024); } while (0)
; #define PG8_MMA(ai, bj, At, Bt) do { __builtin_amdgcn_s_setprio(1); _Pragma("unroll") for (int m = 0; m < 4; ++m) _Pragma("unroll") for (int n = 0; n < 2; ++n) _Pragma("unroll") for (int k = 0; k < 2; ++k) \
;         acc[ai][bj][m][n] = __builtin_amdgcn_mfma_f32_16x16x32_bf16(Bt[n][k], At[m][k], acc[ai][bj][m][n], 0, 0, 0); __builtin_amdgcn_s_setprio(0); } while (0)
; #define PG8_WAIT_V(n) asm volatile("s_waitcnt vmcnt(" #n ")" ::: "memory")
; #define PG8_WAIT_L(n) asm volatile("s_waitcnt lgkmcnt(" #n ")" ::: "memory")
; #define PG8_BAR __builtin_amdgcn_s_barrier()
; #define PG8_SCHED __builtin_amdgcn_sched_barrier(0)
; template <class Epi, class Sched, bool ALIGN_EPI = false, bool SP2 = false>
; __device__ __forceinline__ void gemm_phase(PG8_LAS unsigned char* lds, const Gemm g, const Sched& S, const Epi& E, int tid_in) {
;     ...
;             PG8_LDA(At, 1, 1); PG8_STAGE(PG8_SB(1, 0), b3, voffB); PG8_STAGE(PG8_SB(1, 1), b3 + hstep, voffB); PG8_STAGE(PG8_SA(1, 0), a3, voffA);
;             PG8_WAIT_V(8); PG8_WAIT_L(0); PG8_BAR; PG8_MMA(1, 0, At, B0); PG8_MMA(1, 1, At, B1); PG8_BAR; PG8_SCHED;
;     ...
;         if constexpr (ALIGN_EPI) { if (wr == 0) PG8_BAR; }
	s_add_i32 s34, s40, s44
	v_lshl_add_u64 v[214:215], v[214:215], 0, s[92:93]
	s_mov_b32 m0, s34
	ds_read_b128 v[202:205], v249 offset:49152
	ds_read_b128 v[206:209], v249 offset:50176
	ds_read_b128 v[210:213], v249 offset:51200
	ds_read_b128 v[220:223], v249 offset:52224
	ds_read_b128 v[224:227], v249 offset:53248
	ds_read_b128 v[228:231], v249 offset:54272
	ds_read_b128 v[232:235], v249 offset:55296
	ds_read_b128 v[250:253], v249 offset:56320
	global_load_lds_dwordx4 v[214:215], off
	s_add_i32 m0, s34, 0x2000
	s_add_u32 s12, s12, 0x40080
	v_lshl_add_u64 v[214:215], v[244:245], 0, s[92:93]
	s_addc_u32 s13, s13, 0
	s_add_i32 s34, s41, s44
	global_load_lds_dwordx4 v[214:215], off
	v_lshl_add_u64 v[214:215], s[12:13], 0, v[170:171]
	s_mov_b32 m0, s34
	s_nop 0
	global_load_lds_dwordx4 v[214:215], off
	v_lshl_add_u64 v[214:215], s[12:13], 0, v[174:175]
	s_add_i32 m0, s34, 0x2000
	s_nop 0
	global_load_lds_dwordx4 v[214:215], off
	v_lshl_add_u64 v[214:215], v[236:237], 0, s[92:93]
	s_mov_b32 m0, s49
	s_nop 0
	global_load_lds_dwordx4 v[214:215], off
	v_lshl_add_u64 v[214:215], v[238:239], 0, s[92:93]
	s_mov_b32 m0, s50
	s_nop 0
	global_load_lds_dwordx4 v[214:215], off
	s_waitcnt vmcnt(8) lgkmcnt(0)
	s_barrier
	s_setprio 1
	v_mfma_f32_16x16x32_bf16 v[78:81], v[58:61], v[202:205], v[78:81]
	v_mfma_f32_16x16x32_bf16 v[74:77], v[66:69], v[202:205], v[74:77]
	v_mfma_f32_16x16x32_bf16 v[54:57], v[58:61], v[210:213], v[54:57]
	v_mfma_f32_16x16x32_bf16 v[50:53], v[66:69], v[210:213], v[50:53]
	v_mfma_f32_16x16x32_bf16 v[30:33], v[58:61], v[224:227], v[30:33]
	v_mfma_f32_16x16x32_bf16 v[26:29], v[66:69], v[224:227], v[26:29]
	v_mfma_f32_16x16x32_bf16 v[14:17], v[58:61], v[232:235], v[14:17]
	v_mfma_f32_16x16x32_bf16 v[10:13], v[66:69], v[232:235], v[10:13]
	v_mfma_f32_16x16x32_bf16 v[78:81], v[62:65], v[206:209], v[78:81]
	v_mfma_f32_16x16x32_bf16 v[74:77], v[70:73], v[206:209], v[74:77]
	v_mfma_f32_16x16x32_bf16 v[54:57], v[62:65], v[220:223], v[54:57]
	v_mfma_f32_16x16x32_bf16 v[50:53], v[70:73], v[220:223], v[50:53]
	v_mfma_f32_16x16x32_bf16 v[30:33], v[62:65], v[228:231], v[30:33]
	v_mfma_f32_16x16x32_bf16 v[26:29], v[70:73], v[228:231], v[26:29]
	v_mfma_f32_16x16x32_bf16 v[14:17], v[62:65], v[250:253], v[14:17]
	v_mfma_f32_16x16x32_bf16 v[10:13], v[70:73], v[250:253], v[10:13]
	v_mfma_f32_16x16x32_bf16 v[42:45], v[82:85], v[202:205], v[42:45]
	v_mfma_f32_16x16x32_bf16 v[62:65], v[86:89], v[206:209], v[42:45]
	v_mfma_f32_16x16x32_bf16 v[42:45], v[106:109], v[202:205], v[46:49]
	v_mfma_f32_16x16x32_bf16 v[38:41], v[82:85], v[210:213], v[38:41]
	v_mfma_f32_16x16x32_bf16 v[34:37], v[106:109], v[210:213], v[34:37]
	v_mfma_f32_16x16x32_bf16 v[22:25], v[82:85], v[224:227], v[22:25]
	v_mfma_f32_16x16x32_bf16 v[18:21], v[106:109], v[224:227], v[18:21]
	v_mfma_f32_16x16x32_bf16 v[6:9], v[82:85], v[232:235], v[6:9]
	v_mfma_f32_16x16x32_bf16 v[2:5], v[106:109], v[232:235], v[2:5]
	v_mfma_f32_16x16x32_bf16 v[58:61], v[110:113], v[206:209], v[42:45]
	v_mfma_f32_16x16x32_bf16 v[38:41], v[86:89], v[220:223], v[38:41]
	v_mfma_f32_16x16x32_bf16 v[34:37], v[110:113], v[220:223], v[34:37]
	v_mfma_f32_16x16x32_bf16 v[22:25], v[86:89], v[228:231], v[22:25]
	v_mfma_f32_16x16x32_bf16 v[18:21], v[110:113], v[228:231], v[18:21]
	v_mfma_f32_16x16x32_bf16 v[6:9], v[86:89], v[250:253], v[6:9]
	v_mfma_f32_16x16x32_bf16 v[2:5], v[110:113], v[250:253], v[2:5]
	s_setprio 0
	s_barrier
	s_add_i32 s39, s39, 2
	s_add_u32 s10, s10, 0x100
	s_addc_u32 s11, s11, 0
	s_add_u32 s37, s37, 0x100
	s_addc_u32 s38, s38, 0
	s_cmp_gt_u32 s39, 13
	s_cbranch_scc0 .LBB0_467
	s_and_b64 vcc, exec, s[18:19]
	s_cbranch_vccz .LBB0_470
	s_barrier

; __global__ void __launch_bounds__(NTHREADS, 2) mega_fwd(Args A_unused) {
	.amdhsa_kernel _Z8mega_fwd4Args
		.amdhsa_group_segment_fixed_size 0
		.amdhsa_private_segment_fixed_size 0
		.amdhsa_kernarg_size 424
		.amdhsa_user_sgpr_count 2
		.amdhsa_user_sgpr_dispatch_ptr 0
		.amdhsa_user_sgpr_queue_ptr 0
		.amdhsa_user_sgpr_kernarg_segment_ptr 1
		.amdhsa_user_sgpr_dispatch_id 0
		.amdhsa_user_sgpr_kernarg_preload_length 0
		.amdhsa_user_sgpr_kernarg_preload_offset 0
		.amdhsa_user_sgpr_private_segment_size 0
		.amdhsa_uses_dynamic_stack 0
		.amdhsa_enable_private_segment 0
		.amdhsa_system_sgpr_workgroup_id_x 1
		.amdhsa_system_sgpr_workgroup_id_y 0
		.amdhsa_system_sgpr_workgroup_id_z 0
		.amdhsa_system_sgpr_workgroup_info 0
		.amdhsa_system_vgpr_workitem_id 2
		.amdhsa_next_free_vgpr 256
		.amdhsa_next_free_sgpr 102
		.amdhsa_accum_offset 256
		.amdhsa_reserve_vcc 1
		.amdhsa_float_round_mode_32 0
		.amdhsa_float_round_mode_16_64 0
		.amdhsa_float_denorm_mode_32 3
		.amdhsa_float_denorm_mode_16_64 3
		.amdhsa_dx10_clamp 1
		.amdhsa_ieee_mode 1
		.amdhsa_fp16_overflow 0
		.amdhsa_tg_split 0
		.amdhsa_exception_fp_ieee_invalid_op 0
		.amdhsa_exception_fp_denorm_src 0
		.amdhsa_exception_fp_ieee_div_zero 0
		.amdhsa_exception_fp_ieee_overflow 0
		.amdhsa_exception_fp_ieee_underflow 0
		.amdhsa_exception_fp_ieee_inexact 0
		.amdhsa_exception_int_div_zero 0
	.end_amdhsa_kernel

; __global__ void __launch_bounds__(NTHREADS, 2) mega_fwd(Args A_unused) {
amdhsa.kernels:
  - .agpr_count:     0
    .args:
      - .offset:         0
        .size:           168
        .value_kind:     by_value
      - .offset:         168
        .size:           4
        .value_kind:     hidden_block_count_x
      - .offset:         172
        .size:           4
        .value_kind:     hidden_block_count_y
      - .offset:         176
        .size:           4
        .value_kind:     hidden_block_count_z
      - .offset:         180
        .size:           2
        .value_kind:     hidden_group_size_x
      - .offset:         182
        .size:           2
        .value_kind:     hidden_group_size_y
      - .offset:         184
        .size:           2
        .value_kind:     hidden_group_size_z
      - .offset:         186
        .size:           2
        .value_kind:     hidden_remainder_x
      - .offset:         188
        .size:           2
        .value_kind:     hidden_remainder_y
      - .offset:         190
        .size:           2
        .value_kind:     hidden_remainder_z
      - .offset:         208
        .size:           8
        .value_kind:     hidden_global_offset_x
      - .offset:         216
        .size:           8
        .value_kind:     hidden_global_offset_y
      - .offset:         224
        .size:           8
        .value_kind:     hidden_global_offset_z
      - .offset:         232
        .size:           2
        .value_kind:     hidden_grid_dims
      - .offset:         256
        .size:           8
        .value_kind:     hidden_multigrid_sync_arg
      - .offset:         288
        .size:           4
        .value_kind:     hidden_dynamic_lds_size
    .group_segment_fixed_size: 0
    .kernarg_segment_align: 8
    .kernarg_segment_size: 424
    .language:       OpenCL C
    .language_version:
      - 2
      - 0
    .max_flat_workgroup_size: 512
    .name:           _Z8mega_fwd4Args
    .private_segment_fixed_size: 0
    .sgpr_count:     108
    .sgpr_spill_count: 66
    .symbol:         _Z8mega_fwd4Args.kd
    .uniform_work_group_size: 1
    .uses_dynamic_stack: false
    .vgpr_count:     256
    .vgpr_spill_count: 0
    .wavefront_size: 64
